# all four 256x256 GEMM k-loops (in-proj, out-proj, ffn-up, ffn-down): LDS-DMA staging + software-pipelined fragment reads
# speedup vs baseline: 1.0532x; 1.0199x over previous
; template <int MI, int NI>
; DI void gemm_kloop(const u16* Au, int lda, const u16* Bu, int ldb, int K, f32x4 (&acc)[NI][MI], unsigned char* smem) {
;   int tid_ = threadIdx.x; asm volatile("" : "+v"(tid_));
;   const int tid = tid_, lane = tid & 63, wave = tid >> 6, wm = wave >> 1, wn = wave & 1;
;   const int lr = tid >> 3, lc = tid & 7;
;   const int voa = lr * lda + lc * 8, vob = lr * ldb + lc * 8;
;   constexpr int NB2 = NI / 2;
;   u32x4 ra[MI], rb[NB2];
;   const int nk = K >> 6;
;   const int fsw = (lane & 15) >> 1;
;   const int fro0 = (lane & 15) * 128 + (((lane >> 4) ^ fsw) << 4);
;   const int fro1 = (lane & 15) * 128 + ((((lane >> 4) + 4) ^ fsw) << 4);
;   const int wof = lr * 128 + ((lc ^ ((lr >> 1) & 7)) << 4);
;     ...
;   GLOAD(0);
;   SWRITE(0);
; DI void phase_ffnup(const Params& p, int layer, unsigned char* smem) {
;     ...
;     const int g = it / (4 * NT), rem = it - g * (4 * NT), nt = rem >> 2, mt = g * 4 + (rem & 3);
;     const int b = mt / 17, ti = mt - b * 17, tbase = 254 * ti - 2;
;     f32x4 acc[8][4];
;     zero_acc<4, 8>(acc);
;     gemm_kloop<4, 8>(p.hb + ((ptrdiff_t)(b * TP + tbase)) * DM, DM, W + (size_t)(nt * 256) * DM, DM, DM, acc, smem);
.LBB0_23:
	s_mul_hi_i32 s2, s28, 0x2e8ba2e9
	s_lshr_b32 s3, s2, 31
	s_ashr_i32 s2, s2, 4
	s_add_i32 s53, s2, s3
	s_mul_i32 s2, s53, 0xffffffa8
	s_add_i32 s2, s2, s28
	s_ashr_i32 s34, s2, 2
	s_lshl_b32 s2, s53, 2
	s_and_b32 s3, s28, 3
	s_or_b32 s2, s2, s3
	s_mul_hi_i32 s3, s2, 0x78787879
	s_lshr_b32 s4, s3, 31
	s_ashr_i32 s3, s3, 3
	s_add_i32 s54, s3, s4
	s_mul_i32 s3, s54, 0xffffffef
	s_add_i32 s3, s3, s2
	s_mulk_i32 s3, 0xfe
	s_load_dwordx16 s[56:71], s[0:1], 0xc8
	s_add_i32 s35, s3, -2
	s_mul_i32 s2, s54, 0x1080
	v_mov_b32_e32 v52, v166
	s_add_i32 s4, s35, s2
	s_ashr_i32 s5, s4, 31
	v_lshlrev_b32_e32 v2, 3, v52
	v_ashrrev_i32_e32 v53, 3, v52
	v_and_b32_e32 v2, 56, v2
	s_and_b32 s52, s31, 3
	s_lshl_b64 s[4:5], s[4:5], 11
	v_lshl_or_b32 v2, v53, 10, v2
	s_waitcnt lgkmcnt(0)
	s_add_u32 s48, s56, s4
	v_ashrrev_i32_e32 v3, 31, v2
	s_addc_u32 s49, s57, s5
	s_waitcnt vmcnt(3)
	v_lshlrev_b64 v[34:35], 1, v[2:3]
	v_lshl_add_u64 v[36:37], s[48:49], 0, v[34:35]
	s_lshl_b32 s4, s34, 8
	s_waitcnt vmcnt(2)
	v_add_co_u32_e32 v38, vcc, s33, v36
	s_ashr_i32 s5, s4, 31
	s_nop 0
	v_addc_co_u32_e32 v39, vcc, 0, v37, vcc
	s_lshl_b64 s[4:5], s[4:5], 11
	v_add_co_u32_e32 v40, vcc, s36, v36
	s_add_u32 s50, s29, s4
	s_nop 0
	v_addc_co_u32_e32 v41, vcc, 0, v37, vcc
	s_addc_u32 s51, s30, s5
	s_waitcnt vmcnt(1)
	v_add_co_u32_e32 v42, vcc, s37, v36
	v_lshl_add_u64 v[44:45], s[50:51], 0, v[34:35]
	s_nop 0
	v_addc_co_u32_e32 v43, vcc, 0, v37, vcc
	s_waitcnt vmcnt(0)
	s_mov_b64 s[88:89], s[48:49]
	s_mov_b64 s[90:91], s[50:51]
	v_lshrrev_b32_e32 v190, 3, v166
	v_lshlrev_b32_e32 v191, 4, v166
	v_xor_b32_e32 v191, v191, v166
	v_and_b32_e32 v191, 0x70, v191
	v_lshl_or_b32 v186, v190, 11, v191
	v_lshrrev_b32_e32 v192, 6, v166
	s_nop 0
	v_readfirstlane_b32 s94, v192
	v_and_b32_e32 v190, 15, v166
	v_bfe_u32 v191, v166, 4, 2
	v_lshrrev_b32_e32 v192, 1, v190
	v_xor_b32_e32 v230, v191, v192
	v_or_b32_e32 v191, 4, v191
	v_xor_b32_e32 v231, v191, v192
	v_lshlrev_b32_e32 v190, 7, v190
	v_lshl_or_b32 v230, v230, 4, v190
	v_lshl_or_b32 v231, v231, 4, v190
	v_lshrrev_b32_e32 v190, 7, v166
	v_bfe_u32 v191, v166, 6, 1
	v_mul_u32_u24_e32 v191, 0x4000, v191
	v_add_u32_e32 v232, v191, v230
	v_add_u32_e32 v233, v191, v231
	v_mul_u32_u24_e32 v190, 0x2000, v190
	v_add_u32_e32 v230, v190, v230
	v_add_u32_e32 v231, v190, v231
	s_lshl_b32 s94, s94, 10
	s_mov_b32 m0, s94
	s_nop 0
	global_load_lds_dwordx4 v186, s[88:89]
	s_add_u32 m0, m0, 0x2000
	s_add_u32 s92, s88, 0x20000
	s_addc_u32 s93, s89, 0
	global_load_lds_dwordx4 v186, s[92:93]
	s_add_u32 m0, m0, 0x2000
	s_add_u32 s92, s88, 0x40000
	s_addc_u32 s93, s89, 0
	global_load_lds_dwordx4 v186, s[92:93]
	s_add_u32 m0, m0, 0x2000
	s_add_u32 s92, s88, 0x60000
	s_addc_u32 s93, s89, 0
	global_load_lds_dwordx4 v186, s[92:93]
	s_add_u32 m0, m0, 0x2000
	s_nop 0
	global_load_lds_dwordx4 v186, s[90:91]
	s_add_u32 m0, m0, 0x2000
	s_add_u32 s92, s90, 0x20000
	s_addc_u32 s93, s91, 0
	global_load_lds_dwordx4 v186, s[92:93]
	s_add_u32 m0, m0, 0x2000
	s_add_u32 s92, s90, 0x40000
	s_addc_u32 s93, s91, 0
	global_load_lds_dwordx4 v186, s[92:93]
	s_add_u32 m0, m0, 0x2000
	s_add_u32 s92, s90, 0x60000
	s_addc_u32 s93, s91, 0
	global_load_lds_dwordx4 v186, s[92:93]
	s_add_u32 s88, s88, 0x80
	s_addc_u32 s89, s89, 0
	s_add_u32 s90, s90, 0x80
	s_addc_u32 s91, s91, 0
	v_add_co_u32_e32 v46, vcc, s33, v44
	v_addc_co_u32_e32 v47, vcc, 0, v45, vcc
	v_add_co_u32_e32 v48, vcc, s36, v44
	v_addc_co_u32_e32 v49, vcc, 0, v45, vcc
	v_add_co_u32_e32 v50, vcc, s37, v44
	v_addc_co_u32_e32 v51, vcc, 0, v45, vcc
	s_add_u32 s4, s23, s4
	s_addc_u32 s5, s21, s5
	s_mulk_i32 s52, 0xfe
	v_lshl_add_u64 v[168:169], s[4:5], 0, v[34:35]
	s_mul_i32 s4, s53, 0x3f8
	s_add_i32 s4, s4, s52
	s_mulk_i32 s54, 0x5e
	s_sub_i32 s4, s4, s54
	v_lshlrev_b32_e32 v58, 4, v52
	s_add_i32 s4, s4, -2
	v_and_b32_e32 v54, 15, v52
	v_bfe_u32 v55, v52, 1, 3
	v_lshrrev_b32_e32 v56, 4, v52
	v_bfe_u32 v57, v52, 4, 2
	v_lshlrev_b32_e32 v59, 6, v52
	v_lshlrev_b32_e32 v60, 8, v52
	v_xor_b32_e32 v52, v58, v52
	v_lshlrev_b32_e32 v53, 7, v53
	s_ashr_i32 s5, s4, 31
	v_and_or_b32 v177, v52, s12, v53
	s_lshl_b64 s[4:5], s[4:5], 11
	v_lshlrev_b32_e32 v54, 7, v54
	v_bitop3_b32 v56, v56, v55, 3 bitop3:0x6c
	s_add_u32 s4, s56, s4
	v_lshl_or_b32 v176, v56, 4, v54
	s_addc_u32 s5, s57, s5
	s_mov_b32 s48, 0
	v_and_b32_e32 v174, 0xffffe000, v59
	v_and_b32_e32 v175, 0x4000, v60
	v_lshl_add_u64 v[170:171], s[4:5], 0, v[34:35]
	s_mov_b64 s[4:5], 0
	v_bitop3_b32 v2, v57, v55, 4 bitop3:0x36
	v_lshl_or_b32 v173, v2, 4, v54
	v_mov_b32_e32 v54, 0
	v_mov_b32_e32 v55, v54
	v_mov_b32_e32 v56, v54
	v_mov_b32_e32 v57, v54
	v_mov_b32_e32 v38, v54
	v_mov_b32_e32 v39, v54
	v_mov_b32_e32 v40, v54
	v_mov_b32_e32 v41, v54
	v_mov_b32_e32 v26, v54
	v_mov_b32_e32 v27, v54
	v_mov_b32_e32 v28, v54
	v_mov_b32_e32 v29, v54
	v_mov_b32_e32 v10, v54
	v_mov_b32_e32 v11, v54
	v_mov_b32_e32 v12, v54
	v_mov_b32_e32 v13, v54
	v_mov_b32_e32 v30, v54
	v_mov_b32_e32 v31, v54
	v_mov_b32_e32 v32, v54
	v_mov_b32_e32 v33, v54
	v_mov_b32_e32 v2, v54
	v_mov_b32_e32 v3, v54
	v_mov_b32_e32 v4, v54
	v_mov_b32_e32 v5, v54
	v_mov_b32_e32 v6, v54
	v_mov_b32_e32 v7, v54
	v_mov_b32_e32 v8, v54
	v_mov_b32_e32 v9, v54
	v_mov_b32_e32 v14, v54
	v_mov_b32_e32 v15, v54
	v_mov_b32_e32 v16, v54
	v_mov_b32_e32 v17, v54
	v_mov_b32_e32 v18, v54
	v_mov_b32_e32 v19, v54
	v_mov_b32_e32 v20, v54
	v_mov_b32_e32 v21, v54
	v_mov_b32_e32 v22, v54
	v_mov_b32_e32 v23, v54
	v_mov_b32_e32 v24, v54
	v_mov_b32_e32 v25, v54
	v_mov_b32_e32 v34, v54
	v_mov_b32_e32 v35, v54
	v_mov_b32_e32 v36, v54
	v_mov_b32_e32 v37, v54
	v_mov_b32_e32 v42, v54
	v_mov_b32_e32 v43, v54
	v_mov_b32_e32 v44, v54
	v_mov_b32_e32 v45, v54
; DI f32x4 mfma16(bf16x8 a, bf16x8 b, f32x4 c) { return __builtin_amdgcn_mfma_f32_16x16x32_bf16(a, b, c, 0, 0, 0); }
; template <int MI, int NI>
; DI void gemm_kloop(const u16* Au, int lda, const u16* Bu, int ldb, int K, f32x4 (&acc)[NI][MI], unsigned char* smem) {
;     ...
;   for (int kt = 0; kt < nk; ++kt) {
;     __syncthreads();
;     if (kt + 1 < nk) {
;       SWRITE((kt + 1) & 1);
;       if (kt + 2 < nk) GLOAD((kt + 2) << 6);
;     }
;     {
;       const unsigned char* sa = smem + (kt & 1) * 65536;
;       const unsigned char* sb = sa + 32768;
; #pragma unroll
;       for (int ks = 0; ks < 2; ++ks) {
;         const int fo = ks ? fro1 : fro0;
;         bf16x8 af[MI];
; #pragma unroll
;         for (int i = 0; i < MI; ++i) af[i] = *(const bf16x8*)(sa + (wm * 16 * MI + i * 16) * 128 + fo);
; #pragma unroll
;         for (int nh = 0; nh < NI; nh += 4) {
;           bf16x8 wf[4];
; #pragma unroll
;           for (int i = 0; i < 4; ++i) wf[i] = *(const bf16x8*)(sb + (wn * 16 * NI + (nh + i) * 16) * 128 + fo);
; #pragma unroll
;           for (int ni = 0; ni < 4; ++ni)
; #pragma unroll
;             for (int mi = 0; mi < MI; ++mi) acc[nh + ni][mi] = mfma16(wf[ni], af[mi], acc[nh + ni][mi]);
;         }
	v_mov_b32_e32 v46, v54
	v_mov_b32_e32 v47, v54
	v_mov_b32_e32 v48, v54
	v_mov_b32_e32 v49, v54
	v_mov_b32_e32 v50, v54
	v_mov_b32_e32 v51, v54
	v_mov_b32_e32 v52, v54
	v_mov_b32_e32 v53, v54
	v_mov_b32_e32 v58, v54
	v_mov_b32_e32 v59, v54
	v_mov_b32_e32 v60, v54
	v_mov_b32_e32 v61, v54
	v_mov_b32_e32 v62, v54
	v_mov_b32_e32 v63, v54
	v_mov_b32_e32 v64, v54
	v_mov_b32_e32 v65, v54
	v_mov_b32_e32 v66, v54
	v_mov_b32_e32 v67, v54
	v_mov_b32_e32 v68, v54
	v_mov_b32_e32 v69, v54
	v_mov_b32_e32 v70, v54
	v_mov_b32_e32 v71, v54
	v_mov_b32_e32 v72, v54
	v_mov_b32_e32 v73, v54
	v_mov_b32_e32 v74, v54
	v_mov_b32_e32 v75, v54
	v_mov_b32_e32 v76, v54
	v_mov_b32_e32 v77, v54
	v_mov_b32_e32 v78, v54
	v_mov_b32_e32 v79, v54
	v_mov_b32_e32 v80, v54
	v_mov_b32_e32 v81, v54
	v_mov_b32_e32 v82, v54
	v_mov_b32_e32 v83, v54
	v_mov_b32_e32 v84, v54
	v_mov_b32_e32 v85, v54
	v_mov_b32_e32 v86, v54
	v_mov_b32_e32 v87, v54
	v_mov_b32_e32 v88, v54
	v_mov_b32_e32 v89, v54
	v_mov_b32_e32 v90, v54
	v_mov_b32_e32 v91, v54
	v_mov_b32_e32 v92, v54
	v_mov_b32_e32 v93, v54
	v_mov_b32_e32 v94, v54
	v_mov_b32_e32 v95, v54
	v_mov_b32_e32 v96, v54
	v_mov_b32_e32 v97, v54
	v_mov_b32_e32 v98, v54
	v_mov_b32_e32 v99, v54
	v_mov_b32_e32 v100, v54
	v_mov_b32_e32 v101, v54
	v_mov_b32_e32 v102, v54
	v_mov_b32_e32 v103, v54
	v_mov_b32_e32 v104, v54
	v_mov_b32_e32 v105, v54
	v_mov_b32_e32 v106, v54
	v_mov_b32_e32 v107, v54
	v_mov_b32_e32 v108, v54
	v_mov_b32_e32 v109, v54
	v_mov_b32_e32 v114, v54
	v_mov_b32_e32 v115, v54
	v_mov_b32_e32 v116, v54
	v_mov_b32_e32 v117, v54
	v_mov_b32_e32 v146, v54
	v_mov_b32_e32 v147, v54
	v_mov_b32_e32 v148, v54
	v_mov_b32_e32 v149, v54
	v_mov_b32_e32 v154, v54
	v_mov_b32_e32 v155, v54
	v_mov_b32_e32 v156, v54
	v_mov_b32_e32 v157, v54
	v_mov_b32_e32 v150, v54
	v_mov_b32_e32 v151, v54
	v_mov_b32_e32 v152, v54
	v_mov_b32_e32 v153, v54
	v_mov_b32_e32 v158, v54
	v_mov_b32_e32 v159, v54
	v_mov_b32_e32 v160, v54
	v_mov_b32_e32 v161, v54
	s_mov_b32 s95, 0
.Lk_ffnup:
	s_waitcnt vmcnt(0) lgkmcnt(0)
	s_barrier
	ds_read_b128 v[118:121], v230
	ds_read_b128 v[122:125], v230 offset:2048
	ds_read_b128 v[130:133], v230 offset:4096
	ds_read_b128 v[134:137], v230 offset:6144
	ds_read_b128 v[110:113], v232 offset:32768
	ds_read_b128 v[126:129], v232 offset:34816
	ds_read_b128 v[162:165], v232 offset:36864
	s_and_b32 s92, s95, 1
	s_xor_b32 s92, s92, 1
	s_lshl_b32 s92, s92, 16
	s_waitcnt lgkmcnt(2)
	v_mfma_f32_16x16x32_bf16 v[114:117], v[110:113], v[118:121], v[114:117]
	ds_read_b128 v[226:229], v232 offset:38912
	v_mfma_f32_16x16x32_bf16 v[106:109], v[110:113], v[122:125], v[106:109]
	v_mfma_f32_16x16x32_bf16 v[102:105], v[110:113], v[130:133], v[102:105]
	s_add_u32 m0, s92, s94
	s_nop 0
	global_load_lds_dwordx4 v186, s[88:89]
	v_mfma_f32_16x16x32_bf16 v[98:101], v[110:113], v[134:137], v[98:101]
	s_waitcnt lgkmcnt(2)
	v_mfma_f32_16x16x32_bf16 v[94:97], v[126:129], v[118:121], v[94:97]
	ds_read_b128 v[110:113], v232 offset:40960
	v_mfma_f32_16x16x32_bf16 v[90:93], v[126:129], v[122:125], v[90:93]
	ds_read_b128 v[138:141], v231
	v_mfma_f32_16x16x32_bf16 v[86:89], v[126:129], v[130:133], v[86:89]
	s_add_u32 m0, m0, 0x2000
	s_add_u32 s92, s88, 0x20000
	s_addc_u32 s93, s89, 0
	global_load_lds_dwordx4 v186, s[92:93]
	v_mfma_f32_16x16x32_bf16 v[82:85], v[126:129], v[134:137], v[82:85]
	s_waitcnt lgkmcnt(3)
	v_mfma_f32_16x16x32_bf16 v[78:81], v[162:165], v[118:121], v[78:81]
	ds_read_b128 v[126:129], v232 offset:43008
	v_mfma_f32_16x16x32_bf16 v[74:77], v[162:165], v[122:125], v[74:77]
	ds_read_b128 v[142:145], v231 offset:2048
	v_mfma_f32_16x16x32_bf16 v[70:73], v[162:165], v[130:133], v[70:73]
	s_add_u32 m0, m0, 0x2000
	s_add_u32 s92, s88, 0x40000
	s_addc_u32 s93, s89, 0
	global_load_lds_dwordx4 v186, s[92:93]
	v_mfma_f32_16x16x32_bf16 v[66:69], v[162:165], v[134:137], v[66:69]
	s_waitcnt lgkmcnt(4)
	v_mfma_f32_16x16x32_bf16 v[62:65], v[226:229], v[118:121], v[62:65]
	ds_read_b128 v[162:165], v232 offset:45056
	v_mfma_f32_16x16x32_bf16 v[58:61], v[226:229], v[122:125], v[58:61]
	ds_read_b128 v[178:181], v231 offset:4096
	v_mfma_f32_16x16x32_bf16 v[50:53], v[226:229], v[130:133], v[50:53]
	s_add_u32 m0, m0, 0x2000
	s_add_u32 s92, s88, 0x60000
	s_addc_u32 s93, s89, 0
	global_load_lds_dwordx4 v186, s[92:93]
	v_mfma_f32_16x16x32_bf16 v[46:49], v[226:229], v[134:137], v[46:49]
	s_waitcnt lgkmcnt(5)
	v_mfma_f32_16x16x32_bf16 v[42:45], v[110:113], v[118:121], v[42:45]
	ds_read_b128 v[226:229], v232 offset:47104
	v_mfma_f32_16x16x32_bf16 v[34:37], v[110:113], v[122:125], v[34:37]
	ds_read_b128 v[182:185], v231 offset:6144
	v_mfma_f32_16x16x32_bf16 v[22:25], v[110:113], v[130:133], v[22:25]
	s_add_u32 m0, m0, 0x2000
	s_nop 0
	global_load_lds_dwordx4 v186, s[90:91]
	v_mfma_f32_16x16x32_bf16 v[18:21], v[110:113], v[134:137], v[18:21]
	s_waitcnt lgkmcnt(5)
	v_mfma_f32_16x16x32_bf16 v[14:17], v[126:129], v[118:121], v[14:17]
	ds_read_b128 v[110:113], v233 offset:32768
	v_mfma_f32_16x16x32_bf16 v[6:9], v[126:129], v[122:125], v[6:9]
	v_mfma_f32_16x16x32_bf16 v[2:5], v[126:129], v[130:133], v[2:5]
	s_add_u32 m0, m0, 0x2000
	s_add_u32 s92, s90, 0x20000
	s_addc_u32 s93, s91, 0
	global_load_lds_dwordx4 v186, s[92:93]
	v_mfma_f32_16x16x32_bf16 v[30:33], v[126:129], v[134:137], v[30:33]
	s_waitcnt lgkmcnt(4)
	v_mfma_f32_16x16x32_bf16 v[10:13], v[162:165], v[118:121], v[10:13]
	ds_read_b128 v[126:129], v233 offset:34816
	v_mfma_f32_16x16x32_bf16 v[26:29], v[162:165], v[122:125], v[26:29]
	v_mfma_f32_16x16x32_bf16 v[38:41], v[162:165], v[130:133], v[38:41]
	s_add_u32 m0, m0, 0x2000
	s_add_u32 s92, s90, 0x40000
	s_addc_u32 s93, s91, 0
	global_load_lds_dwordx4 v186, s[92:93]
	v_mfma_f32_16x16x32_bf16 v[54:57], v[162:165], v[134:137], v[54:57]
	s_waitcnt lgkmcnt(3)
; DI f32x4 mfma16(bf16x8 a, bf16x8 b, f32x4 c) { return __builtin_amdgcn_mfma_f32_16x16x32_bf16(a, b, c, 0, 0, 0); }
; template <int MI, int NI>
; DI void gemm_kloop(const u16* Au, int lda, const u16* Bu, int ldb, int K, f32x4 (&acc)[NI][MI], unsigned char* smem) {
;     ...
;   for (int kt = 0; kt < nk; ++kt) {
;     __syncthreads();
;     if (kt + 1 < nk) {
;       SWRITE((kt + 1) & 1);
;       if (kt + 2 < nk) GLOAD((kt + 2) << 6);
;     }
;     {
;       const unsigned char* sa = smem + (kt & 1) * 65536;
;       const unsigned char* sb = sa + 32768;
; #pragma unroll
;       for (int ks = 0; ks < 2; ++ks) {
;         const int fo = ks ? fro1 : fro0;
;         bf16x8 af[MI];
; #pragma unroll
;         for (int i = 0; i < MI; ++i) af[i] = *(const bf16x8*)(sa + (wm * 16 * MI + i * 16) * 128 + fo);
; #pragma unroll
;         for (int nh = 0; nh < NI; nh += 4) {
;           bf16x8 wf[4];
; #pragma unroll
;           for (int i = 0; i < 4; ++i) wf[i] = *(const bf16x8*)(sb + (wn * 16 * NI + (nh + i) * 16) * 128 + fo);
; #pragma unroll
;           for (int ni = 0; ni < 4; ++ni)
; #pragma unroll
;             for (int mi = 0; mi < MI; ++mi) acc[nh + ni][mi] = mfma16(wf[ni], af[mi], acc[nh + ni][mi]);
;         }
	v_mfma_f32_16x16x32_bf16 v[146:149], v[226:229], v[118:121], v[146:149]
	ds_read_b128 v[162:165], v233 offset:36864
	v_mfma_f32_16x16x32_bf16 v[154:157], v[226:229], v[122:125], v[154:157]
	v_mfma_f32_16x16x32_bf16 v[150:153], v[226:229], v[130:133], v[150:153]
	s_add_u32 m0, m0, 0x2000
	s_add_u32 s92, s90, 0x60000
	s_addc_u32 s93, s91, 0
	global_load_lds_dwordx4 v186, s[92:93]
	v_mfma_f32_16x16x32_bf16 v[158:161], v[226:229], v[134:137], v[158:161]
	s_waitcnt lgkmcnt(2)
	v_mfma_f32_16x16x32_bf16 v[114:117], v[110:113], v[138:141], v[114:117]
	ds_read_b128 v[226:229], v233 offset:38912
	v_mfma_f32_16x16x32_bf16 v[106:109], v[110:113], v[142:145], v[106:109]
	v_mfma_f32_16x16x32_bf16 v[102:105], v[110:113], v[178:181], v[102:105]
	v_mfma_f32_16x16x32_bf16 v[98:101], v[110:113], v[182:185], v[98:101]
	s_waitcnt lgkmcnt(2)
	v_mfma_f32_16x16x32_bf16 v[94:97], v[126:129], v[138:141], v[94:97]
	ds_read_b128 v[110:113], v233 offset:40960
	v_mfma_f32_16x16x32_bf16 v[90:93], v[126:129], v[142:145], v[90:93]
	v_mfma_f32_16x16x32_bf16 v[86:89], v[126:129], v[178:181], v[86:89]
	v_mfma_f32_16x16x32_bf16 v[82:85], v[126:129], v[182:185], v[82:85]
	s_waitcnt lgkmcnt(2)
	v_mfma_f32_16x16x32_bf16 v[78:81], v[162:165], v[138:141], v[78:81]
	ds_read_b128 v[126:129], v233 offset:43008
	v_mfma_f32_16x16x32_bf16 v[74:77], v[162:165], v[142:145], v[74:77]
	v_mfma_f32_16x16x32_bf16 v[70:73], v[162:165], v[178:181], v[70:73]
	v_mfma_f32_16x16x32_bf16 v[66:69], v[162:165], v[182:185], v[66:69]
	s_waitcnt lgkmcnt(2)
	v_mfma_f32_16x16x32_bf16 v[62:65], v[226:229], v[138:141], v[62:65]
	ds_read_b128 v[162:165], v233 offset:45056
	v_mfma_f32_16x16x32_bf16 v[58:61], v[226:229], v[142:145], v[58:61]
	v_mfma_f32_16x16x32_bf16 v[50:53], v[226:229], v[178:181], v[50:53]
	v_mfma_f32_16x16x32_bf16 v[46:49], v[226:229], v[182:185], v[46:49]
	s_waitcnt lgkmcnt(2)
	v_mfma_f32_16x16x32_bf16 v[42:45], v[110:113], v[138:141], v[42:45]
	ds_read_b128 v[226:229], v233 offset:47104
	v_mfma_f32_16x16x32_bf16 v[34:37], v[110:113], v[142:145], v[34:37]
	v_mfma_f32_16x16x32_bf16 v[22:25], v[110:113], v[178:181], v[22:25]
	v_mfma_f32_16x16x32_bf16 v[18:21], v[110:113], v[182:185], v[18:21]
	s_waitcnt lgkmcnt(2)
	v_mfma_f32_16x16x32_bf16 v[14:17], v[126:129], v[138:141], v[14:17]
	v_mfma_f32_16x16x32_bf16 v[6:9], v[126:129], v[142:145], v[6:9]
	v_mfma_f32_16x16x32_bf16 v[2:5], v[126:129], v[178:181], v[2:5]
	v_mfma_f32_16x16x32_bf16 v[30:33], v[126:129], v[182:185], v[30:33]
	s_waitcnt lgkmcnt(1)
	v_mfma_f32_16x16x32_bf16 v[10:13], v[162:165], v[138:141], v[10:13]
	v_mfma_f32_16x16x32_bf16 v[26:29], v[162:165], v[142:145], v[26:29]
	v_mfma_f32_16x16x32_bf16 v[38:41], v[162:165], v[178:181], v[38:41]
	v_mfma_f32_16x16x32_bf16 v[54:57], v[162:165], v[182:185], v[54:57]
	s_waitcnt lgkmcnt(0)
	v_mfma_f32_16x16x32_bf16 v[146:149], v[226:229], v[138:141], v[146:149]
	v_mfma_f32_16x16x32_bf16 v[154:157], v[226:229], v[142:145], v[154:157]
	v_mfma_f32_16x16x32_bf16 v[150:153], v[226:229], v[178:181], v[150:153]
	v_mfma_f32_16x16x32_bf16 v[158:161], v[226:229], v[182:185], v[158:161]
	v_xor_b32_e32 v230, 0x10000, v230
	v_xor_b32_e32 v231, 0x10000, v231
	v_xor_b32_e32 v232, 0x10000, v232
	v_xor_b32_e32 v233, 0x10000, v233
	s_add_u32 s88, s88, 0x80
	s_addc_u32 s89, s89, 0
	s_add_u32 s90, s90, 0x80
	s_addc_u32 s91, s91, 0
	s_add_u32 s95, s95, 1
	s_cmp_lg_u32 s95, 14
	s_cbranch_scc1 .Lk_ffnup
	s_waitcnt vmcnt(0)
	s_barrier
	s_add_u32 m0, s94, 0x10000
	s_nop 0
	global_load_lds_dwordx4 v186, s[88:89]
	s_add_u32 m0, m0, 0x2000
	s_add_u32 s92, s88, 0x20000
	s_addc_u32 s93, s89, 0
	global_load_lds_dwordx4 v186, s[92:93]
	s_add_u32 m0, m0, 0x2000
	s_add_u32 s92, s88, 0x40000
	s_addc_u32 s93, s89, 0
	global_load_lds_dwordx4 v186, s[92:93]
	s_add_u32 m0, m0, 0x2000
	s_add_u32 s92, s88, 0x60000
	s_addc_u32 s93, s89, 0
	global_load_lds_dwordx4 v186, s[92:93]
	s_add_u32 m0, m0, 0x2000
	s_nop 0
	global_load_lds_dwordx4 v186, s[90:91]
	s_add_u32 m0, m0, 0x2000
	s_add_u32 s92, s90, 0x20000
	s_addc_u32 s93, s91, 0
	global_load_lds_dwordx4 v186, s[92:93]
	s_add_u32 m0, m0, 0x2000
	s_add_u32 s92, s90, 0x40000
	s_addc_u32 s93, s91, 0
	global_load_lds_dwordx4 v186, s[92:93]
	s_add_u32 m0, m0, 0x2000
	s_add_u32 s92, s90, 0x60000
	s_addc_u32 s93, s91, 0
	global_load_lds_dwordx4 v186, s[92:93]
	v_add_u32_e32 v138, v175, v176
	ds_read_b128 v[110:113], v138 offset:32768
	v_add_u32_e32 v134, v174, v176
	ds_read_b128 v[118:121], v134
	ds_read_b128 v[122:125], v134 offset:2048
	ds_read_b128 v[126:129], v138 offset:34816
	ds_read_b128 v[130:133], v134 offset:4096
	ds_read_b128 v[134:137], v134 offset:6144
	s_waitcnt lgkmcnt(4)
	v_mfma_f32_16x16x32_bf16 v[114:117], v[110:113], v[118:121], v[114:117]
	v_or_b32_e32 v186, 0x18000, v175
	v_add_u32_e32 v187, v186, v176
	v_add_u32_e32 v190, 0x10000, v174
	s_waitcnt lgkmcnt(3)
	v_mfma_f32_16x16x32_bf16 v[106:109], v[110:113], v[122:125], v[106:109]
	v_add_u32_e32 v194, v186, v173
	s_movk_i32 s4, 0x1080
	s_waitcnt lgkmcnt(1)
	v_mfma_f32_16x16x32_bf16 v[102:105], v[110:113], v[130:133], v[102:105]
	s_waitcnt lgkmcnt(0)
	v_mfma_f32_16x16x32_bf16 v[98:101], v[110:113], v[134:137], v[98:101]
	v_mfma_f32_16x16x32_bf16 v[94:97], v[126:129], v[118:121], v[94:97]
	v_mfma_f32_16x16x32_bf16 v[90:93], v[126:129], v[122:125], v[90:93]
	v_mfma_f32_16x16x32_bf16 v[86:89], v[126:129], v[130:133], v[86:89]
	v_mfma_f32_16x16x32_bf16 v[82:85], v[126:129], v[134:137], v[82:85]
	ds_read_b128 v[110:113], v138 offset:36864
	ds_read_b128 v[126:129], v138 offset:38912
	s_waitcnt lgkmcnt(1)
; DI f32x4 mfma16(bf16x8 a, bf16x8 b, f32x4 c) { return __builtin_amdgcn_mfma_f32_16x16x32_bf16(a, b, c, 0, 0, 0); }
; template <int MI, int NI>
; DI void gemm_kloop(const u16* Au, int lda, const u16* Bu, int ldb, int K, f32x4 (&acc)[NI][MI], unsigned char* smem) {
;     ...
;     {
;       const unsigned char* sa = smem + (kt & 1) * 65536;
;       const unsigned char* sb = sa + 32768;
; #pragma unroll
;       for (int ks = 0; ks < 2; ++ks) {
;         const int fo = ks ? fro1 : fro0;
;         bf16x8 af[MI];
; #pragma unroll
;         for (int i = 0; i < MI; ++i) af[i] = *(const bf16x8*)(sa + (wm * 16 * MI + i * 16) * 128 + fo);
; #pragma unroll
;         for (int nh = 0; nh < NI; nh += 4) {
;           bf16x8 wf[4];
; #pragma unroll
;           for (int i = 0; i < 4; ++i) wf[i] = *(const bf16x8*)(sb + (wn * 16 * NI + (nh + i) * 16) * 128 + fo);
; #pragma unroll
;           for (int ni = 0; ni < 4; ++ni)
; #pragma unroll
;             for (int mi = 0; mi < MI; ++mi) acc[nh + ni][mi] = mfma16(wf[ni], af[mi], acc[nh + ni][mi]);
;         }
	v_mfma_f32_16x16x32_bf16 v[78:81], v[110:113], v[118:121], v[78:81]
	v_mfma_f32_16x16x32_bf16 v[74:77], v[110:113], v[122:125], v[74:77]
	v_mfma_f32_16x16x32_bf16 v[70:73], v[110:113], v[130:133], v[70:73]
	v_mfma_f32_16x16x32_bf16 v[66:69], v[110:113], v[134:137], v[66:69]
	s_waitcnt lgkmcnt(0)
	v_mfma_f32_16x16x32_bf16 v[62:65], v[126:129], v[118:121], v[62:65]
	v_mfma_f32_16x16x32_bf16 v[58:61], v[126:129], v[122:125], v[58:61]
	v_mfma_f32_16x16x32_bf16 v[50:53], v[126:129], v[130:133], v[50:53]
	v_mfma_f32_16x16x32_bf16 v[46:49], v[126:129], v[134:137], v[46:49]
	ds_read_b128 v[110:113], v138 offset:40960
	ds_read_b128 v[126:129], v138 offset:43008
	s_waitcnt lgkmcnt(1)
	v_mfma_f32_16x16x32_bf16 v[42:45], v[110:113], v[118:121], v[42:45]
	v_mfma_f32_16x16x32_bf16 v[34:37], v[110:113], v[122:125], v[34:37]
	v_mfma_f32_16x16x32_bf16 v[22:25], v[110:113], v[130:133], v[22:25]
	v_mfma_f32_16x16x32_bf16 v[18:21], v[110:113], v[134:137], v[18:21]
	s_waitcnt lgkmcnt(0)
	v_mfma_f32_16x16x32_bf16 v[14:17], v[126:129], v[118:121], v[14:17]
	v_mfma_f32_16x16x32_bf16 v[6:9], v[126:129], v[122:125], v[6:9]
	v_mfma_f32_16x16x32_bf16 v[2:5], v[126:129], v[130:133], v[2:5]
	v_mfma_f32_16x16x32_bf16 v[30:33], v[126:129], v[134:137], v[30:33]
	ds_read_b128 v[110:113], v138 offset:45056
	ds_read_b128 v[126:129], v138 offset:47104
	s_waitcnt lgkmcnt(1)
	v_mfma_f32_16x16x32_bf16 v[10:13], v[110:113], v[118:121], v[10:13]
	v_mfma_f32_16x16x32_bf16 v[26:29], v[110:113], v[122:125], v[26:29]
	v_mfma_f32_16x16x32_bf16 v[38:41], v[110:113], v[130:133], v[38:41]
	v_mfma_f32_16x16x32_bf16 v[54:57], v[110:113], v[134:137], v[54:57]
	s_waitcnt lgkmcnt(0)
	v_mfma_f32_16x16x32_bf16 v[110:113], v[126:129], v[118:121], v[146:149]
	v_mfma_f32_16x16x32_bf16 v[118:121], v[126:129], v[122:125], v[154:157]
	s_nop 2
	v_add_u32_e32 v154, v175, v173
	v_mfma_f32_16x16x32_bf16 v[122:125], v[126:129], v[130:133], v[150:153]
	ds_read_b128 v[130:133], v154 offset:32768
	s_nop 1
	v_add_u32_e32 v150, v174, v173
	v_mfma_f32_16x16x32_bf16 v[126:129], v[126:129], v[134:137], v[158:161]
	ds_read_b128 v[134:137], v150
	ds_read_b128 v[138:141], v150 offset:2048
	ds_read_b128 v[142:145], v154 offset:34816
	ds_read_b128 v[146:149], v150 offset:4096
	ds_read_b128 v[150:153], v150 offset:6144
	s_waitcnt lgkmcnt(4)
	v_mfma_f32_16x16x32_bf16 v[114:117], v[130:133], v[134:137], v[114:117]
	s_waitcnt lgkmcnt(3)
	v_mfma_f32_16x16x32_bf16 v[106:109], v[130:133], v[138:141], v[106:109]
	s_waitcnt lgkmcnt(1)
	v_mfma_f32_16x16x32_bf16 v[102:105], v[130:133], v[146:149], v[102:105]
	s_waitcnt lgkmcnt(0)
	v_mfma_f32_16x16x32_bf16 v[98:101], v[130:133], v[150:153], v[98:101]
	v_mfma_f32_16x16x32_bf16 v[94:97], v[142:145], v[134:137], v[94:97]
	v_mfma_f32_16x16x32_bf16 v[90:93], v[142:145], v[138:141], v[90:93]
	v_mfma_f32_16x16x32_bf16 v[86:89], v[142:145], v[146:149], v[86:89]
	v_mfma_f32_16x16x32_bf16 v[82:85], v[142:145], v[150:153], v[82:85]
	ds_read_b128 v[130:133], v154 offset:36864
	ds_read_b128 v[142:145], v154 offset:38912
	s_waitcnt lgkmcnt(1)
	v_mfma_f32_16x16x32_bf16 v[78:81], v[130:133], v[134:137], v[78:81]
	v_mfma_f32_16x16x32_bf16 v[74:77], v[130:133], v[138:141], v[74:77]
	v_mfma_f32_16x16x32_bf16 v[70:73], v[130:133], v[146:149], v[70:73]
	v_mfma_f32_16x16x32_bf16 v[66:69], v[130:133], v[150:153], v[66:69]
	s_waitcnt lgkmcnt(0)
	v_mfma_f32_16x16x32_bf16 v[62:65], v[142:145], v[134:137], v[62:65]
	v_mfma_f32_16x16x32_bf16 v[58:61], v[142:145], v[138:141], v[58:61]
	v_mfma_f32_16x16x32_bf16 v[50:53], v[142:145], v[146:149], v[50:53]
	v_mfma_f32_16x16x32_bf16 v[46:49], v[142:145], v[150:153], v[46:49]
	ds_read_b128 v[130:133], v154 offset:40960
	ds_read_b128 v[142:145], v154 offset:43008
	s_waitcnt lgkmcnt(1)
	v_mfma_f32_16x16x32_bf16 v[42:45], v[130:133], v[134:137], v[42:45]
	v_mfma_f32_16x16x32_bf16 v[34:37], v[130:133], v[138:141], v[34:37]
	v_mfma_f32_16x16x32_bf16 v[22:25], v[130:133], v[146:149], v[22:25]
	v_mfma_f32_16x16x32_bf16 v[18:21], v[130:133], v[150:153], v[18:21]
	s_waitcnt lgkmcnt(0)
	v_mfma_f32_16x16x32_bf16 v[14:17], v[142:145], v[134:137], v[14:17]
	v_mfma_f32_16x16x32_bf16 v[6:9], v[142:145], v[138:141], v[6:9]
	v_mfma_f32_16x16x32_bf16 v[2:5], v[142:145], v[146:149], v[2:5]
	v_mfma_f32_16x16x32_bf16 v[30:33], v[142:145], v[150:153], v[30:33]
	ds_read_b128 v[130:133], v154 offset:45056
	ds_read_b128 v[142:145], v154 offset:47104
	s_waitcnt vmcnt(0) lgkmcnt(0)
	s_barrier
; DI f32x4 mfma16(bf16x8 a, bf16x8 b, f32x4 c) { return __builtin_amdgcn_mfma_f32_16x16x32_bf16(a, b, c, 0, 0, 0); }
; template <int MI, int NI>
; DI void gemm_kloop(const u16* Au, int lda, const u16* Bu, int ldb, int K, f32x4 (&acc)[NI][MI], unsigned char* smem) {
;     ...
;     {
;       const unsigned char* sa = smem + (kt & 1) * 65536;
;       const unsigned char* sb = sa + 32768;
; #pragma unroll
;       for (int ks = 0; ks < 2; ++ks) {
;         const int fo = ks ? fro1 : fro0;
;         bf16x8 af[MI];
; #pragma unroll
;         for (int i = 0; i < MI; ++i) af[i] = *(const bf16x8*)(sa + (wm * 16 * MI + i * 16) * 128 + fo);
; #pragma unroll
;         for (int nh = 0; nh < NI; nh += 4) {
;           bf16x8 wf[4];
; #pragma unroll
;           for (int i = 0; i < 4; ++i) wf[i] = *(const bf16x8*)(sb + (wn * 16 * NI + (nh + i) * 16) * 128 + fo);
; #pragma unroll
;           for (int ni = 0; ni < 4; ++ni)
; #pragma unroll
;             for (int mi = 0; mi < MI; ++mi) acc[nh + ni][mi] = mfma16(wf[ni], af[mi], acc[nh + ni][mi]);
;         }
;       }
;     }
;   }
;   __syncthreads();
	v_mfma_f32_16x16x32_bf16 v[10:13], v[130:133], v[134:137], v[10:13]
	v_mfma_f32_16x16x32_bf16 v[26:29], v[130:133], v[138:141], v[26:29]
	v_mfma_f32_16x16x32_bf16 v[38:41], v[130:133], v[146:149], v[38:41]
	v_mfma_f32_16x16x32_bf16 v[54:57], v[130:133], v[150:153], v[54:57]
	ds_read_b128 v[130:133], v187
	v_mfma_f32_16x16x32_bf16 v[122:125], v[142:145], v[146:149], v[122:125]
	v_add_u32_e32 v146, v190, v176
	v_mfma_f32_16x16x32_bf16 v[110:113], v[142:145], v[134:137], v[110:113]
	ds_read_b128 v[134:137], v146
	v_mfma_f32_16x16x32_bf16 v[118:121], v[142:145], v[138:141], v[118:121]
	ds_read_b128 v[138:141], v146 offset:2048
	v_mfma_f32_16x16x32_bf16 v[126:129], v[142:145], v[150:153], v[126:129]
	ds_read_b128 v[142:145], v146 offset:4096
	ds_read_b128 v[146:149], v146 offset:6144
	s_waitcnt lgkmcnt(3)
	v_mfma_f32_16x16x32_bf16 v[114:117], v[130:133], v[134:137], v[114:117]
	s_waitcnt lgkmcnt(2)
	v_mfma_f32_16x16x32_bf16 v[106:109], v[130:133], v[138:141], v[106:109]
	s_waitcnt lgkmcnt(1)
	v_mfma_f32_16x16x32_bf16 v[102:105], v[130:133], v[142:145], v[102:105]
	s_waitcnt lgkmcnt(0)
	v_mfma_f32_16x16x32_bf16 v[98:101], v[130:133], v[146:149], v[98:101]
	ds_read_b128 v[130:133], v187 offset:2048
	s_waitcnt lgkmcnt(0)
	v_mfma_f32_16x16x32_bf16 v[94:97], v[130:133], v[134:137], v[94:97]
	v_mfma_f32_16x16x32_bf16 v[90:93], v[130:133], v[138:141], v[90:93]
	v_mfma_f32_16x16x32_bf16 v[86:89], v[130:133], v[142:145], v[86:89]
	v_mfma_f32_16x16x32_bf16 v[82:85], v[130:133], v[146:149], v[82:85]
	ds_read_b128 v[130:133], v187 offset:4096
	s_waitcnt lgkmcnt(0)
	v_mfma_f32_16x16x32_bf16 v[78:81], v[130:133], v[134:137], v[78:81]
	v_mfma_f32_16x16x32_bf16 v[74:77], v[130:133], v[138:141], v[74:77]
	v_mfma_f32_16x16x32_bf16 v[70:73], v[130:133], v[142:145], v[70:73]
	v_mfma_f32_16x16x32_bf16 v[66:69], v[130:133], v[146:149], v[66:69]
	ds_read_b128 v[130:133], v187 offset:6144
	s_waitcnt lgkmcnt(0)
	v_mfma_f32_16x16x32_bf16 v[154:157], v[130:133], v[146:149], v[46:49]
	s_nop 2
	ds_read_b128 v[46:49], v187 offset:8192
	s_waitcnt lgkmcnt(0)
	v_mfma_f32_16x16x32_bf16 v[158:161], v[46:49], v[146:149], v[18:21]
	s_nop 2
	ds_read_b128 v[18:21], v187 offset:10240
	s_waitcnt lgkmcnt(0)
	v_mfma_f32_16x16x32_bf16 v[168:171], v[18:21], v[138:141], v[6:9]
	s_nop 2
	ds_read_b128 v[6:9], v187 offset:12288
	s_waitcnt lgkmcnt(0)
	v_mfma_f32_16x16x32_bf16 v[10:13], v[6:9], v[134:137], v[10:13]
	v_mfma_f32_16x16x32_bf16 v[174:177], v[6:9], v[138:141], v[26:29]
	v_mfma_f32_16x16x32_bf16 v[178:181], v[6:9], v[142:145], v[38:41]
	v_mfma_f32_16x16x32_bf16 v[182:185], v[6:9], v[146:149], v[54:57]
	ds_read_b128 v[6:9], v187 offset:14336
	s_nop 0
	ds_read_b128 v[38:41], v194
	v_mfma_f32_16x16x32_bf16 v[42:45], v[46:49], v[134:137], v[42:45]
	v_mfma_f32_16x16x32_bf16 v[34:37], v[46:49], v[138:141], v[34:37]
	v_mfma_f32_16x16x32_bf16 v[22:25], v[46:49], v[142:145], v[22:25]
	v_add_u32_e32 v46, v190, v173
	ds_read_b128 v[190:193], v46 offset:2048
	ds_read_b128 v[226:229], v46 offset:4096
	ds_read_b128 v[230:233], v46 offset:6144
	v_mfma_f32_16x16x32_bf16 v[30:33], v[18:21], v[146:149], v[30:33]
	s_waitcnt lgkmcnt(4)
	v_mfma_f32_16x16x32_bf16 v[126:129], v[6:9], v[146:149], v[126:129]
	ds_read_b128 v[146:149], v46
	v_mfma_f32_16x16x32_bf16 v[62:65], v[130:133], v[134:137], v[62:65]
	v_mfma_f32_16x16x32_bf16 v[150:153], v[130:133], v[138:141], v[58:61]
	v_mfma_f32_16x16x32_bf16 v[162:165], v[18:21], v[134:137], v[14:17]
	v_mfma_f32_16x16x32_bf16 v[2:5], v[18:21], v[142:145], v[2:5]
	v_mfma_f32_16x16x32_bf16 v[134:137], v[6:9], v[134:137], v[110:113]
	v_mfma_f32_16x16x32_bf16 v[138:141], v[6:9], v[138:141], v[118:121]
	v_mfma_f32_16x16x32_bf16 v[186:189], v[6:9], v[142:145], v[122:125]
	s_waitcnt lgkmcnt(0)
	v_mfma_f32_16x16x32_bf16 v[26:29], v[38:41], v[146:149], v[114:117]
	v_mfma_f32_16x16x32_bf16 v[18:21], v[38:41], v[190:193], v[106:109]
	v_mfma_f32_16x16x32_bf16 v[14:17], v[38:41], v[226:229], v[102:105]
	v_mfma_f32_16x16x32_bf16 v[6:9], v[38:41], v[230:233], v[98:101]
	ds_read_b128 v[38:41], v194 offset:2048
	v_mfma_f32_16x16x32_bf16 v[50:53], v[130:133], v[142:145], v[50:53]
	s_waitcnt lgkmcnt(0)
	v_mfma_f32_16x16x32_bf16 v[142:145], v[38:41], v[146:149], v[94:97]
	v_mfma_f32_16x16x32_bf16 v[130:133], v[38:41], v[190:193], v[90:93]
	v_mfma_f32_16x16x32_bf16 v[106:109], v[38:41], v[226:229], v[86:89]
	v_mfma_f32_16x16x32_bf16 v[98:101], v[38:41], v[230:233], v[82:85]
	ds_read_b128 v[38:41], v194 offset:4096
	s_waitcnt lgkmcnt(0)
	v_mfma_f32_16x16x32_bf16 v[58:61], v[38:41], v[146:149], v[78:81]
	v_mfma_f32_16x16x32_bf16 v[54:57], v[38:41], v[190:193], v[74:77]
	v_mfma_f32_16x16x32_bf16 v[46:49], v[38:41], v[226:229], v[70:73]
	v_mfma_f32_16x16x32_bf16 v[38:41], v[38:41], v[230:233], v[66:69]
	s_nop 2
	ds_read_b128 v[66:69], v194 offset:6144
	s_waitcnt lgkmcnt(0)
	v_mfma_f32_16x16x32_bf16 v[74:77], v[66:69], v[226:229], v[50:53]
	s_nop 2
	ds_read_b128 v[50:53], v194 offset:8192
	s_waitcnt lgkmcnt(0)
	v_mfma_f32_16x16x32_bf16 v[70:73], v[50:53], v[226:229], v[22:25]
	s_nop 2
	ds_read_b128 v[22:25], v194 offset:10240
	v_mfma_f32_16x16x32_bf16 v[86:89], v[50:53], v[146:149], v[42:45]
	s_waitcnt lgkmcnt(0)
	v_mfma_f32_16x16x32_bf16 v[42:45], v[22:25], v[226:229], v[2:5]
	s_nop 2
	ds_read_b128 v[2:5], v194 offset:12288
	s_waitcnt lgkmcnt(0)
	v_mfma_f32_16x16x32_bf16 v[122:125], v[2:5], v[146:149], v[10:13]
	v_mfma_f32_16x16x32_bf16 v[118:121], v[2:5], v[190:193], v[174:177]
	v_mfma_f32_16x16x32_bf16 v[102:105], v[2:5], v[226:229], v[178:181]
	v_mfma_f32_16x16x32_bf16 v[114:117], v[2:5], v[230:233], v[182:185]
	ds_read_b128 v[2:5], v194 offset:14336
	s_waitcnt lgkmcnt(0)
	s_barrier
; DI f32x4 mfma16(bf16x8 a, bf16x8 b, f32x4 c) { return __builtin_amdgcn_mfma_f32_16x16x32_bf16(a, b, c, 0, 0, 0); }
; template <int MI, int NI>
; DI void gemm_kloop(const u16* Au, int lda, const u16* Bu, int ldb, int K, f32x4 (&acc)[NI][MI], unsigned char* smem) {
;     ...
;           for (int ni = 0; ni < 4; ++ni)
; #pragma unroll
;             for (int mi = 0; mi < MI; ++mi) acc[nh + ni][mi] = mfma16(wf[ni], af[mi], acc[nh + ni][mi]);
;         }
;       }
;     }
;   }
;   __syncthreads();
; DI void phase_ffnup(const Params& p, int layer, unsigned char* smem) {
;     ...
;     for (int mi = 0; mi < 4; ++mi) {
;       const int r = r0 + mi * 16;
;       tt[mi] = tbase + r;
;       float rs = (tt[mi] >= 0 && tt[mi] < TP) ? rsqrtf(rowss[b * TP + tt[mi]] * (1.f / DM) + EPS) : 0.f;
	v_mfma_f32_16x16x32_bf16 v[94:97], v[66:69], v[146:149], v[62:65]
	v_mfma_f32_16x16x32_bf16 v[82:85], v[66:69], v[190:193], v[150:153]
	v_mfma_f32_16x16x32_bf16 v[66:69], v[66:69], v[230:233], v[154:157]
	s_nop 1
	v_mov_b32_e32 v152, 0
	v_mfma_f32_16x16x32_bf16 v[78:81], v[50:53], v[190:193], v[34:37]
	v_mov_b32_e32 v154, 0
	v_mfma_f32_16x16x32_bf16 v[110:113], v[50:53], v[230:233], v[158:161]
	v_mfma_f32_16x16x32_bf16 v[62:65], v[22:25], v[146:149], v[162:165]
	s_nop 1
	v_mov_b32_e32 v160, v0
	v_mfma_f32_16x16x32_bf16 v[50:53], v[22:25], v[190:193], v[168:171]
	v_mfma_f32_16x16x32_bf16 v[34:37], v[22:25], v[230:233], v[30:33]
	s_nop 1
	v_mov_b32_e32 v168, v172
	v_mfma_f32_16x16x32_bf16 v[30:33], v[2:5], v[146:149], v[134:137]
	v_add_u32_e32 v162, s35, v160
	v_cmp_gt_u32_e32 vcc, s4, v162
	v_mfma_f32_16x16x32_bf16 v[22:25], v[2:5], v[190:193], v[138:141]
	v_mfma_f32_16x16x32_bf16 v[10:13], v[2:5], v[226:229], v[186:189]
	v_mfma_f32_16x16x32_bf16 v[2:5], v[2:5], v[230:233], v[126:129]
	s_and_saveexec_b64 s[4:5], vcc
	s_cbranch_execz .LBB0_27
	s_ashr_i32 s35, s2, 31
	s_ashr_i32 s49, s3, 31
	s_add_u32 s48, s2, s3
	v_ashrrev_i32_e32 v161, 31, v160
	s_addc_u32 s49, s35, s49
	v_lshl_add_u64 v[90:91], s[48:49], 0, v[160:161]
	v_lshl_add_u64 v[90:91], v[90:91], 2, s[8:9]
	global_load_dword v90, v[90:91], off offset:-8
	s_waitcnt vmcnt(0)
	v_fmamk_f32 v90, v90, 0x3a800000, v199
	v_mul_f32_e32 v91, 0x4b800000, v90
	v_cmp_gt_f32_e32 vcc, s14, v90
	s_nop 1
	v_cndmask_b32_e32 v90, v90, v91, vcc
	v_rsq_f32_e32 v90, v90
	s_nop 0
	v_mul_f32_e32 v91, 0x45800000, v90
	v_cndmask_b32_e32 v154, v90, v91, vcc

; template <int MI, int NI>
; DI void gemm_kloop(const u16* Au, int lda, const u16* Bu, int ldb, int K, f32x4 (&acc)[NI][MI], unsigned char* smem) {
;   int tid_ = threadIdx.x; asm volatile("" : "+v"(tid_));
;   const int tid = tid_, lane = tid & 63, wave = tid >> 6, wm = wave >> 1, wn = wave & 1;
;   const int lr = tid >> 3, lc = tid & 7;
;   const int voa = lr * lda + lc * 8, vob = lr * ldb + lc * 8;
;   constexpr int NB2 = NI / 2;
;   u32x4 ra[MI], rb[NB2];
;   const int nk = K >> 6;
;   const int fsw = (lane & 15) >> 1;
;   const int fro0 = (lane & 15) * 128 + (((lane >> 4) ^ fsw) << 4);
;   const int fro1 = (lane & 15) * 128 + ((((lane >> 4) + 4) ^ fsw) << 4);
;   const int wof = lr * 128 + ((lc ^ ((lr >> 1) & 7)) << 4);
;     ...
;   GLOAD(0);
;   SWRITE(0);
; DI void phase_resid(const Params& p, int from_x, const u16* A, int K, const u16* W, float* rowss_next, bool last,
;                     unsigned char* smem) {
;     ...
;   for (int it = vblock(); it < nfull; it += gridDim.x) {
;     const int g = it / (4 * NT), rem = it - g * (4 * NT), nt = rem >> 2, mt = g * 4 + (rem & 3);
;     f32x4 acc[8][4];
;     zero_acc<4, 8>(acc);
;     gemm_kloop<4, 8>(A + (size_t)(mt * 256) * K, K, W + (size_t)(nt * 256) * K, K, K, acc, smem);
.LBB0_72:
	s_ashr_i32 s2, s49, 31
	s_lshr_b32 s2, s2, 28
	s_add_i32 s2, s49, s2
	s_lshl_b32 s2, s2, 6
	s_and_b32 s57, s2, 0xfffffc00
	s_lshl_b32 s2, s49, 8
	s_and_b32 s2, s2, 0x300
	v_mov_b32_e32 v52, v166
	s_or_b32 s34, s57, s2
	s_ashr_i32 s35, s34, 31
	v_lshlrev_b32_e32 v2, 3, v52
	v_ashrrev_i32_e32 v53, 3, v52
	v_and_b32_e32 v2, 56, v2
	s_and_b32 s56, s52, 0x300
	s_lshl_b64 s[2:3], s[34:35], 11
	v_lshl_or_b32 v2, v53, 10, v2
	s_add_u32 s28, s84, s2
	s_waitcnt lgkmcnt(0)
	v_ashrrev_i32_e32 v3, 31, v2
	s_addc_u32 s29, s85, s3
	s_lshl_b32 s2, s49, 6
	s_waitcnt vmcnt(3)
	v_lshlrev_b64 v[34:35], 1, v[2:3]
	s_sub_i32 s2, s2, s57
	v_lshl_add_u64 v[36:37], s[28:29], 0, v[34:35]
	s_and_b32 s2, s2, 0xffffff00
	s_waitcnt vmcnt(2)
	v_add_co_u32_e32 v38, vcc, s33, v36
	s_ashr_i32 s3, s2, 31
	s_nop 0
	v_addc_co_u32_e32 v39, vcc, 0, v37, vcc
	s_lshl_b64 s[54:55], s[2:3], 11
	v_add_co_u32_e32 v40, vcc, s36, v36
	s_add_u32 s54, s30, s54
	s_nop 0
	v_addc_co_u32_e32 v41, vcc, 0, v37, vcc
	s_addc_u32 s55, s31, s55
	s_waitcnt vmcnt(1)
	v_add_co_u32_e32 v42, vcc, s37, v36
	v_lshl_add_u64 v[44:45], s[54:55], 0, v[34:35]
	s_nop 0
	v_addc_co_u32_e32 v43, vcc, 0, v37, vcc
	s_waitcnt vmcnt(0)
	s_mov_b64 s[88:89], s[28:29]
	s_mov_b64 s[90:91], s[54:55]
	v_lshrrev_b32_e32 v142, 3, v166
	v_lshlrev_b32_e32 v143, 4, v166
	v_xor_b32_e32 v143, v143, v166
	v_and_b32_e32 v143, 0x70, v143
	v_lshl_or_b32 v255, v142, 11, v143
	v_lshrrev_b32_e32 v144, 6, v166
	s_nop 0
	v_readfirstlane_b32 s94, v144
	v_and_b32_e32 v142, 15, v166
	v_bfe_u32 v143, v166, 4, 2
	v_lshrrev_b32_e32 v144, 1, v142
	v_xor_b32_e32 v183, v143, v144
	v_or_b32_e32 v143, 4, v143
	v_xor_b32_e32 v226, v143, v144
	v_lshlrev_b32_e32 v142, 7, v142
	v_lshl_or_b32 v183, v183, 4, v142
	v_lshl_or_b32 v226, v226, 4, v142
	v_lshrrev_b32_e32 v142, 7, v166
	v_bfe_u32 v143, v166, 6, 1
	v_mul_u32_u24_e32 v143, 0x4000, v143
	v_add_u32_e32 v227, v143, v183
	v_add_u32_e32 v254, v143, v226
	v_mul_u32_u24_e32 v142, 0x2000, v142
	v_add_u32_e32 v183, v142, v183
	v_add_u32_e32 v226, v142, v226
	s_lshl_b32 s94, s94, 10
	s_mov_b32 m0, s94
	s_nop 0
	global_load_lds_dwordx4 v255, s[88:89]
	s_add_u32 m0, m0, 0x2000
	s_add_u32 s92, s88, 0x20000
	s_addc_u32 s93, s89, 0
	global_load_lds_dwordx4 v255, s[92:93]
	s_add_u32 m0, m0, 0x2000
	s_add_u32 s92, s88, 0x40000
	s_addc_u32 s93, s89, 0
	global_load_lds_dwordx4 v255, s[92:93]
	s_add_u32 m0, m0, 0x2000
	s_add_u32 s92, s88, 0x60000
	s_addc_u32 s93, s89, 0
	global_load_lds_dwordx4 v255, s[92:93]
	s_add_u32 m0, m0, 0x2000
	s_nop 0
	global_load_lds_dwordx4 v255, s[90:91]
	s_add_u32 m0, m0, 0x2000
	s_add_u32 s92, s90, 0x20000
	s_addc_u32 s93, s91, 0
	global_load_lds_dwordx4 v255, s[92:93]
	s_add_u32 m0, m0, 0x2000
	s_add_u32 s92, s90, 0x40000
	s_addc_u32 s93, s91, 0
	global_load_lds_dwordx4 v255, s[92:93]
	s_add_u32 m0, m0, 0x2000
	s_add_u32 s92, s90, 0x60000
	s_addc_u32 s93, s91, 0
	global_load_lds_dwordx4 v255, s[92:93]
	s_add_u32 s88, s88, 0x80
	s_addc_u32 s89, s89, 0
	s_add_u32 s90, s90, 0x80
	s_addc_u32 s91, s91, 0
	v_add_co_u32_e32 v46, vcc, s33, v44
	v_addc_co_u32_e32 v47, vcc, 0, v45, vcc
	v_add_co_u32_e32 v48, vcc, s36, v44
	v_addc_co_u32_e32 v49, vcc, 0, v45, vcc
	v_add_co_u32_e32 v50, vcc, s37, v44
	v_addc_co_u32_e32 v51, vcc, 0, v45, vcc
	s_sub_i32 s28, s50, s57
	s_and_b32 s28, s28, 0xffffff00
	s_ashr_i32 s29, s28, 31
	s_lshl_b64 s[28:29], s[28:29], 11
	s_add_u32 s28, s23, s28
	s_addc_u32 s29, s21, s29
	v_lshl_add_u64 v[168:169], s[28:29], 0, v[34:35]
	s_or_b32 s28, s57, s56
	s_ashr_i32 s29, s28, 31
	v_lshlrev_b32_e32 v58, 4, v52
	s_lshl_b64 s[28:29], s[28:29], 11
	v_and_b32_e32 v54, 15, v52
	v_bfe_u32 v55, v52, 1, 3
	v_lshrrev_b32_e32 v56, 4, v52
	v_bfe_u32 v57, v52, 4, 2
	v_lshlrev_b32_e32 v59, 6, v52
	v_lshlrev_b32_e32 v60, 8, v52
	v_xor_b32_e32 v52, v58, v52
	v_lshlrev_b32_e32 v53, 7, v53
	s_add_u32 s28, s84, s28
	v_lshlrev_b32_e32 v54, 7, v54
	v_bitop3_b32 v56, v56, v55, 3 bitop3:0x6c
	v_bitop3_b32 v55, v57, v55, 4 bitop3:0x36
	v_and_or_b32 v182, v52, s12, v53
	s_addc_u32 s29, s85, s29
	v_mov_b32_e32 v158, 0
	s_mov_b32 s3, 0
	v_and_b32_e32 v179, 0xffffe000, v59
	v_and_b32_e32 v181, 0x4000, v60
	v_lshl_or_b32 v180, v56, 4, v54
	v_lshl_or_b32 v178, v55, 4, v54
	v_lshl_add_u64 v[170:171], s[28:29], 0, v[34:35]
	s_mov_b64 s[28:29], 0
	v_mov_b32_e32 v159, v158
	v_mov_b32_e32 v160, v158
	v_mov_b32_e32 v161, v158
	v_mov_b32_e32 v62, v158
	v_mov_b32_e32 v63, v158
	v_mov_b32_e32 v64, v158
	v_mov_b32_e32 v65, v158
	v_mov_b32_e32 v74, v158
	v_mov_b32_e32 v75, v158
	v_mov_b32_e32 v76, v158
	v_mov_b32_e32 v77, v158
	v_mov_b32_e32 v82, v158
	v_mov_b32_e32 v83, v158
	v_mov_b32_e32 v84, v158
	v_mov_b32_e32 v85, v158
	v_mov_b32_e32 v66, v158
	v_mov_b32_e32 v67, v158
	v_mov_b32_e32 v68, v158
	v_mov_b32_e32 v69, v158
	v_mov_b32_e32 v38, v158
	v_mov_b32_e32 v39, v158
	v_mov_b32_e32 v40, v158
	v_mov_b32_e32 v41, v158
	v_mov_b32_e32 v26, v158
	v_mov_b32_e32 v27, v158
	v_mov_b32_e32 v28, v158
	v_mov_b32_e32 v29, v158
	v_mov_b32_e32 v10, v158
	v_mov_b32_e32 v11, v158
	v_mov_b32_e32 v12, v158
	v_mov_b32_e32 v13, v158
	v_mov_b32_e32 v30, v158
	v_mov_b32_e32 v31, v158
	v_mov_b32_e32 v32, v158
	v_mov_b32_e32 v33, v158
	v_mov_b32_e32 v2, v158
	v_mov_b32_e32 v3, v158
	v_mov_b32_e32 v4, v158
	v_mov_b32_e32 v5, v158
	v_mov_b32_e32 v6, v158
	v_mov_b32_e32 v7, v158
	v_mov_b32_e32 v8, v158
	v_mov_b32_e32 v9, v158
	v_mov_b32_e32 v14, v158
	v_mov_b32_e32 v15, v158
	v_mov_b32_e32 v16, v158
	v_mov_b32_e32 v17, v158
	v_mov_b32_e32 v18, v158
	v_mov_b32_e32 v19, v158
	v_mov_b32_e32 v20, v158
	v_mov_b32_e32 v21, v158
	v_mov_b32_e32 v22, v158
	v_mov_b32_e32 v23, v158
	v_mov_b32_e32 v24, v158
	v_mov_b32_e32 v25, v158
; DI f32x4 mfma16(bf16x8 a, bf16x8 b, f32x4 c) { return __builtin_amdgcn_mfma_f32_16x16x32_bf16(a, b, c, 0, 0, 0); }
; template <int MI, int NI>
; DI void gemm_kloop(const u16* Au, int lda, const u16* Bu, int ldb, int K, f32x4 (&acc)[NI][MI], unsigned char* smem) {
;     ...
;   for (int kt = 0; kt < nk; ++kt) {
;     __syncthreads();
;     if (kt + 1 < nk) {
;       SWRITE((kt + 1) & 1);
;       if (kt + 2 < nk) GLOAD((kt + 2) << 6);
;     }
;     {
;       const unsigned char* sa = smem + (kt & 1) * 65536;
;       const unsigned char* sb = sa + 32768;
; #pragma unroll
;       for (int ks = 0; ks < 2; ++ks) {
;         const int fo = ks ? fro1 : fro0;
;         bf16x8 af[MI];
; #pragma unroll
;         for (int i = 0; i < MI; ++i) af[i] = *(const bf16x8*)(sa + (wm * 16 * MI + i * 16) * 128 + fo);
; #pragma unroll
;         for (int nh = 0; nh < NI; nh += 4) {
;           bf16x8 wf[4];
; #pragma unroll
;           for (int i = 0; i < 4; ++i) wf[i] = *(const bf16x8*)(sb + (wn * 16 * NI + (nh + i) * 16) * 128 + fo);
; #pragma unroll
;           for (int ni = 0; ni < 4; ++ni)
; #pragma unroll
;             for (int mi = 0; mi < MI; ++mi) acc[nh + ni][mi] = mfma16(wf[ni], af[mi], acc[nh + ni][mi]);
;         }
; template <int MI, int NI>
; DI void zero_acc(f32x4 (&acc)[NI][MI]) {
; #pragma unroll
;   for (int i = 0; i < NI; ++i)
; #pragma unroll
;     for (int j = 0; j < MI; ++j) acc[i][j] = f32x4{0.f, 0.f, 0.f, 0.f};
; }
	v_mov_b32_e32 v34, v158
	v_mov_b32_e32 v35, v158
	v_mov_b32_e32 v36, v158
	v_mov_b32_e32 v37, v158
	v_mov_b32_e32 v42, v158
	v_mov_b32_e32 v43, v158
	v_mov_b32_e32 v44, v158
	v_mov_b32_e32 v45, v158
	v_mov_b32_e32 v46, v158
	v_mov_b32_e32 v47, v158
	v_mov_b32_e32 v48, v158
	v_mov_b32_e32 v49, v158
	v_mov_b32_e32 v50, v158
	v_mov_b32_e32 v51, v158
	v_mov_b32_e32 v52, v158
	v_mov_b32_e32 v53, v158
	v_mov_b32_e32 v54, v158
	v_mov_b32_e32 v55, v158
	v_mov_b32_e32 v56, v158
	v_mov_b32_e32 v57, v158
	v_mov_b32_e32 v58, v158
	v_mov_b32_e32 v59, v158
	v_mov_b32_e32 v60, v158
	v_mov_b32_e32 v61, v158
	v_mov_b32_e32 v70, v158
	v_mov_b32_e32 v71, v158
	v_mov_b32_e32 v72, v158
	v_mov_b32_e32 v73, v158
	v_mov_b32_e32 v78, v158
	v_mov_b32_e32 v79, v158
	v_mov_b32_e32 v80, v158
	v_mov_b32_e32 v81, v158
	v_mov_b32_e32 v86, v158
	v_mov_b32_e32 v87, v158
	v_mov_b32_e32 v88, v158
	v_mov_b32_e32 v89, v158
	v_mov_b32_e32 v90, v158
	v_mov_b32_e32 v91, v158
	v_mov_b32_e32 v92, v158
	v_mov_b32_e32 v93, v158
	v_mov_b32_e32 v94, v158
	v_mov_b32_e32 v95, v158
	v_mov_b32_e32 v96, v158
	v_mov_b32_e32 v97, v158
	v_mov_b32_e32 v98, v158
	v_mov_b32_e32 v99, v158
	v_mov_b32_e32 v100, v158
	v_mov_b32_e32 v101, v158
	v_mov_b32_e32 v102, v158
	v_mov_b32_e32 v103, v158
	v_mov_b32_e32 v104, v158
	v_mov_b32_e32 v105, v158
	v_mov_b32_e32 v106, v158
	v_mov_b32_e32 v107, v158
	v_mov_b32_e32 v108, v158
	v_mov_b32_e32 v109, v158
	v_mov_b32_e32 v110, v158
	v_mov_b32_e32 v111, v158
	v_mov_b32_e32 v112, v158
	v_mov_b32_e32 v113, v158
	v_mov_b32_e32 v114, v158
	v_mov_b32_e32 v115, v158
	v_mov_b32_e32 v116, v158
	v_mov_b32_e32 v117, v158
	v_mov_b32_e32 v118, v158
	v_mov_b32_e32 v119, v158
	v_mov_b32_e32 v120, v158
	v_mov_b32_e32 v121, v158
	v_mov_b32_e32 v134, v158
	v_mov_b32_e32 v135, v158
	v_mov_b32_e32 v136, v158
	v_mov_b32_e32 v137, v158
	s_mov_b32 s95, 0
.Lk_outproj:
	s_waitcnt vmcnt(0) lgkmcnt(0)
	s_barrier
	ds_read_b128 v[122:125], v183
	ds_read_b128 v[126:129], v183 offset:2048
	ds_read_b128 v[130:133], v183 offset:4096
	ds_read_b128 v[138:141], v183 offset:6144
	ds_read_b128 v[162:165], v227 offset:32768
	ds_read_b128 v[184:187], v227 offset:34816
	ds_read_b128 v[188:191], v227 offset:36864
	s_and_b32 s92, s95, 1
	s_xor_b32 s92, s92, 1
	s_lshl_b32 s92, s92, 16
	s_waitcnt lgkmcnt(2)
	v_mfma_f32_16x16x32_bf16 v[134:137], v[162:165], v[122:125], v[134:137]
	ds_read_b128 v[192:195], v227 offset:38912
	v_mfma_f32_16x16x32_bf16 v[118:121], v[162:165], v[126:129], v[118:121]
	v_mfma_f32_16x16x32_bf16 v[114:117], v[162:165], v[130:133], v[114:117]
	s_add_u32 m0, s92, s94
	s_nop 0
	global_load_lds_dwordx4 v255, s[88:89]
	v_mfma_f32_16x16x32_bf16 v[110:113], v[162:165], v[138:141], v[110:113]
	s_waitcnt lgkmcnt(2)
	v_mfma_f32_16x16x32_bf16 v[106:109], v[184:187], v[122:125], v[106:109]
	ds_read_b128 v[162:165], v227 offset:40960
	v_mfma_f32_16x16x32_bf16 v[102:105], v[184:187], v[126:129], v[102:105]
	ds_read_b128 v[142:145], v226
	v_mfma_f32_16x16x32_bf16 v[98:101], v[184:187], v[130:133], v[98:101]
	s_add_u32 m0, m0, 0x2000
	s_add_u32 s92, s88, 0x20000
	s_addc_u32 s93, s89, 0
	global_load_lds_dwordx4 v255, s[92:93]
	v_mfma_f32_16x16x32_bf16 v[94:97], v[184:187], v[138:141], v[94:97]
	s_waitcnt lgkmcnt(3)
	v_mfma_f32_16x16x32_bf16 v[90:93], v[188:191], v[122:125], v[90:93]
	ds_read_b128 v[184:187], v227 offset:43008
	v_mfma_f32_16x16x32_bf16 v[86:89], v[188:191], v[126:129], v[86:89]
	ds_read_b128 v[146:149], v226 offset:2048
	v_mfma_f32_16x16x32_bf16 v[78:81], v[188:191], v[130:133], v[78:81]
	s_add_u32 m0, m0, 0x2000
	s_add_u32 s92, s88, 0x40000
	s_addc_u32 s93, s89, 0
	global_load_lds_dwordx4 v255, s[92:93]
	v_mfma_f32_16x16x32_bf16 v[70:73], v[188:191], v[138:141], v[70:73]
	s_waitcnt lgkmcnt(4)
	v_mfma_f32_16x16x32_bf16 v[58:61], v[192:195], v[122:125], v[58:61]
	ds_read_b128 v[188:191], v227 offset:45056
	v_mfma_f32_16x16x32_bf16 v[54:57], v[192:195], v[126:129], v[54:57]
	ds_read_b128 v[150:153], v226 offset:4096
	v_mfma_f32_16x16x32_bf16 v[50:53], v[192:195], v[130:133], v[50:53]
	s_add_u32 m0, m0, 0x2000
	s_add_u32 s92, s88, 0x60000
	s_addc_u32 s93, s89, 0
	global_load_lds_dwordx4 v255, s[92:93]
	v_mfma_f32_16x16x32_bf16 v[46:49], v[192:195], v[138:141], v[46:49]
	s_waitcnt lgkmcnt(5)
	v_mfma_f32_16x16x32_bf16 v[42:45], v[162:165], v[122:125], v[42:45]
	ds_read_b128 v[192:195], v227 offset:47104
	v_mfma_f32_16x16x32_bf16 v[34:37], v[162:165], v[126:129], v[34:37]
	ds_read_b128 v[154:157], v226 offset:6144
	v_mfma_f32_16x16x32_bf16 v[22:25], v[162:165], v[130:133], v[22:25]
	s_add_u32 m0, m0, 0x2000
	s_nop 0
	global_load_lds_dwordx4 v255, s[90:91]
	v_mfma_f32_16x16x32_bf16 v[18:21], v[162:165], v[138:141], v[18:21]
	s_waitcnt lgkmcnt(5)
	v_mfma_f32_16x16x32_bf16 v[14:17], v[184:187], v[122:125], v[14:17]
	ds_read_b128 v[162:165], v254 offset:32768
	v_mfma_f32_16x16x32_bf16 v[6:9], v[184:187], v[126:129], v[6:9]
	v_mfma_f32_16x16x32_bf16 v[2:5], v[184:187], v[130:133], v[2:5]
	s_add_u32 m0, m0, 0x2000
	s_add_u32 s92, s90, 0x20000
	s_addc_u32 s93, s91, 0
	global_load_lds_dwordx4 v255, s[92:93]
	v_mfma_f32_16x16x32_bf16 v[30:33], v[184:187], v[138:141], v[30:33]
	s_waitcnt lgkmcnt(4)
	v_mfma_f32_16x16x32_bf16 v[10:13], v[188:191], v[122:125], v[10:13]
	ds_read_b128 v[184:187], v254 offset:34816
	v_mfma_f32_16x16x32_bf16 v[26:29], v[188:191], v[126:129], v[26:29]
	v_mfma_f32_16x16x32_bf16 v[38:41], v[188:191], v[130:133], v[38:41]
	s_add_u32 m0, m0, 0x2000
	s_add_u32 s92, s90, 0x40000
	s_addc_u32 s93, s91, 0
	global_load_lds_dwordx4 v255, s[92:93]
	v_mfma_f32_16x16x32_bf16 v[66:69], v[188:191], v[138:141], v[66:69]
	s_waitcnt lgkmcnt(3)
; DI f32x4 mfma16(bf16x8 a, bf16x8 b, f32x4 c) { return __builtin_amdgcn_mfma_f32_16x16x32_bf16(a, b, c, 0, 0, 0); }
; template <int MI, int NI>
; DI void gemm_kloop(const u16* Au, int lda, const u16* Bu, int ldb, int K, f32x4 (&acc)[NI][MI], unsigned char* smem) {
;     ...
;   for (int kt = 0; kt < nk; ++kt) {
;     __syncthreads();
;     if (kt + 1 < nk) {
;       SWRITE((kt + 1) & 1);
;       if (kt + 2 < nk) GLOAD((kt + 2) << 6);
;     }
;     {
;       const unsigned char* sa = smem + (kt & 1) * 65536;
;       const unsigned char* sb = sa + 32768;
; #pragma unroll
;       for (int ks = 0; ks < 2; ++ks) {
;         const int fo = ks ? fro1 : fro0;
;         bf16x8 af[MI];
; #pragma unroll
;         for (int i = 0; i < MI; ++i) af[i] = *(const bf16x8*)(sa + (wm * 16 * MI + i * 16) * 128 + fo);
; #pragma unroll
;         for (int nh = 0; nh < NI; nh += 4) {
;           bf16x8 wf[4];
; #pragma unroll
;           for (int i = 0; i < 4; ++i) wf[i] = *(const bf16x8*)(sb + (wn * 16 * NI + (nh + i) * 16) * 128 + fo);
; #pragma unroll
;           for (int ni = 0; ni < 4; ++ni)
; #pragma unroll
;             for (int mi = 0; mi < MI; ++mi) acc[nh + ni][mi] = mfma16(wf[ni], af[mi], acc[nh + ni][mi]);
;         }
	v_mfma_f32_16x16x32_bf16 v[82:85], v[192:195], v[122:125], v[82:85]
	ds_read_b128 v[188:191], v254 offset:36864
	v_mfma_f32_16x16x32_bf16 v[74:77], v[192:195], v[126:129], v[74:77]
	v_mfma_f32_16x16x32_bf16 v[62:65], v[192:195], v[130:133], v[62:65]
	s_add_u32 m0, m0, 0x2000
	s_add_u32 s92, s90, 0x60000
	s_addc_u32 s93, s91, 0
	global_load_lds_dwordx4 v255, s[92:93]
	v_mfma_f32_16x16x32_bf16 v[158:161], v[192:195], v[138:141], v[158:161]
	s_waitcnt lgkmcnt(2)
	v_mfma_f32_16x16x32_bf16 v[134:137], v[162:165], v[142:145], v[134:137]
	ds_read_b128 v[192:195], v254 offset:38912
	v_mfma_f32_16x16x32_bf16 v[118:121], v[162:165], v[146:149], v[118:121]
	v_mfma_f32_16x16x32_bf16 v[114:117], v[162:165], v[150:153], v[114:117]
	v_mfma_f32_16x16x32_bf16 v[110:113], v[162:165], v[154:157], v[110:113]
	s_waitcnt lgkmcnt(2)
	v_mfma_f32_16x16x32_bf16 v[106:109], v[184:187], v[142:145], v[106:109]
	ds_read_b128 v[162:165], v254 offset:40960
	v_mfma_f32_16x16x32_bf16 v[102:105], v[184:187], v[146:149], v[102:105]
	v_mfma_f32_16x16x32_bf16 v[98:101], v[184:187], v[150:153], v[98:101]
	v_mfma_f32_16x16x32_bf16 v[94:97], v[184:187], v[154:157], v[94:97]
	s_waitcnt lgkmcnt(2)
	v_mfma_f32_16x16x32_bf16 v[90:93], v[188:191], v[142:145], v[90:93]
	ds_read_b128 v[184:187], v254 offset:43008
	v_mfma_f32_16x16x32_bf16 v[86:89], v[188:191], v[146:149], v[86:89]
	v_mfma_f32_16x16x32_bf16 v[78:81], v[188:191], v[150:153], v[78:81]
	v_mfma_f32_16x16x32_bf16 v[70:73], v[188:191], v[154:157], v[70:73]
	s_waitcnt lgkmcnt(2)
	v_mfma_f32_16x16x32_bf16 v[58:61], v[192:195], v[142:145], v[58:61]
	ds_read_b128 v[188:191], v254 offset:45056
	v_mfma_f32_16x16x32_bf16 v[54:57], v[192:195], v[146:149], v[54:57]
	v_mfma_f32_16x16x32_bf16 v[50:53], v[192:195], v[150:153], v[50:53]
	v_mfma_f32_16x16x32_bf16 v[46:49], v[192:195], v[154:157], v[46:49]
	s_waitcnt lgkmcnt(2)
	v_mfma_f32_16x16x32_bf16 v[42:45], v[162:165], v[142:145], v[42:45]
	ds_read_b128 v[192:195], v254 offset:47104
	v_mfma_f32_16x16x32_bf16 v[34:37], v[162:165], v[146:149], v[34:37]
	v_mfma_f32_16x16x32_bf16 v[22:25], v[162:165], v[150:153], v[22:25]
	v_mfma_f32_16x16x32_bf16 v[18:21], v[162:165], v[154:157], v[18:21]
	s_waitcnt lgkmcnt(2)
	v_mfma_f32_16x16x32_bf16 v[14:17], v[184:187], v[142:145], v[14:17]
	v_mfma_f32_16x16x32_bf16 v[6:9], v[184:187], v[146:149], v[6:9]
	v_mfma_f32_16x16x32_bf16 v[2:5], v[184:187], v[150:153], v[2:5]
	v_mfma_f32_16x16x32_bf16 v[30:33], v[184:187], v[154:157], v[30:33]
	s_waitcnt lgkmcnt(1)
	v_mfma_f32_16x16x32_bf16 v[10:13], v[188:191], v[142:145], v[10:13]
	v_mfma_f32_16x16x32_bf16 v[26:29], v[188:191], v[146:149], v[26:29]
	v_mfma_f32_16x16x32_bf16 v[38:41], v[188:191], v[150:153], v[38:41]
	v_mfma_f32_16x16x32_bf16 v[66:69], v[188:191], v[154:157], v[66:69]
	s_waitcnt lgkmcnt(0)
	v_mfma_f32_16x16x32_bf16 v[82:85], v[192:195], v[142:145], v[82:85]
	v_mfma_f32_16x16x32_bf16 v[74:77], v[192:195], v[146:149], v[74:77]
	v_mfma_f32_16x16x32_bf16 v[62:65], v[192:195], v[150:153], v[62:65]
	v_mfma_f32_16x16x32_bf16 v[158:161], v[192:195], v[154:157], v[158:161]
	v_xor_b32_e32 v183, 0x10000, v183
	v_xor_b32_e32 v226, 0x10000, v226
	v_xor_b32_e32 v227, 0x10000, v227
	v_xor_b32_e32 v254, 0x10000, v254
	s_add_u32 s88, s88, 0x80
	s_addc_u32 s89, s89, 0
	s_add_u32 s90, s90, 0x80
	s_addc_u32 s91, s91, 0
	s_add_u32 s95, s95, 1
	s_cmp_lg_u32 s95, 14
	s_cbranch_scc1 .Lk_outproj
	s_waitcnt vmcnt(0)
	s_barrier
	s_add_u32 m0, s94, 0x10000
	s_nop 0
	global_load_lds_dwordx4 v255, s[88:89]
	s_add_u32 m0, m0, 0x2000
	s_add_u32 s92, s88, 0x20000
	s_addc_u32 s93, s89, 0
	global_load_lds_dwordx4 v255, s[92:93]
	s_add_u32 m0, m0, 0x2000
	s_add_u32 s92, s88, 0x40000
	s_addc_u32 s93, s89, 0
	global_load_lds_dwordx4 v255, s[92:93]
	s_add_u32 m0, m0, 0x2000
	s_add_u32 s92, s88, 0x60000
	s_addc_u32 s93, s89, 0
	global_load_lds_dwordx4 v255, s[92:93]
	s_add_u32 m0, m0, 0x2000
	s_nop 0
	global_load_lds_dwordx4 v255, s[90:91]
	s_add_u32 m0, m0, 0x2000
	s_add_u32 s92, s90, 0x20000
	s_addc_u32 s93, s91, 0
	global_load_lds_dwordx4 v255, s[92:93]
	s_add_u32 m0, m0, 0x2000
	s_add_u32 s92, s90, 0x40000
	s_addc_u32 s93, s91, 0
	global_load_lds_dwordx4 v255, s[92:93]
	s_add_u32 m0, m0, 0x2000
	s_add_u32 s92, s90, 0x60000
	s_addc_u32 s93, s91, 0
	global_load_lds_dwordx4 v255, s[92:93]
	v_add_u32_e32 v150, v181, v180
	ds_read_b128 v[122:125], v150 offset:32768
	v_add_u32_e32 v146, v179, v180
	ds_read_b128 v[126:129], v146
	ds_read_b128 v[130:133], v146 offset:2048
	ds_read_b128 v[138:141], v150 offset:34816
	ds_read_b128 v[142:145], v146 offset:4096
	ds_read_b128 v[146:149], v146 offset:6144
	s_waitcnt lgkmcnt(4)
	v_mfma_f32_16x16x32_bf16 v[134:137], v[122:125], v[126:129], v[134:137]
	v_add_u32_e32 v154, v181, v178
	v_or_b32_e32 v225, 0x18000, v181
	v_add_u32_e32 v192, v225, v180
	s_waitcnt lgkmcnt(3)
	v_mfma_f32_16x16x32_bf16 v[118:121], v[122:125], v[130:133], v[118:121]
	v_add_u32_e32 v225, v225, v178
	s_waitcnt lgkmcnt(1)
	v_mfma_f32_16x16x32_bf16 v[114:117], v[122:125], v[142:145], v[114:117]
	s_waitcnt lgkmcnt(0)
	v_mfma_f32_16x16x32_bf16 v[110:113], v[122:125], v[146:149], v[110:113]
	v_mfma_f32_16x16x32_bf16 v[106:109], v[138:141], v[126:129], v[106:109]
	v_mfma_f32_16x16x32_bf16 v[102:105], v[138:141], v[130:133], v[102:105]
	v_mfma_f32_16x16x32_bf16 v[98:101], v[138:141], v[142:145], v[98:101]
	v_mfma_f32_16x16x32_bf16 v[94:97], v[138:141], v[146:149], v[94:97]
	ds_read_b128 v[122:125], v150 offset:36864
	ds_read_b128 v[138:141], v150 offset:38912
	s_waitcnt lgkmcnt(1)
; DI f32x4 mfma16(bf16x8 a, bf16x8 b, f32x4 c) { return __builtin_amdgcn_mfma_f32_16x16x32_bf16(a, b, c, 0, 0, 0); }
; template <int MI, int NI>
; DI void gemm_kloop(const u16* Au, int lda, const u16* Bu, int ldb, int K, f32x4 (&acc)[NI][MI], unsigned char* smem) {
;     ...
;     {
;       const unsigned char* sa = smem + (kt & 1) * 65536;
;       const unsigned char* sb = sa + 32768;
; #pragma unroll
;       for (int ks = 0; ks < 2; ++ks) {
;         const int fo = ks ? fro1 : fro0;
;         bf16x8 af[MI];
; #pragma unroll
;         for (int i = 0; i < MI; ++i) af[i] = *(const bf16x8*)(sa + (wm * 16 * MI + i * 16) * 128 + fo);
; #pragma unroll
;         for (int nh = 0; nh < NI; nh += 4) {
;           bf16x8 wf[4];
; #pragma unroll
;           for (int i = 0; i < 4; ++i) wf[i] = *(const bf16x8*)(sb + (wn * 16 * NI + (nh + i) * 16) * 128 + fo);
; #pragma unroll
;           for (int ni = 0; ni < 4; ++ni)
; #pragma unroll
;             for (int mi = 0; mi < MI; ++mi) acc[nh + ni][mi] = mfma16(wf[ni], af[mi], acc[nh + ni][mi]);
;         }
	v_mfma_f32_16x16x32_bf16 v[90:93], v[122:125], v[126:129], v[90:93]
	v_mfma_f32_16x16x32_bf16 v[86:89], v[122:125], v[130:133], v[86:89]
	v_mfma_f32_16x16x32_bf16 v[78:81], v[122:125], v[142:145], v[78:81]
	v_mfma_f32_16x16x32_bf16 v[70:73], v[122:125], v[146:149], v[70:73]
	s_waitcnt lgkmcnt(0)
	v_mfma_f32_16x16x32_bf16 v[58:61], v[138:141], v[126:129], v[58:61]
	v_mfma_f32_16x16x32_bf16 v[54:57], v[138:141], v[130:133], v[54:57]
	v_mfma_f32_16x16x32_bf16 v[50:53], v[138:141], v[142:145], v[50:53]
	v_mfma_f32_16x16x32_bf16 v[46:49], v[138:141], v[146:149], v[46:49]
	ds_read_b128 v[122:125], v150 offset:40960
	ds_read_b128 v[138:141], v150 offset:43008
	s_waitcnt lgkmcnt(1)
	v_mfma_f32_16x16x32_bf16 v[42:45], v[122:125], v[126:129], v[42:45]
	v_mfma_f32_16x16x32_bf16 v[34:37], v[122:125], v[130:133], v[34:37]
	v_mfma_f32_16x16x32_bf16 v[22:25], v[122:125], v[142:145], v[22:25]
	v_mfma_f32_16x16x32_bf16 v[18:21], v[122:125], v[146:149], v[18:21]
	s_waitcnt lgkmcnt(0)
	v_mfma_f32_16x16x32_bf16 v[14:17], v[138:141], v[126:129], v[14:17]
	v_mfma_f32_16x16x32_bf16 v[6:9], v[138:141], v[130:133], v[6:9]
	v_mfma_f32_16x16x32_bf16 v[2:5], v[138:141], v[142:145], v[2:5]
	v_mfma_f32_16x16x32_bf16 v[30:33], v[138:141], v[146:149], v[30:33]
	ds_read_b128 v[122:125], v150 offset:45056
	ds_read_b128 v[138:141], v150 offset:47104
	v_add_u32_e32 v150, v179, v178
	v_add_u32_e32 v179, 0x10000, v179
	s_waitcnt lgkmcnt(1)
	v_mfma_f32_16x16x32_bf16 v[10:13], v[122:125], v[126:129], v[10:13]
	v_mfma_f32_16x16x32_bf16 v[26:29], v[122:125], v[130:133], v[26:29]
	v_mfma_f32_16x16x32_bf16 v[38:41], v[122:125], v[142:145], v[38:41]
	v_mfma_f32_16x16x32_bf16 v[66:69], v[122:125], v[146:149], v[66:69]
	ds_read_b128 v[122:125], v154 offset:32768
	s_waitcnt lgkmcnt(1)
	v_mfma_f32_16x16x32_bf16 v[82:85], v[138:141], v[126:129], v[82:85]
	v_mfma_f32_16x16x32_bf16 v[74:77], v[138:141], v[130:133], v[74:77]
	v_mfma_f32_16x16x32_bf16 v[62:65], v[138:141], v[142:145], v[62:65]
	v_mfma_f32_16x16x32_bf16 v[126:129], v[138:141], v[146:149], v[158:161]
	ds_read_b128 v[130:133], v150
	ds_read_b128 v[138:141], v150 offset:2048
	ds_read_b128 v[142:145], v154 offset:34816
	ds_read_b128 v[146:149], v150 offset:4096
	ds_read_b128 v[150:153], v150 offset:6144
	s_waitcnt lgkmcnt(4)
	v_mfma_f32_16x16x32_bf16 v[134:137], v[122:125], v[130:133], v[134:137]
	s_waitcnt lgkmcnt(3)
	v_mfma_f32_16x16x32_bf16 v[118:121], v[122:125], v[138:141], v[118:121]
	s_waitcnt lgkmcnt(1)
	v_mfma_f32_16x16x32_bf16 v[114:117], v[122:125], v[146:149], v[114:117]
	s_waitcnt lgkmcnt(0)
	v_mfma_f32_16x16x32_bf16 v[110:113], v[122:125], v[150:153], v[110:113]
	v_mfma_f32_16x16x32_bf16 v[106:109], v[142:145], v[130:133], v[106:109]
	v_mfma_f32_16x16x32_bf16 v[102:105], v[142:145], v[138:141], v[102:105]
	v_mfma_f32_16x16x32_bf16 v[98:101], v[142:145], v[146:149], v[98:101]
	v_mfma_f32_16x16x32_bf16 v[94:97], v[142:145], v[150:153], v[94:97]
	ds_read_b128 v[122:125], v154 offset:36864
	ds_read_b128 v[142:145], v154 offset:38912
	s_waitcnt lgkmcnt(1)
	v_mfma_f32_16x16x32_bf16 v[90:93], v[122:125], v[130:133], v[90:93]
	v_mfma_f32_16x16x32_bf16 v[86:89], v[122:125], v[138:141], v[86:89]
	v_mfma_f32_16x16x32_bf16 v[78:81], v[122:125], v[146:149], v[78:81]
	v_mfma_f32_16x16x32_bf16 v[70:73], v[122:125], v[150:153], v[70:73]
	s_waitcnt lgkmcnt(0)
	v_mfma_f32_16x16x32_bf16 v[58:61], v[142:145], v[130:133], v[58:61]
	v_mfma_f32_16x16x32_bf16 v[54:57], v[142:145], v[138:141], v[54:57]
	v_mfma_f32_16x16x32_bf16 v[50:53], v[142:145], v[146:149], v[50:53]
	v_mfma_f32_16x16x32_bf16 v[46:49], v[142:145], v[150:153], v[46:49]
	ds_read_b128 v[122:125], v154 offset:40960
	ds_read_b128 v[142:145], v154 offset:43008
	s_waitcnt lgkmcnt(1)
	v_mfma_f32_16x16x32_bf16 v[42:45], v[122:125], v[130:133], v[42:45]
	v_mfma_f32_16x16x32_bf16 v[34:37], v[122:125], v[138:141], v[34:37]
	v_mfma_f32_16x16x32_bf16 v[22:25], v[122:125], v[146:149], v[22:25]
	v_mfma_f32_16x16x32_bf16 v[18:21], v[122:125], v[150:153], v[18:21]
	s_waitcnt lgkmcnt(0)
	v_mfma_f32_16x16x32_bf16 v[14:17], v[142:145], v[130:133], v[14:17]
	v_mfma_f32_16x16x32_bf16 v[6:9], v[142:145], v[138:141], v[6:9]
	v_mfma_f32_16x16x32_bf16 v[2:5], v[142:145], v[146:149], v[2:5]
	v_mfma_f32_16x16x32_bf16 v[30:33], v[142:145], v[150:153], v[30:33]
	ds_read_b128 v[122:125], v154 offset:45056
	ds_read_b128 v[142:145], v154 offset:47104
	s_waitcnt vmcnt(0) lgkmcnt(0)
	s_barrier
; DI f32x4 mfma16(bf16x8 a, bf16x8 b, f32x4 c) { return __builtin_amdgcn_mfma_f32_16x16x32_bf16(a, b, c, 0, 0, 0); }
; template <int MI, int NI>
; DI void gemm_kloop(const u16* Au, int lda, const u16* Bu, int ldb, int K, f32x4 (&acc)[NI][MI], unsigned char* smem) {
;     ...
;     {
;       const unsigned char* sa = smem + (kt & 1) * 65536;
;       const unsigned char* sb = sa + 32768;
; #pragma unroll
;       for (int ks = 0; ks < 2; ++ks) {
;         const int fo = ks ? fro1 : fro0;
;         bf16x8 af[MI];
; #pragma unroll
;         for (int i = 0; i < MI; ++i) af[i] = *(const bf16x8*)(sa + (wm * 16 * MI + i * 16) * 128 + fo);
; #pragma unroll
;         for (int nh = 0; nh < NI; nh += 4) {
;           bf16x8 wf[4];
; #pragma unroll
;           for (int i = 0; i < 4; ++i) wf[i] = *(const bf16x8*)(sb + (wn * 16 * NI + (nh + i) * 16) * 128 + fo);
; #pragma unroll
;           for (int ni = 0; ni < 4; ++ni)
; #pragma unroll
;             for (int mi = 0; mi < MI; ++mi) acc[nh + ni][mi] = mfma16(wf[ni], af[mi], acc[nh + ni][mi]);
;         }
;       }
;     }
;   }
;   __syncthreads();
	v_mfma_f32_16x16x32_bf16 v[10:13], v[122:125], v[130:133], v[10:13]
	v_mfma_f32_16x16x32_bf16 v[26:29], v[122:125], v[138:141], v[26:29]
	v_mfma_f32_16x16x32_bf16 v[38:41], v[122:125], v[146:149], v[38:41]
	v_mfma_f32_16x16x32_bf16 v[66:69], v[122:125], v[150:153], v[66:69]
	ds_read_b128 v[122:125], v192
	v_mfma_f32_16x16x32_bf16 v[126:129], v[142:145], v[150:153], v[126:129]
	v_add_u32_e32 v150, v179, v180
	v_mfma_f32_16x16x32_bf16 v[82:85], v[142:145], v[130:133], v[82:85]
	v_mfma_f32_16x16x32_bf16 v[74:77], v[142:145], v[138:141], v[74:77]
	v_mfma_f32_16x16x32_bf16 v[62:65], v[142:145], v[146:149], v[62:65]
	ds_read_b128 v[130:133], v150
	ds_read_b128 v[138:141], v150 offset:2048
	ds_read_b128 v[142:145], v192 offset:2048
	ds_read_b128 v[146:149], v150 offset:4096
	ds_read_b128 v[150:153], v150 offset:6144
	s_waitcnt lgkmcnt(4)
	v_mfma_f32_16x16x32_bf16 v[134:137], v[122:125], v[130:133], v[134:137]
	s_waitcnt lgkmcnt(3)
	v_mfma_f32_16x16x32_bf16 v[118:121], v[122:125], v[138:141], v[118:121]
	s_waitcnt lgkmcnt(1)
	v_mfma_f32_16x16x32_bf16 v[114:117], v[122:125], v[146:149], v[114:117]
	s_waitcnt lgkmcnt(0)
	v_mfma_f32_16x16x32_bf16 v[110:113], v[122:125], v[150:153], v[110:113]
	v_mfma_f32_16x16x32_bf16 v[106:109], v[142:145], v[130:133], v[106:109]
	v_mfma_f32_16x16x32_bf16 v[102:105], v[142:145], v[138:141], v[102:105]
	v_mfma_f32_16x16x32_bf16 v[98:101], v[142:145], v[146:149], v[98:101]
	v_mfma_f32_16x16x32_bf16 v[142:145], v[142:145], v[150:153], v[94:97]
	s_nop 2
	ds_read_b128 v[94:97], v192 offset:4096
	ds_read_b128 v[122:125], v192 offset:6144
	s_waitcnt lgkmcnt(0)
	v_mfma_f32_16x16x32_bf16 v[158:161], v[122:125], v[130:133], v[58:61]
	v_mfma_f32_16x16x32_bf16 v[162:165], v[122:125], v[138:141], v[54:57]
	s_nop 2
	ds_read_b128 v[54:57], v192 offset:8192
	ds_read_b128 v[58:61], v192 offset:10240
	s_waitcnt lgkmcnt(1)
	v_mfma_f32_16x16x32_bf16 v[180:183], v[54:57], v[150:153], v[18:21]
	s_waitcnt lgkmcnt(0)
	v_mfma_f32_16x16x32_bf16 v[184:187], v[58:61], v[130:133], v[14:17]
	s_nop 2
	ds_read_b128 v[14:17], v192 offset:12288
	ds_read_b128 v[18:21], v192 offset:14336
	s_waitcnt lgkmcnt(1)
	v_mfma_f32_16x16x32_bf16 v[192:195], v[14:17], v[130:133], v[10:13]
	s_nop 2
	ds_read_b128 v[10:13], v225
	v_mfma_f32_16x16x32_bf16 v[154:157], v[94:97], v[130:133], v[90:93]
	v_mfma_f32_16x16x32_bf16 v[86:89], v[94:97], v[138:141], v[86:89]
	v_mfma_f32_16x16x32_bf16 v[78:81], v[94:97], v[146:149], v[78:81]
	v_mfma_f32_16x16x32_bf16 v[70:73], v[94:97], v[150:153], v[70:73]
	v_mfma_f32_16x16x32_bf16 v[50:53], v[122:125], v[146:149], v[50:53]
	v_mfma_f32_16x16x32_bf16 v[46:49], v[122:125], v[150:153], v[46:49]
	v_mfma_f32_16x16x32_bf16 v[42:45], v[54:57], v[130:133], v[42:45]
	v_mfma_f32_16x16x32_bf16 v[34:37], v[54:57], v[138:141], v[34:37]
	v_mfma_f32_16x16x32_bf16 v[168:171], v[54:57], v[146:149], v[22:25]
	v_mfma_f32_16x16x32_bf16 v[6:9], v[58:61], v[138:141], v[6:9]
	v_mfma_f32_16x16x32_bf16 v[2:5], v[58:61], v[146:149], v[2:5]
	v_mfma_f32_16x16x32_bf16 v[188:191], v[58:61], v[150:153], v[30:33]
	v_mfma_f32_16x16x32_bf16 v[226:229], v[14:17], v[138:141], v[26:29]
	v_mfma_f32_16x16x32_bf16 v[38:41], v[14:17], v[146:149], v[38:41]
	v_mfma_f32_16x16x32_bf16 v[66:69], v[14:17], v[150:153], v[66:69]
	s_waitcnt lgkmcnt(1)
	v_mfma_f32_16x16x32_bf16 v[130:133], v[18:21], v[130:133], v[82:85]
	v_mfma_f32_16x16x32_bf16 v[138:141], v[18:21], v[138:141], v[74:77]
	v_mfma_f32_16x16x32_bf16 v[146:149], v[18:21], v[146:149], v[62:65]
	v_mfma_f32_16x16x32_bf16 v[150:153], v[18:21], v[150:153], v[126:129]
	v_add_u32_e32 v18, v179, v178
	ds_read_b128 v[230:233], v18
	ds_read_b128 v[234:237], v18 offset:2048
	ds_read_b128 v[14:17], v225 offset:2048
	ds_read_b128 v[238:241], v18 offset:4096
	ds_read_b128 v[248:251], v18 offset:6144
	s_waitcnt lgkmcnt(4)
	v_mfma_f32_16x16x32_bf16 v[126:129], v[10:13], v[230:233], v[134:137]
	s_nop 2
	v_add_u32_e32 v136, s34, v176
	s_waitcnt lgkmcnt(3)
	v_mfma_f32_16x16x32_bf16 v[94:97], v[10:13], v[234:237], v[118:121]
	s_waitcnt lgkmcnt(1)
	v_mfma_f32_16x16x32_bf16 v[62:65], v[10:13], v[238:241], v[114:117]
	s_waitcnt lgkmcnt(0)
	v_mfma_f32_16x16x32_bf16 v[30:33], v[10:13], v[248:251], v[110:113]
	v_mfma_f32_16x16x32_bf16 v[122:125], v[14:17], v[230:233], v[106:109]
	v_mfma_f32_16x16x32_bf16 v[90:93], v[14:17], v[234:237], v[102:105]
	v_mfma_f32_16x16x32_bf16 v[58:61], v[14:17], v[238:241], v[98:101]
	v_mfma_f32_16x16x32_bf16 v[26:29], v[14:17], v[248:251], v[142:145]
	ds_read_b128 v[10:13], v225 offset:4096
	ds_read_b128 v[14:17], v225 offset:6144
	s_waitcnt lgkmcnt(1)
	v_mfma_f32_16x16x32_bf16 v[118:121], v[10:13], v[230:233], v[154:157]
	v_mfma_f32_16x16x32_bf16 v[86:89], v[10:13], v[234:237], v[86:89]
	v_mfma_f32_16x16x32_bf16 v[54:57], v[10:13], v[238:241], v[78:81]
	v_mfma_f32_16x16x32_bf16 v[22:25], v[10:13], v[248:251], v[70:73]
	ds_read_b128 v[10:13], v225 offset:8192
	s_nop 1
	ds_read_b128 v[70:73], v225 offset:10240
	s_waitcnt lgkmcnt(1)
	v_mfma_f32_16x16x32_bf16 v[110:113], v[10:13], v[230:233], v[42:45]
	s_waitcnt lgkmcnt(0)
	v_mfma_f32_16x16x32_bf16 v[42:45], v[70:73], v[238:241], v[2:5]
	s_nop 2
	ds_read_b128 v[2:5], v225 offset:12288
	ds_read_b128 v[142:145], v225 offset:14336
	s_waitcnt lgkmcnt(0)
	s_barrier
; DI f32x4 mfma16(bf16x8 a, bf16x8 b, f32x4 c) { return __builtin_amdgcn_mfma_f32_16x16x32_bf16(a, b, c, 0, 0, 0); }
; template <int MI, int NI>
; DI void gemm_kloop(const u16* Au, int lda, const u16* Bu, int ldb, int K, f32x4 (&acc)[NI][MI], unsigned char* smem) {
;     ...
;           for (int ni = 0; ni < 4; ++ni)
; #pragma unroll
;             for (int mi = 0; mi < MI; ++mi) acc[nh + ni][mi] = mfma16(wf[ni], af[mi], acc[nh + ni][mi]);
;         }
;       }
;     }
;   }
;   __syncthreads();
; template <int MI, int NI>
; DI void resid_epilogue(const Params& p, int from_x, const f32x4 (&acc)[NI][MI], int row0, int n0, float* rowss_next, bool last, int lm, int lg) {
; #pragma unroll
;   for (int mi = 0; mi < MI; ++mi) {
;     const int m = row0 + mi * 16 + lm;
;     const float* hr = hrow_r(p, from_x == 1 ? 0 : 1, m);
;     float* hw = hrow_w(p, m);
;     u16* hbr = p.hb + (size_t)m * DM;
;     float ss = 0.f;
; #pragma unroll
;     for (int ni = 0; ni < NI; ++ni) {
;       const int n = n0 + ni * 16 + lg * 4;
;       float4 h;
;       if (from_x >= 2) {
;         const u32x2 pk = *(const u32x2*)(hbr + n);
;         h = make_float4(__uint_as_float(pk[0] << 16), __uint_as_float(pk[0] & 0xffff0000u), __uint_as_float(pk[1] << 16), __uint_as_float(pk[1] & 0xffff0000u));
;       } else h = *(const float4*)(hr + n);
;       h.x += acc[ni][mi][0]; h.y += acc[ni][mi][1]; h.z += acc[ni][mi][2]; h.w += acc[ni][mi][3];
	v_mfma_f32_16x16x32_bf16 v[114:117], v[14:17], v[230:233], v[158:161]
	v_mfma_f32_16x16x32_bf16 v[82:85], v[14:17], v[234:237], v[162:165]
	v_mfma_f32_16x16x32_bf16 v[50:53], v[14:17], v[238:241], v[50:53]
	v_mfma_f32_16x16x32_bf16 v[18:21], v[14:17], v[248:251], v[46:49]
	v_mfma_f32_16x16x32_bf16 v[78:81], v[10:13], v[234:237], v[34:37]
	v_mfma_f32_16x16x32_bf16 v[46:49], v[10:13], v[238:241], v[168:171]
	v_mfma_f32_16x16x32_bf16 v[14:17], v[10:13], v[248:251], v[180:183]
	v_mfma_f32_16x16x32_bf16 v[106:109], v[70:73], v[230:233], v[184:187]
	v_mfma_f32_16x16x32_bf16 v[74:77], v[70:73], v[234:237], v[6:9]
	v_mfma_f32_16x16x32_bf16 v[10:13], v[70:73], v[248:251], v[188:191]
	v_mfma_f32_16x16x32_bf16 v[102:105], v[2:5], v[230:233], v[192:195]
	v_mfma_f32_16x16x32_bf16 v[70:73], v[2:5], v[234:237], v[226:229]
	v_mfma_f32_16x16x32_bf16 v[38:41], v[2:5], v[238:241], v[38:41]
	v_mfma_f32_16x16x32_bf16 v[6:9], v[2:5], v[248:251], v[66:69]
	v_mul_hi_i32 v2, v136, s81
	v_lshrrev_b32_e32 v3, 31, v2
	v_ashrrev_i32_e32 v2, 10, v2
	v_mfma_f32_16x16x32_bf16 v[98:101], v[142:145], v[230:233], v[130:133]
	v_mfma_f32_16x16x32_bf16 v[66:69], v[142:145], v[234:237], v[138:141]
	s_nop 1
	v_add_u32_e32 v132, v2, v3
	v_mad_i32_i24 v130, v132, s82, v136
	v_add_u32_e32 v133, -16, v130
	v_mfma_f32_16x16x32_bf16 v[34:37], v[142:145], v[238:241], v[146:149]
	v_cmp_lt_u32_e32 vcc, s83, v133
	v_mfma_f32_16x16x32_bf16 v[2:5], v[142:145], v[248:251], v[150:153]
	s_and_saveexec_b64 s[28:29], vcc
	s_xor_b64 s[28:29], exec, s[28:29]
	v_add_u32_e32 v131, 0xfffff000, v130
	v_cmp_gt_i32_e32 vcc, 16, v130
	s_nop 1
	v_cndmask_b32_e32 v130, v131, v130, vcc
	v_lshl_add_u32 v140, v132, 7, v130
	s_or_saveexec_b64 s[28:29], s[28:29]
	v_mov_b64_e32 v[130:131], s[96:97]
	s_xor_b64 exec, exec, s[28:29]
	v_lshl_add_u32 v140, v132, 12, v133
	v_mov_b64_e32 v[130:131], s[46:47]
	s_or_b64 exec, exec, s[28:29]
	global_load_dwordx2 v[142:143], v[130:131], off
	s_load_dwordx16 s[56:71], s[0:1], 0xc8
	v_ashrrev_i32_e32 v137, 31, v136
	v_or_b32_e32 v134, s2, v177
	v_lshlrev_b64 v[130:131], 11, v[136:137]
	v_ashrrev_i32_e32 v135, 31, v134
	s_waitcnt lgkmcnt(0)
	v_lshl_add_u64 v[130:131], s[56:57], 0, v[130:131]
	s_mov_b64 s[2:3], -1
	s_andn2_b64 vcc, exec, s[4:5]
	v_lshl_add_u64 v[138:139], v[134:135], 1, v[130:131]
	s_cbranch_vccnz .LBB0_80
	global_load_dwordx2 v[132:133], v[138:139], off
	s_mov_b64 s[2:3], 0
	s_waitcnt vmcnt(0)
	v_and_b32_e32 v131, 0xffff0000, v132
	v_lshlrev_b32_e32 v130, 16, v132
	v_lshlrev_b32_e32 v132, 16, v133
	v_and_b32_e32 v133, 0xffff0000, v133

; template <int MI, int NI>
; DI void gemm_kloop(const u16* Au, int lda, const u16* Bu, int ldb, int K, f32x4 (&acc)[NI][MI], unsigned char* smem) {
;   int tid_ = threadIdx.x; asm volatile("" : "+v"(tid_));
;   const int tid = tid_, lane = tid & 63, wave = tid >> 6, wm = wave >> 1, wn = wave & 1;
;   const int lr = tid >> 3, lc = tid & 7;
;   const int voa = lr * lda + lc * 8, vob = lr * ldb + lc * 8;
;   constexpr int NB2 = NI / 2;
;   u32x4 ra[MI], rb[NB2];
;   const int nk = K >> 6;
;   const int fsw = (lane & 15) >> 1;
;   const int fro0 = (lane & 15) * 128 + (((lane >> 4) ^ fsw) << 4);
;   const int fro1 = (lane & 15) * 128 + ((((lane >> 4) + 4) ^ fsw) << 4);
;   const int wof = lr * 128 + ((lc ^ ((lr >> 1) & 7)) << 4);
;     ...
;   GLOAD(0);
;   SWRITE(0);
; DI void phase_resid(const Params& p, int from_x, const u16* A, int K, const u16* W, float* rowss_next, bool last,
;                     unsigned char* smem) {
;     ...
;   for (int it = vblock(); it < nfull; it += gridDim.x) {
;     const int g = it / (4 * NT), rem = it - g * (4 * NT), nt = rem >> 2, mt = g * 4 + (rem & 3);
;     f32x4 acc[8][4];
;     zero_acc<4, 8>(acc);
;     gemm_kloop<4, 8>(A + (size_t)(mt * 256) * K, K, W + (size_t)(nt * 256) * K, K, K, acc, smem);
.LBB0_959:
	s_ashr_i32 s2, s31, 31
	s_lshr_b32 s2, s2, 28
	s_add_i32 s2, s31, s2
	s_lshl_b32 s2, s2, 6
	s_and_b32 s49, s2, 0xfffffc00
	s_lshl_b32 s2, s31, 8
	v_mov_b32_e32 v52, v166
	s_and_b32 s2, s2, 0x300
	s_movk_i32 s50, 0xb00
	v_ashrrev_i32_e32 v53, 3, v52
	s_or_b32 s43, s49, s2
	v_mul_lo_u32 v2, v53, s50
	s_waitcnt lgkmcnt(0)
	v_lshlrev_b32_e32 v3, 3, v52
	s_and_b32 s48, s44, 0x300
	s_mul_i32 s2, s43, 0x1600
	v_and_or_b32 v2, v3, 56, v2
	s_mul_hi_i32 s3, s43, 0x1600
	s_add_u32 s2, s86, s2
	v_ashrrev_i32_e32 v3, 31, v2
	s_addc_u32 s3, s87, s3
	s_waitcnt vmcnt(3)
	v_lshlrev_b64 v[34:35], 1, v[2:3]
	s_lshl_b32 s42, s31, 6
	v_lshl_add_u64 v[36:37], s[2:3], 0, v[34:35]
	s_sub_i32 s42, s42, s49
	s_waitcnt vmcnt(2)
	v_add_co_u32_e32 v38, vcc, s24, v36
	s_and_b32 s42, s42, 0xffffff00
	s_nop 0
	v_addc_co_u32_e32 v39, vcc, 0, v37, vcc
	s_mul_i32 s46, s42, 0x1600
	v_add_co_u32_e32 v40, vcc, s80, v36
	s_mul_hi_i32 s47, s42, 0x1600
	s_add_u32 s46, s28, s46
	v_addc_co_u32_e32 v41, vcc, 0, v37, vcc
	s_addc_u32 s47, s29, s47
	s_waitcnt vmcnt(1)
	v_add_co_u32_e32 v42, vcc, s18, v36
	v_lshl_add_u64 v[44:45], s[46:47], 0, v[34:35]
	s_nop 0
	v_addc_co_u32_e32 v43, vcc, 0, v37, vcc
	s_waitcnt vmcnt(0)
	s_mov_b64 s[88:89], s[2:3]
	s_mov_b64 s[90:91], s[46:47]
	v_lshrrev_b32_e32 v138, 3, v166
	v_lshlrev_b32_e32 v139, 4, v166
	v_xor_b32_e32 v139, v139, v166
	v_and_b32_e32 v139, 0x70, v139
	v_mul_u32_u24_e32 v255, 0x1600, v138
	v_or_b32_e32 v255, v255, v139
	v_lshrrev_b32_e32 v140, 6, v166
	s_nop 0
	v_readfirstlane_b32 s94, v140
	v_and_b32_e32 v138, 15, v166
	v_bfe_u32 v139, v166, 4, 2
	v_lshrrev_b32_e32 v140, 1, v138
	v_xor_b32_e32 v183, v139, v140
	v_or_b32_e32 v139, 4, v139
	v_xor_b32_e32 v226, v139, v140
	v_lshlrev_b32_e32 v138, 7, v138
	v_lshl_or_b32 v183, v183, 4, v138
	v_lshl_or_b32 v226, v226, 4, v138
	v_lshrrev_b32_e32 v138, 7, v166
	v_bfe_u32 v139, v166, 6, 1
	v_mul_u32_u24_e32 v139, 0x4000, v139
	v_add_u32_e32 v227, v139, v183
	v_add_u32_e32 v254, v139, v226
	v_mul_u32_u24_e32 v138, 0x2000, v138
	v_add_u32_e32 v183, v138, v183
	v_add_u32_e32 v226, v138, v226
	s_lshl_b32 s94, s94, 10
	s_mov_b32 m0, s94
	s_nop 0
	global_load_lds_dwordx4 v255, s[88:89]
	s_add_u32 m0, m0, 0x2000
	s_add_u32 s92, s88, 0x58000
	s_addc_u32 s93, s89, 0
	global_load_lds_dwordx4 v255, s[92:93]
	s_add_u32 m0, m0, 0x2000
	s_add_u32 s92, s88, 0xb0000
	s_addc_u32 s93, s89, 0
	global_load_lds_dwordx4 v255, s[92:93]
	s_add_u32 m0, m0, 0x2000
	s_add_u32 s92, s88, 0x108000
	s_addc_u32 s93, s89, 0
	global_load_lds_dwordx4 v255, s[92:93]
	s_add_u32 m0, m0, 0x2000
	s_nop 0
	global_load_lds_dwordx4 v255, s[90:91]
	s_add_u32 m0, m0, 0x2000
	s_add_u32 s92, s90, 0x58000
	s_addc_u32 s93, s91, 0
	global_load_lds_dwordx4 v255, s[92:93]
	s_add_u32 m0, m0, 0x2000
	s_add_u32 s92, s90, 0xb0000
	s_addc_u32 s93, s91, 0
	global_load_lds_dwordx4 v255, s[92:93]
	s_add_u32 m0, m0, 0x2000
	s_add_u32 s92, s90, 0x108000
	s_addc_u32 s93, s91, 0
	global_load_lds_dwordx4 v255, s[92:93]
	s_add_u32 s88, s88, 0x80
	s_addc_u32 s89, s89, 0
	s_add_u32 s90, s90, 0x80
	s_addc_u32 s91, s91, 0
	v_add_co_u32_e32 v46, vcc, s24, v44
	v_addc_co_u32_e32 v47, vcc, 0, v45, vcc
	v_add_co_u32_e32 v48, vcc, s80, v44
	v_addc_co_u32_e32 v49, vcc, 0, v45, vcc
	v_add_co_u32_e32 v50, vcc, s18, v44
	v_addc_co_u32_e32 v51, vcc, 0, v45, vcc
	s_sub_i32 s2, s34, s49
	s_and_b32 s2, s2, 0xffffff00
	s_mul_hi_i32 s3, s2, 0x1600
	s_mulk_i32 s2, 0x1600
	s_add_u32 s2, s23, s2
	s_addc_u32 s3, s21, s3
	v_lshl_add_u64 v[168:169], s[2:3], 0, v[34:35]
	s_or_b32 s2, s49, s48
	v_lshlrev_b32_e32 v58, 4, v52
	s_mul_hi_i32 s3, s2, 0x1600
	s_mulk_i32 s2, 0x1600
	v_and_b32_e32 v54, 15, v52
	v_bfe_u32 v55, v52, 1, 3
	v_lshrrev_b32_e32 v56, 4, v52
	v_bfe_u32 v57, v52, 4, 2
	v_lshlrev_b32_e32 v59, 6, v52
	v_lshlrev_b32_e32 v60, 8, v52
	v_xor_b32_e32 v52, v58, v52
	v_lshlrev_b32_e32 v53, 7, v53
	s_add_u32 s2, s86, s2
	v_lshlrev_b32_e32 v54, 7, v54
	v_bitop3_b32 v56, v56, v55, 3 bitop3:0x6c
	v_bitop3_b32 v55, v57, v55, 4 bitop3:0x36
	v_and_or_b32 v182, v52, s12, v53
	s_addc_u32 s3, s87, s3
	v_mov_b32_e32 v158, 0
	s_mov_b32 s46, 0
	v_and_b32_e32 v179, 0xffffe000, v59
	v_and_b32_e32 v181, 0x4000, v60
	v_lshl_or_b32 v180, v56, 4, v54
	v_lshl_or_b32 v178, v55, 4, v54
	v_lshl_add_u64 v[170:171], s[2:3], 0, v[34:35]
	s_mov_b64 s[2:3], 0
	v_mov_b32_e32 v159, v158
	v_mov_b32_e32 v160, v158
	v_mov_b32_e32 v161, v158
	v_mov_b32_e32 v58, v158
	v_mov_b32_e32 v59, v158
	v_mov_b32_e32 v60, v158
	v_mov_b32_e32 v61, v158
	v_mov_b32_e32 v74, v158
	v_mov_b32_e32 v75, v158
	v_mov_b32_e32 v76, v158
	v_mov_b32_e32 v77, v158
	v_mov_b32_e32 v78, v158
	v_mov_b32_e32 v79, v158
	v_mov_b32_e32 v80, v158
	v_mov_b32_e32 v81, v158
	v_mov_b32_e32 v62, v158
	v_mov_b32_e32 v63, v158
	v_mov_b32_e32 v64, v158
	v_mov_b32_e32 v65, v158
	v_mov_b32_e32 v38, v158
	v_mov_b32_e32 v39, v158
	v_mov_b32_e32 v40, v158
	v_mov_b32_e32 v41, v158
	v_mov_b32_e32 v2, v158
	v_mov_b32_e32 v3, v158
	v_mov_b32_e32 v4, v158
	v_mov_b32_e32 v5, v158
	v_mov_b32_e32 v6, v158
	v_mov_b32_e32 v7, v158
	v_mov_b32_e32 v8, v158
	v_mov_b32_e32 v9, v158
	v_mov_b32_e32 v10, v158
	v_mov_b32_e32 v11, v158
	v_mov_b32_e32 v12, v158
	v_mov_b32_e32 v13, v158
	v_mov_b32_e32 v14, v158
	v_mov_b32_e32 v15, v158
	v_mov_b32_e32 v16, v158
	v_mov_b32_e32 v17, v158
	v_mov_b32_e32 v18, v158
	v_mov_b32_e32 v19, v158
	v_mov_b32_e32 v20, v158
	v_mov_b32_e32 v21, v158
	v_mov_b32_e32 v22, v158
	v_mov_b32_e32 v23, v158
	v_mov_b32_e32 v24, v158
	v_mov_b32_e32 v25, v158
	v_mov_b32_e32 v26, v158
	v_mov_b32_e32 v27, v158
	v_mov_b32_e32 v28, v158
	v_mov_b32_e32 v29, v158
	v_mov_b32_e32 v30, v158
	v_mov_b32_e32 v31, v158
	v_mov_b32_e32 v32, v158
; DI f32x4 mfma16(bf16x8 a, bf16x8 b, f32x4 c) { return __builtin_amdgcn_mfma_f32_16x16x32_bf16(a, b, c, 0, 0, 0); }
; template <int MI, int NI>
; DI void gemm_kloop(const u16* Au, int lda, const u16* Bu, int ldb, int K, f32x4 (&acc)[NI][MI], unsigned char* smem) {
;     ...
;   for (int kt = 0; kt < nk; ++kt) {
;     __syncthreads();
;     if (kt + 1 < nk) {
;       SWRITE((kt + 1) & 1);
;       if (kt + 2 < nk) GLOAD((kt + 2) << 6);
;     }
;     {
;       const unsigned char* sa = smem + (kt & 1) * 65536;
;       const unsigned char* sb = sa + 32768;
; #pragma unroll
;       for (int ks = 0; ks < 2; ++ks) {
;         const int fo = ks ? fro1 : fro0;
;         bf16x8 af[MI];
; #pragma unroll
;         for (int i = 0; i < MI; ++i) af[i] = *(const bf16x8*)(sa + (wm * 16 * MI + i * 16) * 128 + fo);
; #pragma unroll
;         for (int nh = 0; nh < NI; nh += 4) {
;           bf16x8 wf[4];
; #pragma unroll
;           for (int i = 0; i < 4; ++i) wf[i] = *(const bf16x8*)(sb + (wn * 16 * NI + (nh + i) * 16) * 128 + fo);
; #pragma unroll
;           for (int ni = 0; ni < 4; ++ni)
; #pragma unroll
;             for (int mi = 0; mi < MI; ++mi) acc[nh + ni][mi] = mfma16(wf[ni], af[mi], acc[nh + ni][mi]);
;         }
; template <int MI, int NI>
; DI void zero_acc(f32x4 (&acc)[NI][MI]) {
; #pragma unroll
;   for (int i = 0; i < NI; ++i)
; #pragma unroll
;     for (int j = 0; j < MI; ++j) acc[i][j] = f32x4{0.f, 0.f, 0.f, 0.f};
; }
	v_mov_b32_e32 v33, v158
	v_mov_b32_e32 v34, v158
	v_mov_b32_e32 v35, v158
	v_mov_b32_e32 v36, v158
	v_mov_b32_e32 v37, v158
	v_mov_b32_e32 v42, v158
	v_mov_b32_e32 v43, v158
	v_mov_b32_e32 v44, v158
	v_mov_b32_e32 v45, v158
	v_mov_b32_e32 v46, v158
	v_mov_b32_e32 v47, v158
	v_mov_b32_e32 v48, v158
	v_mov_b32_e32 v49, v158
	v_mov_b32_e32 v50, v158
	v_mov_b32_e32 v51, v158
	v_mov_b32_e32 v52, v158
	v_mov_b32_e32 v53, v158
	v_mov_b32_e32 v54, v158
	v_mov_b32_e32 v55, v158
	v_mov_b32_e32 v56, v158
	v_mov_b32_e32 v57, v158
	v_mov_b32_e32 v66, v158
	v_mov_b32_e32 v67, v158
	v_mov_b32_e32 v68, v158
	v_mov_b32_e32 v69, v158
	v_mov_b32_e32 v70, v158
	v_mov_b32_e32 v71, v158
	v_mov_b32_e32 v72, v158
	v_mov_b32_e32 v73, v158
	v_mov_b32_e32 v82, v158
	v_mov_b32_e32 v83, v158
	v_mov_b32_e32 v84, v158
	v_mov_b32_e32 v85, v158
	v_mov_b32_e32 v86, v158
	v_mov_b32_e32 v87, v158
	v_mov_b32_e32 v88, v158
	v_mov_b32_e32 v89, v158
	v_mov_b32_e32 v90, v158
	v_mov_b32_e32 v91, v158
	v_mov_b32_e32 v92, v158
	v_mov_b32_e32 v93, v158
	v_mov_b32_e32 v94, v158
	v_mov_b32_e32 v95, v158
	v_mov_b32_e32 v96, v158
	v_mov_b32_e32 v97, v158
	v_mov_b32_e32 v98, v158
	v_mov_b32_e32 v99, v158
	v_mov_b32_e32 v100, v158
	v_mov_b32_e32 v101, v158
	v_mov_b32_e32 v102, v158
	v_mov_b32_e32 v103, v158
	v_mov_b32_e32 v104, v158
	v_mov_b32_e32 v105, v158
	v_mov_b32_e32 v106, v158
	v_mov_b32_e32 v107, v158
	v_mov_b32_e32 v108, v158
	v_mov_b32_e32 v109, v158
	v_mov_b32_e32 v110, v158
	v_mov_b32_e32 v111, v158
	v_mov_b32_e32 v112, v158
	v_mov_b32_e32 v113, v158
	v_mov_b32_e32 v114, v158
	v_mov_b32_e32 v115, v158
	v_mov_b32_e32 v116, v158
	v_mov_b32_e32 v117, v158
	v_mov_b32_e32 v118, v158
	v_mov_b32_e32 v119, v158
	v_mov_b32_e32 v120, v158
	v_mov_b32_e32 v121, v158
	v_mov_b32_e32 v150, v158
	v_mov_b32_e32 v151, v158
	v_mov_b32_e32 v152, v158
	v_mov_b32_e32 v153, v158
	s_mov_b32 s95, 0
.Lk_down:
	s_waitcnt vmcnt(0) lgkmcnt(0)
	s_barrier
	ds_read_b128 v[122:125], v183
	ds_read_b128 v[126:129], v183 offset:2048
	ds_read_b128 v[130:133], v183 offset:4096
	ds_read_b128 v[134:137], v183 offset:6144
	ds_read_b128 v[162:165], v227 offset:32768
	ds_read_b128 v[184:187], v227 offset:34816
	ds_read_b128 v[188:191], v227 offset:36864
	s_and_b32 s92, s95, 1
	s_xor_b32 s92, s92, 1
	s_lshl_b32 s92, s92, 16
	s_waitcnt lgkmcnt(2)
	v_mfma_f32_16x16x32_bf16 v[150:153], v[162:165], v[122:125], v[150:153]
	ds_read_b128 v[192:195], v227 offset:38912
	v_mfma_f32_16x16x32_bf16 v[118:121], v[162:165], v[126:129], v[118:121]
	v_mfma_f32_16x16x32_bf16 v[114:117], v[162:165], v[130:133], v[114:117]
	s_add_u32 m0, s92, s94
	s_nop 0
	global_load_lds_dwordx4 v255, s[88:89]
	v_mfma_f32_16x16x32_bf16 v[110:113], v[162:165], v[134:137], v[110:113]
	s_waitcnt lgkmcnt(2)
	v_mfma_f32_16x16x32_bf16 v[106:109], v[184:187], v[122:125], v[106:109]
	ds_read_b128 v[162:165], v227 offset:40960
	v_mfma_f32_16x16x32_bf16 v[102:105], v[184:187], v[126:129], v[102:105]
	ds_read_b128 v[138:141], v226
	v_mfma_f32_16x16x32_bf16 v[98:101], v[184:187], v[130:133], v[98:101]
	s_add_u32 m0, m0, 0x2000
	s_add_u32 s92, s88, 0x58000
	s_addc_u32 s93, s89, 0
	global_load_lds_dwordx4 v255, s[92:93]
	v_mfma_f32_16x16x32_bf16 v[94:97], v[184:187], v[134:137], v[94:97]
	s_waitcnt lgkmcnt(3)
	v_mfma_f32_16x16x32_bf16 v[90:93], v[188:191], v[122:125], v[90:93]
	ds_read_b128 v[184:187], v227 offset:43008
	v_mfma_f32_16x16x32_bf16 v[86:89], v[188:191], v[126:129], v[86:89]
	ds_read_b128 v[142:145], v226 offset:2048
	v_mfma_f32_16x16x32_bf16 v[82:85], v[188:191], v[130:133], v[82:85]
	s_add_u32 m0, m0, 0x2000
	s_add_u32 s92, s88, 0xb0000
	s_addc_u32 s93, s89, 0
	global_load_lds_dwordx4 v255, s[92:93]
	v_mfma_f32_16x16x32_bf16 v[70:73], v[188:191], v[134:137], v[70:73]
	s_waitcnt lgkmcnt(4)
	v_mfma_f32_16x16x32_bf16 v[66:69], v[192:195], v[122:125], v[66:69]
	ds_read_b128 v[188:191], v227 offset:45056
	v_mfma_f32_16x16x32_bf16 v[54:57], v[192:195], v[126:129], v[54:57]
	ds_read_b128 v[146:149], v226 offset:4096
	v_mfma_f32_16x16x32_bf16 v[50:53], v[192:195], v[130:133], v[50:53]
	s_add_u32 m0, m0, 0x2000
	s_add_u32 s92, s88, 0x108000
	s_addc_u32 s93, s89, 0
	global_load_lds_dwordx4 v255, s[92:93]
	v_mfma_f32_16x16x32_bf16 v[46:49], v[192:195], v[134:137], v[46:49]
	s_waitcnt lgkmcnt(5)
	v_mfma_f32_16x16x32_bf16 v[42:45], v[162:165], v[122:125], v[42:45]
	ds_read_b128 v[192:195], v227 offset:47104
	v_mfma_f32_16x16x32_bf16 v[34:37], v[162:165], v[126:129], v[34:37]
	ds_read_b128 v[154:157], v226 offset:6144
	v_mfma_f32_16x16x32_bf16 v[30:33], v[162:165], v[130:133], v[30:33]
	s_add_u32 m0, m0, 0x2000
	s_nop 0
	global_load_lds_dwordx4 v255, s[90:91]
	v_mfma_f32_16x16x32_bf16 v[26:29], v[162:165], v[134:137], v[26:29]
	s_waitcnt lgkmcnt(5)
	v_mfma_f32_16x16x32_bf16 v[22:25], v[184:187], v[122:125], v[22:25]
	ds_read_b128 v[162:165], v254 offset:32768
	v_mfma_f32_16x16x32_bf16 v[18:21], v[184:187], v[126:129], v[18:21]
	v_mfma_f32_16x16x32_bf16 v[14:17], v[184:187], v[130:133], v[14:17]
	s_add_u32 m0, m0, 0x2000
	s_add_u32 s92, s90, 0x58000
	s_addc_u32 s93, s91, 0
	global_load_lds_dwordx4 v255, s[92:93]
	v_mfma_f32_16x16x32_bf16 v[10:13], v[184:187], v[134:137], v[10:13]
	s_waitcnt lgkmcnt(4)
	v_mfma_f32_16x16x32_bf16 v[6:9], v[188:191], v[122:125], v[6:9]
	ds_read_b128 v[184:187], v254 offset:34816
	v_mfma_f32_16x16x32_bf16 v[2:5], v[188:191], v[126:129], v[2:5]
	v_mfma_f32_16x16x32_bf16 v[38:41], v[188:191], v[130:133], v[38:41]
	s_add_u32 m0, m0, 0x2000
	s_add_u32 s92, s90, 0xb0000
	s_addc_u32 s93, s91, 0
	global_load_lds_dwordx4 v255, s[92:93]
	v_mfma_f32_16x16x32_bf16 v[62:65], v[188:191], v[134:137], v[62:65]
	s_waitcnt lgkmcnt(3)
; DI f32x4 mfma16(bf16x8 a, bf16x8 b, f32x4 c) { return __builtin_amdgcn_mfma_f32_16x16x32_bf16(a, b, c, 0, 0, 0); }
; template <int MI, int NI>
; DI void gemm_kloop(const u16* Au, int lda, const u16* Bu, int ldb, int K, f32x4 (&acc)[NI][MI], unsigned char* smem) {
;     ...
;   for (int kt = 0; kt < nk; ++kt) {
;     __syncthreads();
;     if (kt + 1 < nk) {
;       SWRITE((kt + 1) & 1);
;       if (kt + 2 < nk) GLOAD((kt + 2) << 6);
;     }
;     {
;       const unsigned char* sa = smem + (kt & 1) * 65536;
;       const unsigned char* sb = sa + 32768;
; #pragma unroll
;       for (int ks = 0; ks < 2; ++ks) {
;         const int fo = ks ? fro1 : fro0;
;         bf16x8 af[MI];
; #pragma unroll
;         for (int i = 0; i < MI; ++i) af[i] = *(const bf16x8*)(sa + (wm * 16 * MI + i * 16) * 128 + fo);
; #pragma unroll
;         for (int nh = 0; nh < NI; nh += 4) {
;           bf16x8 wf[4];
; #pragma unroll
;           for (int i = 0; i < 4; ++i) wf[i] = *(const bf16x8*)(sb + (wn * 16 * NI + (nh + i) * 16) * 128 + fo);
; #pragma unroll
;           for (int ni = 0; ni < 4; ++ni)
; #pragma unroll
;             for (int mi = 0; mi < MI; ++mi) acc[nh + ni][mi] = mfma16(wf[ni], af[mi], acc[nh + ni][mi]);
;         }
;       }
;     }
;   }
	v_mfma_f32_16x16x32_bf16 v[78:81], v[192:195], v[122:125], v[78:81]
	ds_read_b128 v[188:191], v254 offset:36864
	v_mfma_f32_16x16x32_bf16 v[74:77], v[192:195], v[126:129], v[74:77]
	v_mfma_f32_16x16x32_bf16 v[58:61], v[192:195], v[130:133], v[58:61]
	s_add_u32 m0, m0, 0x2000
	s_add_u32 s92, s90, 0x108000
	s_addc_u32 s93, s91, 0
	global_load_lds_dwordx4 v255, s[92:93]
	v_mfma_f32_16x16x32_bf16 v[158:161], v[192:195], v[134:137], v[158:161]
	s_waitcnt lgkmcnt(2)
	v_mfma_f32_16x16x32_bf16 v[150:153], v[162:165], v[138:141], v[150:153]
	ds_read_b128 v[192:195], v254 offset:38912
	v_mfma_f32_16x16x32_bf16 v[118:121], v[162:165], v[142:145], v[118:121]
	v_mfma_f32_16x16x32_bf16 v[114:117], v[162:165], v[146:149], v[114:117]
	v_mfma_f32_16x16x32_bf16 v[110:113], v[162:165], v[154:157], v[110:113]
	s_waitcnt lgkmcnt(2)
	v_mfma_f32_16x16x32_bf16 v[106:109], v[184:187], v[138:141], v[106:109]
	ds_read_b128 v[162:165], v254 offset:40960
	v_mfma_f32_16x16x32_bf16 v[102:105], v[184:187], v[142:145], v[102:105]
	v_mfma_f32_16x16x32_bf16 v[98:101], v[184:187], v[146:149], v[98:101]
	v_mfma_f32_16x16x32_bf16 v[94:97], v[184:187], v[154:157], v[94:97]
	s_waitcnt lgkmcnt(2)
	v_mfma_f32_16x16x32_bf16 v[90:93], v[188:191], v[138:141], v[90:93]
	ds_read_b128 v[184:187], v254 offset:43008
	v_mfma_f32_16x16x32_bf16 v[86:89], v[188:191], v[142:145], v[86:89]
	v_mfma_f32_16x16x32_bf16 v[82:85], v[188:191], v[146:149], v[82:85]
	v_mfma_f32_16x16x32_bf16 v[70:73], v[188:191], v[154:157], v[70:73]
	s_waitcnt lgkmcnt(2)
	v_mfma_f32_16x16x32_bf16 v[66:69], v[192:195], v[138:141], v[66:69]
	ds_read_b128 v[188:191], v254 offset:45056
	v_mfma_f32_16x16x32_bf16 v[54:57], v[192:195], v[142:145], v[54:57]
	v_mfma_f32_16x16x32_bf16 v[50:53], v[192:195], v[146:149], v[50:53]
	v_mfma_f32_16x16x32_bf16 v[46:49], v[192:195], v[154:157], v[46:49]
	s_waitcnt lgkmcnt(2)
	v_mfma_f32_16x16x32_bf16 v[42:45], v[162:165], v[138:141], v[42:45]
	ds_read_b128 v[192:195], v254 offset:47104
	v_mfma_f32_16x16x32_bf16 v[34:37], v[162:165], v[142:145], v[34:37]
	v_mfma_f32_16x16x32_bf16 v[30:33], v[162:165], v[146:149], v[30:33]
	v_mfma_f32_16x16x32_bf16 v[26:29], v[162:165], v[154:157], v[26:29]
	s_waitcnt lgkmcnt(2)
	v_mfma_f32_16x16x32_bf16 v[22:25], v[184:187], v[138:141], v[22:25]
	v_mfma_f32_16x16x32_bf16 v[18:21], v[184:187], v[142:145], v[18:21]
	v_mfma_f32_16x16x32_bf16 v[14:17], v[184:187], v[146:149], v[14:17]
	v_mfma_f32_16x16x32_bf16 v[10:13], v[184:187], v[154:157], v[10:13]
	s_waitcnt lgkmcnt(1)
	v_mfma_f32_16x16x32_bf16 v[6:9], v[188:191], v[138:141], v[6:9]
	v_mfma_f32_16x16x32_bf16 v[2:5], v[188:191], v[142:145], v[2:5]
	v_mfma_f32_16x16x32_bf16 v[38:41], v[188:191], v[146:149], v[38:41]
	v_mfma_f32_16x16x32_bf16 v[62:65], v[188:191], v[154:157], v[62:65]
	s_waitcnt lgkmcnt(0)
	v_mfma_f32_16x16x32_bf16 v[78:81], v[192:195], v[138:141], v[78:81]
	v_mfma_f32_16x16x32_bf16 v[74:77], v[192:195], v[142:145], v[74:77]
	v_mfma_f32_16x16x32_bf16 v[58:61], v[192:195], v[146:149], v[58:61]
	v_mfma_f32_16x16x32_bf16 v[158:161], v[192:195], v[154:157], v[158:161]
	v_xor_b32_e32 v183, 0x10000, v183
	v_xor_b32_e32 v226, 0x10000, v226
	v_xor_b32_e32 v227, 0x10000, v227
	v_xor_b32_e32 v254, 0x10000, v254
	s_add_u32 s88, s88, 0x80
	s_addc_u32 s89, s89, 0
	s_add_u32 s90, s90, 0x80
	s_addc_u32 s91, s91, 0
	s_add_u32 s95, s95, 1
	s_cmp_lg_u32 s95, 42
	s_cbranch_scc1 .Lk_down
	s_waitcnt vmcnt(0)
	s_barrier
	s_add_u32 m0, s94, 0x10000
	s_nop 0
	global_load_lds_dwordx4 v255, s[88:89]
	s_add_u32 m0, m0, 0x2000
	s_add_u32 s92, s88, 0x58000
	s_addc_u32 s93, s89, 0
	global_load_lds_dwordx4 v255, s[92:93]
	s_add_u32 m0, m0, 0x2000
	s_add_u32 s92, s88, 0xb0000
	s_addc_u32 s93, s89, 0
	global_load_lds_dwordx4 v255, s[92:93]
	s_add_u32 m0, m0, 0x2000
	s_add_u32 s92, s88, 0x108000
	s_addc_u32 s93, s89, 0
	global_load_lds_dwordx4 v255, s[92:93]
	s_add_u32 m0, m0, 0x2000
	s_nop 0
	global_load_lds_dwordx4 v255, s[90:91]
	s_add_u32 m0, m0, 0x2000
	s_add_u32 s92, s90, 0x58000
	s_addc_u32 s93, s91, 0
	global_load_lds_dwordx4 v255, s[92:93]
	s_add_u32 m0, m0, 0x2000
	s_add_u32 s92, s90, 0xb0000
	s_addc_u32 s93, s91, 0
	global_load_lds_dwordx4 v255, s[92:93]
	s_add_u32 m0, m0, 0x2000
	s_add_u32 s92, s90, 0x108000
	s_addc_u32 s93, s91, 0
	global_load_lds_dwordx4 v255, s[92:93]
	v_add_u32_e32 v154, v181, v180
	ds_read_b128 v[122:125], v154 offset:32768
	v_add_u32_e32 v146, v179, v180
	ds_read_b128 v[126:129], v146
	ds_read_b128 v[130:133], v146 offset:2048
	ds_read_b128 v[134:137], v154 offset:34816
	ds_read_b128 v[142:145], v146 offset:4096
	ds_read_b128 v[146:149], v146 offset:6144
	s_waitcnt lgkmcnt(4)
	v_mfma_f32_16x16x32_bf16 v[138:141], v[122:125], v[126:129], v[150:153]
	s_nop 2
	v_add_u32_e32 v150, v179, v178
	v_or_b32_e32 v225, 0x18000, v181
	v_add_u32_e32 v192, v225, v180
	s_waitcnt lgkmcnt(3)
	v_mfma_f32_16x16x32_bf16 v[118:121], v[122:125], v[130:133], v[118:121]
	v_add_u32_e32 v179, 0x10000, v179
	v_add_u32_e32 v225, v225, v178
	s_waitcnt lgkmcnt(1)
	v_mfma_f32_16x16x32_bf16 v[114:117], v[122:125], v[142:145], v[114:117]
	s_waitcnt lgkmcnt(0)
	v_mfma_f32_16x16x32_bf16 v[110:113], v[122:125], v[146:149], v[110:113]
	v_mfma_f32_16x16x32_bf16 v[106:109], v[134:137], v[126:129], v[106:109]
	v_mfma_f32_16x16x32_bf16 v[102:105], v[134:137], v[130:133], v[102:105]
	v_mfma_f32_16x16x32_bf16 v[98:101], v[134:137], v[142:145], v[98:101]
	v_mfma_f32_16x16x32_bf16 v[94:97], v[134:137], v[146:149], v[94:97]
	ds_read_b128 v[122:125], v154 offset:36864
	ds_read_b128 v[134:137], v154 offset:38912
	s_waitcnt lgkmcnt(1)
; DI f32x4 mfma16(bf16x8 a, bf16x8 b, f32x4 c) { return __builtin_amdgcn_mfma_f32_16x16x32_bf16(a, b, c, 0, 0, 0); }
; template <int MI, int NI>
; DI void gemm_kloop(const u16* Au, int lda, const u16* Bu, int ldb, int K, f32x4 (&acc)[NI][MI], unsigned char* smem) {
;     ...
;     {
;       const unsigned char* sa = smem + (kt & 1) * 65536;
;       const unsigned char* sb = sa + 32768;
; #pragma unroll
;       for (int ks = 0; ks < 2; ++ks) {
;         const int fo = ks ? fro1 : fro0;
;         bf16x8 af[MI];
; #pragma unroll
;         for (int i = 0; i < MI; ++i) af[i] = *(const bf16x8*)(sa + (wm * 16 * MI + i * 16) * 128 + fo);
; #pragma unroll
;         for (int nh = 0; nh < NI; nh += 4) {
;           bf16x8 wf[4];
; #pragma unroll
;           for (int i = 0; i < 4; ++i) wf[i] = *(const bf16x8*)(sb + (wn * 16 * NI + (nh + i) * 16) * 128 + fo);
; #pragma unroll
;           for (int ni = 0; ni < 4; ++ni)
; #pragma unroll
;             for (int mi = 0; mi < MI; ++mi) acc[nh + ni][mi] = mfma16(wf[ni], af[mi], acc[nh + ni][mi]);
;         }
;       }
;     }
;   }
;   __syncthreads();
	v_mfma_f32_16x16x32_bf16 v[90:93], v[122:125], v[126:129], v[90:93]
	v_mfma_f32_16x16x32_bf16 v[86:89], v[122:125], v[130:133], v[86:89]
	v_mfma_f32_16x16x32_bf16 v[82:85], v[122:125], v[142:145], v[82:85]
	v_mfma_f32_16x16x32_bf16 v[70:73], v[122:125], v[146:149], v[70:73]
	s_waitcnt lgkmcnt(0)
	v_mfma_f32_16x16x32_bf16 v[66:69], v[134:137], v[126:129], v[66:69]
	v_mfma_f32_16x16x32_bf16 v[54:57], v[134:137], v[130:133], v[54:57]
	v_mfma_f32_16x16x32_bf16 v[50:53], v[134:137], v[142:145], v[50:53]
	v_mfma_f32_16x16x32_bf16 v[46:49], v[134:137], v[146:149], v[46:49]
	ds_read_b128 v[122:125], v154 offset:40960
	ds_read_b128 v[134:137], v154 offset:43008
	s_waitcnt lgkmcnt(1)
	v_mfma_f32_16x16x32_bf16 v[42:45], v[122:125], v[126:129], v[42:45]
	v_mfma_f32_16x16x32_bf16 v[34:37], v[122:125], v[130:133], v[34:37]
	v_mfma_f32_16x16x32_bf16 v[30:33], v[122:125], v[142:145], v[30:33]
	v_mfma_f32_16x16x32_bf16 v[26:29], v[122:125], v[146:149], v[26:29]
	s_waitcnt lgkmcnt(0)
	v_mfma_f32_16x16x32_bf16 v[22:25], v[134:137], v[126:129], v[22:25]
	v_mfma_f32_16x16x32_bf16 v[18:21], v[134:137], v[130:133], v[18:21]
	v_mfma_f32_16x16x32_bf16 v[14:17], v[134:137], v[142:145], v[14:17]
	v_mfma_f32_16x16x32_bf16 v[10:13], v[134:137], v[146:149], v[10:13]
	ds_read_b128 v[122:125], v154 offset:45056
	ds_read_b128 v[134:137], v154 offset:47104
	v_add_u32_e32 v154, v181, v178
	s_waitcnt lgkmcnt(1)
	v_mfma_f32_16x16x32_bf16 v[6:9], v[122:125], v[126:129], v[6:9]
	v_mfma_f32_16x16x32_bf16 v[2:5], v[122:125], v[130:133], v[2:5]
	v_mfma_f32_16x16x32_bf16 v[38:41], v[122:125], v[142:145], v[38:41]
	v_mfma_f32_16x16x32_bf16 v[62:65], v[122:125], v[146:149], v[62:65]
	ds_read_b128 v[122:125], v154 offset:32768
	s_waitcnt lgkmcnt(1)
	v_mfma_f32_16x16x32_bf16 v[78:81], v[134:137], v[126:129], v[78:81]
	v_mfma_f32_16x16x32_bf16 v[74:77], v[134:137], v[130:133], v[74:77]
	v_mfma_f32_16x16x32_bf16 v[58:61], v[134:137], v[142:145], v[58:61]
	v_mfma_f32_16x16x32_bf16 v[126:129], v[134:137], v[146:149], v[158:161]
	ds_read_b128 v[130:133], v150
	ds_read_b128 v[134:137], v150 offset:2048
	ds_read_b128 v[142:145], v154 offset:34816
	ds_read_b128 v[146:149], v150 offset:4096
	ds_read_b128 v[150:153], v150 offset:6144
	s_waitcnt lgkmcnt(4)
	v_mfma_f32_16x16x32_bf16 v[138:141], v[122:125], v[130:133], v[138:141]
	s_waitcnt lgkmcnt(3)
	v_mfma_f32_16x16x32_bf16 v[118:121], v[122:125], v[134:137], v[118:121]
	s_waitcnt lgkmcnt(1)
	v_mfma_f32_16x16x32_bf16 v[114:117], v[122:125], v[146:149], v[114:117]
	s_waitcnt lgkmcnt(0)
	v_mfma_f32_16x16x32_bf16 v[110:113], v[122:125], v[150:153], v[110:113]
	v_mfma_f32_16x16x32_bf16 v[106:109], v[142:145], v[130:133], v[106:109]
	v_mfma_f32_16x16x32_bf16 v[102:105], v[142:145], v[134:137], v[102:105]
	v_mfma_f32_16x16x32_bf16 v[98:101], v[142:145], v[146:149], v[98:101]
	v_mfma_f32_16x16x32_bf16 v[94:97], v[142:145], v[150:153], v[94:97]
	ds_read_b128 v[122:125], v154 offset:36864
	ds_read_b128 v[142:145], v154 offset:38912
	s_waitcnt lgkmcnt(1)
	v_mfma_f32_16x16x32_bf16 v[90:93], v[122:125], v[130:133], v[90:93]
	v_mfma_f32_16x16x32_bf16 v[86:89], v[122:125], v[134:137], v[86:89]
	v_mfma_f32_16x16x32_bf16 v[82:85], v[122:125], v[146:149], v[82:85]
	v_mfma_f32_16x16x32_bf16 v[70:73], v[122:125], v[150:153], v[70:73]
	s_waitcnt lgkmcnt(0)
	v_mfma_f32_16x16x32_bf16 v[66:69], v[142:145], v[130:133], v[66:69]
	v_mfma_f32_16x16x32_bf16 v[54:57], v[142:145], v[134:137], v[54:57]
	v_mfma_f32_16x16x32_bf16 v[50:53], v[142:145], v[146:149], v[50:53]
	v_mfma_f32_16x16x32_bf16 v[46:49], v[142:145], v[150:153], v[46:49]
	ds_read_b128 v[122:125], v154 offset:40960
	ds_read_b128 v[142:145], v154 offset:43008
	s_waitcnt lgkmcnt(1)
	v_mfma_f32_16x16x32_bf16 v[42:45], v[122:125], v[130:133], v[42:45]
	v_mfma_f32_16x16x32_bf16 v[34:37], v[122:125], v[134:137], v[34:37]
	v_mfma_f32_16x16x32_bf16 v[30:33], v[122:125], v[146:149], v[30:33]
	v_mfma_f32_16x16x32_bf16 v[26:29], v[122:125], v[150:153], v[26:29]
	s_waitcnt lgkmcnt(0)
	v_mfma_f32_16x16x32_bf16 v[22:25], v[142:145], v[130:133], v[22:25]
	v_mfma_f32_16x16x32_bf16 v[18:21], v[142:145], v[134:137], v[18:21]
	v_mfma_f32_16x16x32_bf16 v[14:17], v[142:145], v[146:149], v[14:17]
	v_mfma_f32_16x16x32_bf16 v[10:13], v[142:145], v[150:153], v[10:13]
	ds_read_b128 v[122:125], v154 offset:45056
	ds_read_b128 v[142:145], v154 offset:47104
	s_waitcnt vmcnt(0) lgkmcnt(0)
	s_barrier
; DI f32x4 mfma16(bf16x8 a, bf16x8 b, f32x4 c) { return __builtin_amdgcn_mfma_f32_16x16x32_bf16(a, b, c, 0, 0, 0); }
; template <int MI, int NI>
; DI void gemm_kloop(const u16* Au, int lda, const u16* Bu, int ldb, int K, f32x4 (&acc)[NI][MI], unsigned char* smem) {
;     ...
;     {
;       const unsigned char* sa = smem + (kt & 1) * 65536;
;       const unsigned char* sb = sa + 32768;
; #pragma unroll
;       for (int ks = 0; ks < 2; ++ks) {
;         const int fo = ks ? fro1 : fro0;
;         bf16x8 af[MI];
; #pragma unroll
;         for (int i = 0; i < MI; ++i) af[i] = *(const bf16x8*)(sa + (wm * 16 * MI + i * 16) * 128 + fo);
; #pragma unroll
;         for (int nh = 0; nh < NI; nh += 4) {
;           bf16x8 wf[4];
; #pragma unroll
;           for (int i = 0; i < 4; ++i) wf[i] = *(const bf16x8*)(sb + (wn * 16 * NI + (nh + i) * 16) * 128 + fo);
; #pragma unroll
;           for (int ni = 0; ni < 4; ++ni)
; #pragma unroll
;             for (int mi = 0; mi < MI; ++mi) acc[nh + ni][mi] = mfma16(wf[ni], af[mi], acc[nh + ni][mi]);
;         }
;       }
;     }
;   }
;   __syncthreads();
	v_mfma_f32_16x16x32_bf16 v[6:9], v[122:125], v[130:133], v[6:9]
	v_mfma_f32_16x16x32_bf16 v[2:5], v[122:125], v[134:137], v[2:5]
	v_mfma_f32_16x16x32_bf16 v[38:41], v[122:125], v[146:149], v[38:41]
	v_mfma_f32_16x16x32_bf16 v[62:65], v[122:125], v[150:153], v[62:65]
	ds_read_b128 v[122:125], v192
	v_mfma_f32_16x16x32_bf16 v[126:129], v[142:145], v[150:153], v[126:129]
	v_add_u32_e32 v150, v179, v180
	v_mfma_f32_16x16x32_bf16 v[78:81], v[142:145], v[130:133], v[78:81]
	v_mfma_f32_16x16x32_bf16 v[74:77], v[142:145], v[134:137], v[74:77]
	v_mfma_f32_16x16x32_bf16 v[58:61], v[142:145], v[146:149], v[58:61]
	ds_read_b128 v[130:133], v150
	ds_read_b128 v[134:137], v150 offset:2048
	ds_read_b128 v[142:145], v192 offset:2048
	ds_read_b128 v[146:149], v150 offset:4096
	ds_read_b128 v[150:153], v150 offset:6144
	s_waitcnt lgkmcnt(4)
	v_mfma_f32_16x16x32_bf16 v[138:141], v[122:125], v[130:133], v[138:141]
	s_waitcnt lgkmcnt(3)
	v_mfma_f32_16x16x32_bf16 v[118:121], v[122:125], v[134:137], v[118:121]
	s_waitcnt lgkmcnt(1)
	v_mfma_f32_16x16x32_bf16 v[114:117], v[122:125], v[146:149], v[114:117]
	s_waitcnt lgkmcnt(0)
	v_mfma_f32_16x16x32_bf16 v[110:113], v[122:125], v[150:153], v[110:113]
	v_mfma_f32_16x16x32_bf16 v[106:109], v[142:145], v[130:133], v[106:109]
	v_mfma_f32_16x16x32_bf16 v[102:105], v[142:145], v[134:137], v[102:105]
	v_mfma_f32_16x16x32_bf16 v[98:101], v[142:145], v[146:149], v[98:101]
	v_mfma_f32_16x16x32_bf16 v[142:145], v[142:145], v[150:153], v[94:97]
	s_nop 2
	ds_read_b128 v[94:97], v192 offset:4096
	ds_read_b128 v[122:125], v192 offset:6144
	s_waitcnt lgkmcnt(1)
	v_mfma_f32_16x16x32_bf16 v[154:157], v[94:97], v[130:133], v[90:93]
	s_waitcnt lgkmcnt(0)
	v_mfma_f32_16x16x32_bf16 v[158:161], v[122:125], v[134:137], v[54:57]
	s_nop 2
	ds_read_b128 v[54:57], v192 offset:8192
	ds_read_b128 v[90:93], v192 offset:10240
	s_waitcnt lgkmcnt(0)
	v_mfma_f32_16x16x32_bf16 v[184:187], v[90:93], v[134:137], v[18:21]
	v_mfma_f32_16x16x32_bf16 v[188:191], v[90:93], v[146:149], v[14:17]
	s_nop 2
	ds_read_b128 v[14:17], v192 offset:12288
	ds_read_b128 v[18:21], v192 offset:14336
	s_waitcnt lgkmcnt(1)
	v_mfma_f32_16x16x32_bf16 v[6:9], v[14:17], v[130:133], v[6:9]
	v_mfma_f32_16x16x32_bf16 v[2:5], v[14:17], v[134:137], v[2:5]
	v_mfma_f32_16x16x32_bf16 v[38:41], v[14:17], v[146:149], v[38:41]
	v_mfma_f32_16x16x32_bf16 v[192:195], v[14:17], v[150:153], v[62:65]
	ds_read_b128 v[14:17], v225
	v_mfma_f32_16x16x32_bf16 v[180:183], v[90:93], v[130:133], v[22:25]
	s_nop 2
	v_add_u32_e32 v22, v179, v178
	v_mfma_f32_16x16x32_bf16 v[86:89], v[94:97], v[134:137], v[86:89]
	v_mfma_f32_16x16x32_bf16 v[82:85], v[94:97], v[146:149], v[82:85]
	v_mfma_f32_16x16x32_bf16 v[70:73], v[94:97], v[150:153], v[70:73]
	v_mfma_f32_16x16x32_bf16 v[66:69], v[122:125], v[130:133], v[66:69]
	v_mfma_f32_16x16x32_bf16 v[50:53], v[122:125], v[146:149], v[50:53]
	v_mfma_f32_16x16x32_bf16 v[46:49], v[122:125], v[150:153], v[46:49]
	v_mfma_f32_16x16x32_bf16 v[42:45], v[54:57], v[130:133], v[42:45]
	v_mfma_f32_16x16x32_bf16 v[34:37], v[54:57], v[134:137], v[34:37]
	v_mfma_f32_16x16x32_bf16 v[162:165], v[54:57], v[146:149], v[30:33]
	v_mfma_f32_16x16x32_bf16 v[168:171], v[54:57], v[150:153], v[26:29]
	v_mfma_f32_16x16x32_bf16 v[10:13], v[90:93], v[150:153], v[10:13]
	s_waitcnt lgkmcnt(1)
	v_mfma_f32_16x16x32_bf16 v[130:133], v[18:21], v[130:133], v[78:81]
	v_mfma_f32_16x16x32_bf16 v[134:137], v[18:21], v[134:137], v[74:77]
	v_mfma_f32_16x16x32_bf16 v[146:149], v[18:21], v[146:149], v[58:61]
	v_mfma_f32_16x16x32_bf16 v[150:153], v[18:21], v[150:153], v[126:129]
	ds_read_b128 v[226:229], v22
	ds_read_b128 v[230:233], v22 offset:2048
	ds_read_b128 v[18:21], v225 offset:2048
	s_waitcnt lgkmcnt(2)
	v_mfma_f32_16x16x32_bf16 v[126:129], v[14:17], v[226:229], v[138:141]
	s_nop 2
	ds_read_b128 v[138:141], v22 offset:4096
	ds_read_b128 v[234:237], v22 offset:6144
	s_waitcnt lgkmcnt(3)
	v_mfma_f32_16x16x32_bf16 v[94:97], v[14:17], v[230:233], v[118:121]
	s_waitcnt lgkmcnt(1)
	v_mfma_f32_16x16x32_bf16 v[62:65], v[14:17], v[138:141], v[114:117]
	s_waitcnt lgkmcnt(0)
	v_mfma_f32_16x16x32_bf16 v[30:33], v[14:17], v[234:237], v[110:113]
	v_mfma_f32_16x16x32_bf16 v[122:125], v[18:21], v[226:229], v[106:109]
	v_mfma_f32_16x16x32_bf16 v[90:93], v[18:21], v[230:233], v[102:105]
	v_mfma_f32_16x16x32_bf16 v[58:61], v[18:21], v[138:141], v[98:101]
	v_mfma_f32_16x16x32_bf16 v[26:29], v[18:21], v[234:237], v[142:145]
	ds_read_b128 v[14:17], v225 offset:4096
	ds_read_b128 v[18:21], v225 offset:6144
	s_waitcnt lgkmcnt(1)
	v_mfma_f32_16x16x32_bf16 v[118:121], v[14:17], v[226:229], v[154:157]
	v_mfma_f32_16x16x32_bf16 v[86:89], v[14:17], v[230:233], v[86:89]
	v_mfma_f32_16x16x32_bf16 v[54:57], v[14:17], v[138:141], v[82:85]
	v_mfma_f32_16x16x32_bf16 v[22:25], v[14:17], v[234:237], v[70:73]
	s_waitcnt lgkmcnt(0)
	v_mfma_f32_16x16x32_bf16 v[114:117], v[18:21], v[226:229], v[66:69]
	ds_read_b128 v[14:17], v225 offset:8192
	s_nop 1
	ds_read_b128 v[66:69], v225 offset:10240
	s_waitcnt lgkmcnt(1)
	v_mfma_f32_16x16x32_bf16 v[78:81], v[14:17], v[230:233], v[34:37]
	s_nop 2
	ds_read_b128 v[34:37], v225 offset:12288
	ds_read_b128 v[142:145], v225 offset:14336
	s_waitcnt lgkmcnt(0)
	s_barrier
; DI const float* hrow_r(const Params& p, int layer, int gr) {
;   int b = gr / TP, t = gr - b * TP;
;   if (t >= NMETA && t < TREAL) {
;     size_t o = ((size_t)(b * SEQ + t - NMETA)) * DM;
;     return layer == 0 ? p.x + o : p.out + o;
;   }
;   int s = t < NMETA ? t : t - TREAL + NMETA;
;   return p.side + ((size_t)(b * 128 + s)) * DM;
; template <int MI, int NI>
; DI void resid_epilogue(const Params& p, int from_x, const f32x4 (&acc)[NI][MI], int row0, int n0, float* rowss_next, bool last, int lm, int lg) {
; #pragma unroll
;   for (int mi = 0; mi < MI; ++mi) {
;     const int m = row0 + mi * 16 + lm;
;     const float* hr = hrow_r(p, from_x == 1 ? 0 : 1, m);
;     float* hw = hrow_w(p, m);
;     u16* hbr = p.hb + (size_t)m * DM;
	v_mfma_f32_16x16x32_bf16 v[98:101], v[142:145], v[226:229], v[130:133]
	s_nop 2
	v_add_u32_e32 v130, s43, v176
	v_mfma_f32_16x16x32_bf16 v[70:73], v[34:37], v[230:233], v[2:5]
	s_nop 2
	v_mul_hi_i32 v2, v130, s81
	v_lshrrev_b32_e32 v3, 31, v2
	v_ashrrev_i32_e32 v2, 10, v2
	v_mfma_f32_16x16x32_bf16 v[82:85], v[18:21], v[230:233], v[158:161]
	v_add_u32_e32 v131, v2, v3
	v_mad_i32_i24 v133, v131, s82, v130
	v_add_u32_e32 v132, -16, v133
	v_mfma_f32_16x16x32_bf16 v[50:53], v[18:21], v[138:141], v[50:53]
	v_cmp_lt_u32_e32 vcc, s83, v132
	v_mfma_f32_16x16x32_bf16 v[18:21], v[18:21], v[234:237], v[46:49]
	v_mfma_f32_16x16x32_bf16 v[110:113], v[14:17], v[226:229], v[42:45]
	v_mfma_f32_16x16x32_bf16 v[46:49], v[14:17], v[138:141], v[162:165]
	v_mfma_f32_16x16x32_bf16 v[14:17], v[14:17], v[234:237], v[168:171]
	v_mfma_f32_16x16x32_bf16 v[106:109], v[66:69], v[226:229], v[180:183]
	v_mfma_f32_16x16x32_bf16 v[74:77], v[66:69], v[230:233], v[184:187]
	v_mfma_f32_16x16x32_bf16 v[42:45], v[66:69], v[138:141], v[188:191]
	v_mfma_f32_16x16x32_bf16 v[10:13], v[66:69], v[234:237], v[10:13]
	v_mfma_f32_16x16x32_bf16 v[102:105], v[34:37], v[226:229], v[6:9]
	v_mfma_f32_16x16x32_bf16 v[38:41], v[34:37], v[138:141], v[38:41]
	v_mfma_f32_16x16x32_bf16 v[6:9], v[34:37], v[234:237], v[192:195]
	v_mfma_f32_16x16x32_bf16 v[66:69], v[142:145], v[230:233], v[134:137]
	v_mfma_f32_16x16x32_bf16 v[34:37], v[142:145], v[138:141], v[146:149]
	v_mfma_f32_16x16x32_bf16 v[2:5], v[142:145], v[234:237], v[150:153]
	s_and_saveexec_b64 s[2:3], vcc
	s_xor_b64 s[2:3], exec, s[2:3]
	v_add_u32_e32 v132, 0xfffff000, v133
	v_cmp_gt_i32_e32 vcc, 16, v133
	s_nop 1
	v_cndmask_b32_e32 v132, v132, v133, vcc
	v_lshl_add_u32 v136, v131, 7, v132
	s_or_saveexec_b64 s[2:3], s[2:3]
	v_mov_b64_e32 v[134:135], s[96:97]
	s_xor_b64 exec, exec, s[2:3]
	s_cbranch_execz .LBB0_965
	v_readlane_b32 s46, v253, 27
	v_readlane_b32 s47, v253, 28
	v_lshl_add_u32 v136, v131, 12, v132
	s_nop 0
	v_mov_b64_e32 v[134:135], s[46:47]

; template <int MI, int NI>
; DI void gemm_kloop(const u16* Au, int lda, const u16* Bu, int ldb, int K, f32x4 (&acc)[NI][MI], unsigned char* smem) {
;   int tid_ = threadIdx.x; asm volatile("" : "+v"(tid_));
;   const int tid = tid_, lane = tid & 63, wave = tid >> 6, wm = wave >> 1, wn = wave & 1;
;   const int lr = tid >> 3, lc = tid & 7;
;   const int voa = lr * lda + lc * 8, vob = lr * ldb + lc * 8;
;   constexpr int NB2 = NI / 2;
;   u32x4 ra[MI], rb[NB2];
;   const int nk = K >> 6;
;   const int fsw = (lane & 15) >> 1;
;   const int fro0 = (lane & 15) * 128 + (((lane >> 4) ^ fsw) << 4);
;   const int fro1 = (lane & 15) * 128 + ((((lane >> 4) + 4) ^ fsw) << 4);
;   const int wof = lr * 128 + ((lc ^ ((lr >> 1) & 7)) << 4);
;     ...
;   GLOAD(0);
;   SWRITE(0);
;   if (nk > 1) GLOAD(64);
; DI void phase_g1(const Params& p, int layer, unsigned char* smem) {
;     ...
;   for (int it = vblock(); it < NTILES; it += gridDim.x) {
;     const int g = it / (4 * NT), rem = it - g * (4 * NT), nt = rem >> 2, mt = g * 4 + (rem & 3);
;     f32x4 acc[8][4];
;     zero_acc<4, 8>(acc);
;     gemm_kloop<4, 8>(p.hb + (size_t)(mt * 256) * DM, DM, W + (size_t)(nt * 256) * DM, DM, DM, acc, smem);
.LBB0_1182:
	s_mul_hi_i32 s2, s58, 0x4ec4ec4f
	s_lshr_b32 s3, s2, 31
	s_ashr_i32 s2, s2, 4
	s_add_i32 s2, s2, s3
	s_mul_i32 s30, s2, 0xffffffcc
	s_lshl_b32 s48, s2, 10
	s_lshl_b32 s2, s58, 8
	s_load_dwordx16 s[60:75], s[0:1], 0xc8
	s_and_b32 s2, s2, 0x300
	v_mov_b32_e32 v50, v166
	s_or_b32 s2, s48, s2
	s_add_i32 s30, s30, s58
	v_lshlrev_b32_e32 v2, 3, v50
	s_ashr_i32 s3, s2, 31
	v_ashrrev_i32_e32 v51, 3, v50
	v_and_b32_e32 v2, 56, v2
	s_and_b32 s31, s59, 0x300
	s_waitcnt lgkmcnt(0)
	s_ashr_i32 s54, s30, 2
	s_lshl_b64 s[4:5], s[2:3], 11
	v_lshl_or_b32 v2, v51, 10, v2
	s_waitcnt lgkmcnt(0)
	s_add_u32 s28, s60, s4
	v_ashrrev_i32_e32 v3, 31, v2
	s_addc_u32 s29, s61, s5
	s_waitcnt vmcnt(3)
	v_lshlrev_b64 v[34:35], 1, v[2:3]
	v_lshl_add_u64 v[36:37], s[28:29], 0, v[34:35]
	s_lshl_b32 s4, s54, 8
	s_waitcnt vmcnt(2)
	v_add_co_u32_e32 v38, vcc, s33, v36
	s_ashr_i32 s5, s4, 31
	s_nop 0
	v_addc_co_u32_e32 v39, vcc, 0, v37, vcc
	s_lshl_b64 s[34:35], s[4:5], 11
	v_add_co_u32_e32 v40, vcc, s36, v36
	s_add_u32 s34, s23, s34
	s_nop 0
	v_addc_co_u32_e32 v41, vcc, 0, v37, vcc
	s_addc_u32 s35, s21, s35
	s_waitcnt vmcnt(1)
	v_add_co_u32_e32 v42, vcc, s37, v36
	v_lshl_add_u64 v[164:165], s[34:35], 0, v[34:35]
	s_nop 0
	v_addc_co_u32_e32 v43, vcc, 0, v37, vcc
	v_add_co_u32_e32 v44, vcc, s33, v164
	v_addc_co_u32_e32 v45, vcc, 0, v165, vcc
	s_waitcnt vmcnt(2)
	s_mov_b64 s[88:89], s[28:29]
	s_mov_b64 s[90:91], s[34:35]
	v_lshrrev_b32_e32 v98, 3, v166
	v_lshlrev_b32_e32 v99, 4, v166
	v_xor_b32_e32 v99, v99, v166
	v_and_b32_e32 v99, 0x70, v99
	v_lshl_or_b32 v254, v98, 11, v99
	v_lshrrev_b32_e32 v100, 6, v166
	s_nop 0
	v_readfirstlane_b32 s94, v100
	v_and_b32_e32 v98, 15, v166
	v_bfe_u32 v99, v166, 4, 2
	v_lshrrev_b32_e32 v100, 1, v98
	v_xor_b32_e32 v226, v99, v100
	v_or_b32_e32 v99, 4, v99
	v_xor_b32_e32 v227, v99, v100
	v_lshlrev_b32_e32 v98, 7, v98
	v_lshl_or_b32 v226, v226, 4, v98
	v_lshl_or_b32 v227, v227, 4, v98
	v_lshrrev_b32_e32 v98, 7, v166
	v_bfe_u32 v99, v166, 6, 1
	v_mul_u32_u24_e32 v99, 0x4000, v99
	v_add_u32_e32 v228, v99, v226
	v_add_u32_e32 v229, v99, v227
	v_mul_u32_u24_e32 v98, 0x2000, v98
	v_add_u32_e32 v226, v98, v226
	v_add_u32_e32 v227, v98, v227
	s_lshl_b32 s94, s94, 10
	s_mov_b32 m0, s94
	s_nop 0
	global_load_lds_dwordx4 v254, s[88:89]
	s_add_u32 m0, m0, 0x2000
	s_add_u32 s92, s88, 0x20000
	s_addc_u32 s93, s89, 0
	global_load_lds_dwordx4 v254, s[92:93]
	s_add_u32 m0, m0, 0x2000
	s_add_u32 s92, s88, 0x40000
	s_addc_u32 s93, s89, 0
	global_load_lds_dwordx4 v254, s[92:93]
	s_add_u32 m0, m0, 0x2000
	s_add_u32 s92, s88, 0x60000
	s_addc_u32 s93, s89, 0
	global_load_lds_dwordx4 v254, s[92:93]
	s_add_u32 m0, m0, 0x2000
	s_nop 0
	global_load_lds_dwordx4 v254, s[90:91]
	s_add_u32 m0, m0, 0x2000
	s_add_u32 s92, s90, 0x20000
	s_addc_u32 s93, s91, 0
	global_load_lds_dwordx4 v254, s[92:93]
	s_add_u32 m0, m0, 0x2000
	s_add_u32 s92, s90, 0x40000
	s_addc_u32 s93, s91, 0
	global_load_lds_dwordx4 v254, s[92:93]
	s_add_u32 m0, m0, 0x2000
	s_add_u32 s92, s90, 0x60000
	s_addc_u32 s93, s91, 0
	global_load_lds_dwordx4 v254, s[92:93]
	s_add_u32 s88, s88, 0x80
	s_addc_u32 s89, s89, 0
	s_add_u32 s90, s90, 0x80
	s_addc_u32 s91, s91, 0
	v_add_co_u32_e32 v46, vcc, s36, v164
	v_addc_co_u32_e32 v47, vcc, 0, v165, vcc
	v_add_co_u32_e32 v48, vcc, s37, v164
	s_nop 0
	v_addc_co_u32_e32 v49, vcc, 0, v165, vcc
	s_or_b32 s28, s48, s31
	v_lshlrev_b32_e32 v56, 4, v50
	s_ashr_i32 s29, s28, 31
	v_and_b32_e32 v52, 15, v50
	v_bfe_u32 v53, v50, 1, 3
	v_lshrrev_b32_e32 v54, 4, v50
	v_bfe_u32 v55, v50, 4, 2
	v_lshlrev_b32_e32 v57, 6, v50
	v_lshlrev_b32_e32 v58, 8, v50
	v_xor_b32_e32 v50, v56, v50
	v_lshlrev_b32_e32 v51, 7, v51
	s_lshl_b64 s[28:29], s[28:29], 11
	v_and_or_b32 v179, v50, s12, v51
	s_add_u32 s28, s60, s28
	v_lshlrev_b32_e32 v52, 7, v52
	v_bitop3_b32 v54, v54, v53, 3 bitop3:0x6c
	v_bitop3_b32 v53, v55, v53, 4 bitop3:0x36
	s_addc_u32 s29, s61, s29
	s_mov_b32 s3, 0
	v_and_b32_e32 v176, 0xffffe000, v57
	v_and_b32_e32 v178, 0x4000, v58
	v_lshl_or_b32 v177, v54, 4, v52
	v_lshl_or_b32 v175, v53, 4, v52
	v_lshl_add_u64 v[168:169], s[28:29], 0, v[34:35]
	s_mov_b64 s[28:29], 0
	v_mov_b32_e32 v2, 0
	v_mov_b32_e32 v3, v2
	v_mov_b32_e32 v4, v2
	v_mov_b32_e32 v5, v2
	v_mov_b32_e32 v10, v2
	v_mov_b32_e32 v11, v2
	v_mov_b32_e32 v12, v2
	v_mov_b32_e32 v13, v2
	v_mov_b32_e32 v14, v2
	v_mov_b32_e32 v15, v2
	v_mov_b32_e32 v16, v2
	v_mov_b32_e32 v17, v2
	v_mov_b32_e32 v6, v2
	v_mov_b32_e32 v7, v2
	v_mov_b32_e32 v8, v2
	v_mov_b32_e32 v9, v2
	v_mov_b32_e32 v22, v2
	v_mov_b32_e32 v23, v2
	v_mov_b32_e32 v24, v2
	v_mov_b32_e32 v25, v2
	v_mov_b32_e32 v30, v2
	v_mov_b32_e32 v31, v2
	v_mov_b32_e32 v32, v2
	v_mov_b32_e32 v33, v2
	v_mov_b32_e32 v18, v2
	v_mov_b32_e32 v19, v2
	v_mov_b32_e32 v20, v2
	v_mov_b32_e32 v21, v2
	v_mov_b32_e32 v26, v2
	v_mov_b32_e32 v27, v2
	v_mov_b32_e32 v28, v2
	v_mov_b32_e32 v29, v2
	v_mov_b32_e32 v34, v2
	v_mov_b32_e32 v35, v2
	v_mov_b32_e32 v36, v2
	v_mov_b32_e32 v37, v2
	v_mov_b32_e32 v38, v2
	v_mov_b32_e32 v39, v2
	v_mov_b32_e32 v40, v2
	v_mov_b32_e32 v41, v2
	v_mov_b32_e32 v42, v2
	v_mov_b32_e32 v43, v2
	v_mov_b32_e32 v44, v2
	v_mov_b32_e32 v45, v2
	v_mov_b32_e32 v46, v2
	v_mov_b32_e32 v47, v2
	v_mov_b32_e32 v48, v2
	v_mov_b32_e32 v49, v2
	v_mov_b32_e32 v50, v2
	v_mov_b32_e32 v51, v2
	v_mov_b32_e32 v52, v2
	v_mov_b32_e32 v53, v2
	v_mov_b32_e32 v54, v2
	v_mov_b32_e32 v55, v2
	v_mov_b32_e32 v56, v2
	v_mov_b32_e32 v57, v2
	v_mov_b32_e32 v58, v2
	v_mov_b32_e32 v59, v2
	v_mov_b32_e32 v60, v2
	v_mov_b32_e32 v61, v2
	v_mov_b32_e32 v62, v2
	v_mov_b32_e32 v63, v2
	v_mov_b32_e32 v64, v2
	v_mov_b32_e32 v65, v2
	v_mov_b32_e32 v66, v2
	v_mov_b32_e32 v67, v2
	v_mov_b32_e32 v68, v2
; DI f32x4 mfma16(bf16x8 a, bf16x8 b, f32x4 c) { return __builtin_amdgcn_mfma_f32_16x16x32_bf16(a, b, c, 0, 0, 0); }
; template <int MI, int NI>
; DI void gemm_kloop(const u16* Au, int lda, const u16* Bu, int ldb, int K, f32x4 (&acc)[NI][MI], unsigned char* smem) {
;     ...
;   for (int kt = 0; kt < nk; ++kt) {
;     __syncthreads();
;     if (kt + 1 < nk) {
;       SWRITE((kt + 1) & 1);
;       if (kt + 2 < nk) GLOAD((kt + 2) << 6);
;     }
;     {
;       const unsigned char* sa = smem + (kt & 1) * 65536;
;       const unsigned char* sb = sa + 32768;
; #pragma unroll
;       for (int ks = 0; ks < 2; ++ks) {
;         const int fo = ks ? fro1 : fro0;
;         bf16x8 af[MI];
; #pragma unroll
;         for (int i = 0; i < MI; ++i) af[i] = *(const bf16x8*)(sa + (wm * 16 * MI + i * 16) * 128 + fo);
; #pragma unroll
;         for (int nh = 0; nh < NI; nh += 4) {
;           bf16x8 wf[4];
; #pragma unroll
;           for (int i = 0; i < 4; ++i) wf[i] = *(const bf16x8*)(sb + (wn * 16 * NI + (nh + i) * 16) * 128 + fo);
; #pragma unroll
;           for (int ni = 0; ni < 4; ++ni)
; #pragma unroll
;             for (int mi = 0; mi < MI; ++mi) acc[nh + ni][mi] = mfma16(wf[ni], af[mi], acc[nh + ni][mi]);
;         }
; template <int MI, int NI>
; DI void zero_acc(f32x4 (&acc)[NI][MI]) {
; #pragma unroll
;   for (int i = 0; i < NI; ++i)
; #pragma unroll
;     for (int j = 0; j < MI; ++j) acc[i][j] = f32x4{0.f, 0.f, 0.f, 0.f};
	v_mov_b32_e32 v69, v2
	v_mov_b32_e32 v70, v2
	v_mov_b32_e32 v71, v2
	v_mov_b32_e32 v72, v2
	v_mov_b32_e32 v73, v2
	v_mov_b32_e32 v74, v2
	v_mov_b32_e32 v75, v2
	v_mov_b32_e32 v76, v2
	v_mov_b32_e32 v77, v2
	v_mov_b32_e32 v78, v2
	v_mov_b32_e32 v79, v2
	v_mov_b32_e32 v80, v2
	v_mov_b32_e32 v81, v2
	v_mov_b32_e32 v102, v2
	v_mov_b32_e32 v103, v2
	v_mov_b32_e32 v104, v2
	v_mov_b32_e32 v105, v2
	v_mov_b32_e32 v118, v2
	v_mov_b32_e32 v119, v2
	v_mov_b32_e32 v120, v2
	v_mov_b32_e32 v121, v2
	v_mov_b32_e32 v122, v2
	v_mov_b32_e32 v123, v2
	v_mov_b32_e32 v124, v2
	v_mov_b32_e32 v125, v2
	v_mov_b32_e32 v126, v2
	v_mov_b32_e32 v127, v2
	v_mov_b32_e32 v128, v2
	v_mov_b32_e32 v129, v2
	v_mov_b32_e32 v130, v2
	v_mov_b32_e32 v131, v2
	v_mov_b32_e32 v132, v2
	v_mov_b32_e32 v133, v2
	v_mov_b32_e32 v134, v2
	v_mov_b32_e32 v135, v2
	v_mov_b32_e32 v136, v2
	v_mov_b32_e32 v137, v2
	v_mov_b32_e32 v138, v2
	v_mov_b32_e32 v139, v2
	v_mov_b32_e32 v140, v2
	v_mov_b32_e32 v141, v2
	v_mov_b32_e32 v142, v2
	v_mov_b32_e32 v143, v2
	v_mov_b32_e32 v144, v2
	v_mov_b32_e32 v145, v2
	v_mov_b32_e32 v146, v2
	v_mov_b32_e32 v147, v2
	v_mov_b32_e32 v148, v2
	v_mov_b32_e32 v149, v2
	v_mov_b32_e32 v154, v2
	v_mov_b32_e32 v155, v2
	v_mov_b32_e32 v156, v2
	v_mov_b32_e32 v157, v2
	v_mov_b32_e32 v150, v2
	v_mov_b32_e32 v151, v2
	v_mov_b32_e32 v152, v2
	v_mov_b32_e32 v153, v2
	v_mov_b32_e32 v158, v2
	v_mov_b32_e32 v159, v2
	v_mov_b32_e32 v160, v2
	v_mov_b32_e32 v161, v2
	s_mov_b32 s95, 0
.Lk_g1:
	s_waitcnt vmcnt(0) lgkmcnt(0)
	s_barrier
	ds_read_b128 v[82:85], v226
	ds_read_b128 v[86:89], v226 offset:2048
	ds_read_b128 v[90:93], v226 offset:4096
	ds_read_b128 v[94:97], v226 offset:6144
	ds_read_b128 v[180:183], v228 offset:32768
	ds_read_b128 v[184:187], v228 offset:34816
	ds_read_b128 v[188:191], v228 offset:36864
	s_and_b32 s92, s95, 1
	s_xor_b32 s92, s92, 1
	s_lshl_b32 s92, s92, 16
	s_waitcnt lgkmcnt(2)
	v_mfma_f32_16x16x32_bf16 v[142:145], v[180:183], v[82:85], v[142:145]
	ds_read_b128 v[192:195], v228 offset:38912
	v_mfma_f32_16x16x32_bf16 v[138:141], v[180:183], v[86:89], v[138:141]
	v_mfma_f32_16x16x32_bf16 v[134:137], v[180:183], v[90:93], v[134:137]
	s_add_u32 m0, s92, s94
	s_nop 0
	global_load_lds_dwordx4 v254, s[88:89]
	v_mfma_f32_16x16x32_bf16 v[130:133], v[180:183], v[94:97], v[130:133]
	s_waitcnt lgkmcnt(2)
	v_mfma_f32_16x16x32_bf16 v[126:129], v[184:187], v[82:85], v[126:129]
	ds_read_b128 v[180:183], v228 offset:40960
	v_mfma_f32_16x16x32_bf16 v[122:125], v[184:187], v[86:89], v[122:125]
	ds_read_b128 v[98:101], v227
	v_mfma_f32_16x16x32_bf16 v[118:121], v[184:187], v[90:93], v[118:121]
	s_add_u32 m0, m0, 0x2000
	s_add_u32 s92, s88, 0x20000
	s_addc_u32 s93, s89, 0
	global_load_lds_dwordx4 v254, s[92:93]
	v_mfma_f32_16x16x32_bf16 v[102:105], v[184:187], v[94:97], v[102:105]
	s_waitcnt lgkmcnt(3)
	v_mfma_f32_16x16x32_bf16 v[78:81], v[188:191], v[82:85], v[78:81]
	ds_read_b128 v[184:187], v228 offset:43008
	v_mfma_f32_16x16x32_bf16 v[74:77], v[188:191], v[86:89], v[74:77]
	ds_read_b128 v[106:109], v227 offset:2048
	v_mfma_f32_16x16x32_bf16 v[70:73], v[188:191], v[90:93], v[70:73]
	s_add_u32 m0, m0, 0x2000
	s_add_u32 s92, s88, 0x40000
	s_addc_u32 s93, s89, 0
	global_load_lds_dwordx4 v254, s[92:93]
	v_mfma_f32_16x16x32_bf16 v[66:69], v[188:191], v[94:97], v[66:69]
	s_waitcnt lgkmcnt(4)
	v_mfma_f32_16x16x32_bf16 v[62:65], v[192:195], v[82:85], v[62:65]
	ds_read_b128 v[188:191], v228 offset:45056
	v_mfma_f32_16x16x32_bf16 v[58:61], v[192:195], v[86:89], v[58:61]
	ds_read_b128 v[110:113], v227 offset:4096
	v_mfma_f32_16x16x32_bf16 v[54:57], v[192:195], v[90:93], v[54:57]
	s_add_u32 m0, m0, 0x2000
	s_add_u32 s92, s88, 0x60000
	s_addc_u32 s93, s89, 0
	global_load_lds_dwordx4 v254, s[92:93]
	v_mfma_f32_16x16x32_bf16 v[50:53], v[192:195], v[94:97], v[50:53]
	s_waitcnt lgkmcnt(5)
	v_mfma_f32_16x16x32_bf16 v[46:49], v[180:183], v[82:85], v[46:49]
	ds_read_b128 v[192:195], v228 offset:47104
	v_mfma_f32_16x16x32_bf16 v[42:45], v[180:183], v[86:89], v[42:45]
	ds_read_b128 v[114:117], v227 offset:6144
	v_mfma_f32_16x16x32_bf16 v[38:41], v[180:183], v[90:93], v[38:41]
	s_add_u32 m0, m0, 0x2000
	s_nop 0
	global_load_lds_dwordx4 v254, s[90:91]
	v_mfma_f32_16x16x32_bf16 v[34:37], v[180:183], v[94:97], v[34:37]
	s_waitcnt lgkmcnt(5)
	v_mfma_f32_16x16x32_bf16 v[26:29], v[184:187], v[82:85], v[26:29]
	ds_read_b128 v[180:183], v229 offset:32768
	v_mfma_f32_16x16x32_bf16 v[18:21], v[184:187], v[86:89], v[18:21]
	v_mfma_f32_16x16x32_bf16 v[30:33], v[184:187], v[90:93], v[30:33]
	s_add_u32 m0, m0, 0x2000
	s_add_u32 s92, s90, 0x20000
	s_addc_u32 s93, s91, 0
	global_load_lds_dwordx4 v254, s[92:93]
	v_mfma_f32_16x16x32_bf16 v[22:25], v[184:187], v[94:97], v[22:25]
	s_waitcnt lgkmcnt(4)
	v_mfma_f32_16x16x32_bf16 v[6:9], v[188:191], v[82:85], v[6:9]
	ds_read_b128 v[184:187], v229 offset:34816
	v_mfma_f32_16x16x32_bf16 v[14:17], v[188:191], v[86:89], v[14:17]
	v_mfma_f32_16x16x32_bf16 v[10:13], v[188:191], v[90:93], v[10:13]
	s_add_u32 m0, m0, 0x2000
	s_add_u32 s92, s90, 0x40000
	s_addc_u32 s93, s91, 0
	global_load_lds_dwordx4 v254, s[92:93]
	v_mfma_f32_16x16x32_bf16 v[2:5], v[188:191], v[94:97], v[2:5]
	s_waitcnt lgkmcnt(3)
	v_mfma_f32_16x16x32_bf16 v[146:149], v[192:195], v[82:85], v[146:149]
	ds_read_b128 v[188:191], v229 offset:36864
	v_mfma_f32_16x16x32_bf16 v[154:157], v[192:195], v[86:89], v[154:157]
	v_mfma_f32_16x16x32_bf16 v[150:153], v[192:195], v[90:93], v[150:153]
	s_add_u32 m0, m0, 0x2000
	s_add_u32 s92, s90, 0x60000
	s_addc_u32 s93, s91, 0
	global_load_lds_dwordx4 v254, s[92:93]
	v_mfma_f32_16x16x32_bf16 v[158:161], v[192:195], v[94:97], v[158:161]
	s_waitcnt lgkmcnt(2)
; DI f32x4 mfma16(bf16x8 a, bf16x8 b, f32x4 c) { return __builtin_amdgcn_mfma_f32_16x16x32_bf16(a, b, c, 0, 0, 0); }
; template <int MI, int NI>
; DI void gemm_kloop(const u16* Au, int lda, const u16* Bu, int ldb, int K, f32x4 (&acc)[NI][MI], unsigned char* smem) {
;     ...
;   for (int kt = 0; kt < nk; ++kt) {
;     __syncthreads();
;     if (kt + 1 < nk) {
;       SWRITE((kt + 1) & 1);
;       if (kt + 2 < nk) GLOAD((kt + 2) << 6);
;     }
;     {
;       const unsigned char* sa = smem + (kt & 1) * 65536;
;       const unsigned char* sb = sa + 32768;
; #pragma unroll
;       for (int ks = 0; ks < 2; ++ks) {
;         const int fo = ks ? fro1 : fro0;
;         bf16x8 af[MI];
; #pragma unroll
;         for (int i = 0; i < MI; ++i) af[i] = *(const bf16x8*)(sa + (wm * 16 * MI + i * 16) * 128 + fo);
; #pragma unroll
;         for (int nh = 0; nh < NI; nh += 4) {
;           bf16x8 wf[4];
; #pragma unroll
;           for (int i = 0; i < 4; ++i) wf[i] = *(const bf16x8*)(sb + (wn * 16 * NI + (nh + i) * 16) * 128 + fo);
; #pragma unroll
;           for (int ni = 0; ni < 4; ++ni)
; #pragma unroll
;             for (int mi = 0; mi < MI; ++mi) acc[nh + ni][mi] = mfma16(wf[ni], af[mi], acc[nh + ni][mi]);
;         }
;       }
;     }
;   }
;   __syncthreads();
	v_mfma_f32_16x16x32_bf16 v[142:145], v[180:183], v[98:101], v[142:145]
	ds_read_b128 v[192:195], v229 offset:38912
	v_mfma_f32_16x16x32_bf16 v[138:141], v[180:183], v[106:109], v[138:141]
	v_mfma_f32_16x16x32_bf16 v[134:137], v[180:183], v[110:113], v[134:137]
	v_mfma_f32_16x16x32_bf16 v[130:133], v[180:183], v[114:117], v[130:133]
	s_waitcnt lgkmcnt(2)
	v_mfma_f32_16x16x32_bf16 v[126:129], v[184:187], v[98:101], v[126:129]
	ds_read_b128 v[180:183], v229 offset:40960
	v_mfma_f32_16x16x32_bf16 v[122:125], v[184:187], v[106:109], v[122:125]
	v_mfma_f32_16x16x32_bf16 v[118:121], v[184:187], v[110:113], v[118:121]
	v_mfma_f32_16x16x32_bf16 v[102:105], v[184:187], v[114:117], v[102:105]
	s_waitcnt lgkmcnt(2)
	v_mfma_f32_16x16x32_bf16 v[78:81], v[188:191], v[98:101], v[78:81]
	ds_read_b128 v[184:187], v229 offset:43008
	v_mfma_f32_16x16x32_bf16 v[74:77], v[188:191], v[106:109], v[74:77]
	v_mfma_f32_16x16x32_bf16 v[70:73], v[188:191], v[110:113], v[70:73]
	v_mfma_f32_16x16x32_bf16 v[66:69], v[188:191], v[114:117], v[66:69]
	s_waitcnt lgkmcnt(2)
	v_mfma_f32_16x16x32_bf16 v[62:65], v[192:195], v[98:101], v[62:65]
	ds_read_b128 v[188:191], v229 offset:45056
	v_mfma_f32_16x16x32_bf16 v[58:61], v[192:195], v[106:109], v[58:61]
	v_mfma_f32_16x16x32_bf16 v[54:57], v[192:195], v[110:113], v[54:57]
	v_mfma_f32_16x16x32_bf16 v[50:53], v[192:195], v[114:117], v[50:53]
	s_waitcnt lgkmcnt(2)
	v_mfma_f32_16x16x32_bf16 v[46:49], v[180:183], v[98:101], v[46:49]
	ds_read_b128 v[192:195], v229 offset:47104
	v_mfma_f32_16x16x32_bf16 v[42:45], v[180:183], v[106:109], v[42:45]
	v_mfma_f32_16x16x32_bf16 v[38:41], v[180:183], v[110:113], v[38:41]
	v_mfma_f32_16x16x32_bf16 v[34:37], v[180:183], v[114:117], v[34:37]
	s_waitcnt lgkmcnt(2)
	v_mfma_f32_16x16x32_bf16 v[26:29], v[184:187], v[98:101], v[26:29]
	v_mfma_f32_16x16x32_bf16 v[18:21], v[184:187], v[106:109], v[18:21]
	v_mfma_f32_16x16x32_bf16 v[30:33], v[184:187], v[110:113], v[30:33]
	v_mfma_f32_16x16x32_bf16 v[22:25], v[184:187], v[114:117], v[22:25]
	s_waitcnt lgkmcnt(1)
	v_mfma_f32_16x16x32_bf16 v[6:9], v[188:191], v[98:101], v[6:9]
	v_mfma_f32_16x16x32_bf16 v[14:17], v[188:191], v[106:109], v[14:17]
	v_mfma_f32_16x16x32_bf16 v[10:13], v[188:191], v[110:113], v[10:13]
	v_mfma_f32_16x16x32_bf16 v[2:5], v[188:191], v[114:117], v[2:5]
	s_waitcnt lgkmcnt(0)
	v_mfma_f32_16x16x32_bf16 v[146:149], v[192:195], v[98:101], v[146:149]
	v_mfma_f32_16x16x32_bf16 v[154:157], v[192:195], v[106:109], v[154:157]
	v_mfma_f32_16x16x32_bf16 v[150:153], v[192:195], v[110:113], v[150:153]
	v_mfma_f32_16x16x32_bf16 v[158:161], v[192:195], v[114:117], v[158:161]
	v_xor_b32_e32 v226, 0x10000, v226
	v_xor_b32_e32 v227, 0x10000, v227
	v_xor_b32_e32 v228, 0x10000, v228
	v_xor_b32_e32 v229, 0x10000, v229
	s_add_u32 s88, s88, 0x80
	s_addc_u32 s89, s89, 0
	s_add_u32 s90, s90, 0x80
	s_addc_u32 s91, s91, 0
	s_add_u32 s95, s95, 1
	s_cmp_lg_u32 s95, 14
	s_cbranch_scc1 .Lk_g1
	s_waitcnt vmcnt(0)
	s_barrier
	s_add_u32 m0, s94, 0x10000
	s_nop 0
	global_load_lds_dwordx4 v254, s[88:89]
	s_add_u32 m0, m0, 0x2000
	s_add_u32 s92, s88, 0x20000
	s_addc_u32 s93, s89, 0
	global_load_lds_dwordx4 v254, s[92:93]
	s_add_u32 m0, m0, 0x2000
	s_add_u32 s92, s88, 0x40000
	s_addc_u32 s93, s89, 0
	global_load_lds_dwordx4 v254, s[92:93]
	s_add_u32 m0, m0, 0x2000
	s_add_u32 s92, s88, 0x60000
	s_addc_u32 s93, s89, 0
	global_load_lds_dwordx4 v254, s[92:93]
	s_add_u32 m0, m0, 0x2000
	s_nop 0
	global_load_lds_dwordx4 v254, s[90:91]
	s_add_u32 m0, m0, 0x2000
	s_add_u32 s92, s90, 0x20000
	s_addc_u32 s93, s91, 0
	global_load_lds_dwordx4 v254, s[92:93]
	s_add_u32 m0, m0, 0x2000
	s_add_u32 s92, s90, 0x40000
	s_addc_u32 s93, s91, 0
	global_load_lds_dwordx4 v254, s[92:93]
	s_add_u32 m0, m0, 0x2000
	s_add_u32 s92, s90, 0x60000
	s_addc_u32 s93, s91, 0
	global_load_lds_dwordx4 v254, s[92:93]
	v_add_u32_e32 v164, v178, v177
	ds_read_b128 v[82:85], v164 offset:32768
	v_add_u32_e32 v114, v176, v177
	ds_read_b128 v[86:89], v114
	ds_read_b128 v[90:93], v114 offset:2048
	ds_read_b128 v[94:97], v164 offset:34816
	ds_read_b128 v[110:113], v114 offset:4096
	ds_read_b128 v[114:117], v114 offset:6144
	s_waitcnt lgkmcnt(4)
	v_mfma_f32_16x16x32_bf16 v[98:101], v[82:85], v[86:89], v[142:145]
	v_add_u32_e32 v168, 0x10000, v176
	s_cmp_lt_u32 s30, 4
	s_waitcnt lgkmcnt(3)
	v_mfma_f32_16x16x32_bf16 v[106:109], v[82:85], v[90:93], v[138:141]
	s_waitcnt lgkmcnt(1)
	v_mfma_f32_16x16x32_bf16 v[134:137], v[82:85], v[110:113], v[134:137]
	s_waitcnt lgkmcnt(0)
	v_mfma_f32_16x16x32_bf16 v[82:85], v[82:85], v[114:117], v[130:133]
	v_mfma_f32_16x16x32_bf16 v[126:129], v[94:97], v[86:89], v[126:129]
	v_mfma_f32_16x16x32_bf16 v[122:125], v[94:97], v[90:93], v[122:125]
	v_mfma_f32_16x16x32_bf16 v[118:121], v[94:97], v[110:113], v[118:121]
	v_mfma_f32_16x16x32_bf16 v[94:97], v[94:97], v[114:117], v[102:105]
	s_nop 2
	ds_read_b128 v[102:105], v164 offset:36864
	ds_read_b128 v[130:133], v164 offset:38912
	s_waitcnt lgkmcnt(1)
	v_mfma_f32_16x16x32_bf16 v[78:81], v[102:105], v[86:89], v[78:81]
	v_mfma_f32_16x16x32_bf16 v[74:77], v[102:105], v[90:93], v[74:77]
	v_mfma_f32_16x16x32_bf16 v[70:73], v[102:105], v[110:113], v[70:73]
	v_mfma_f32_16x16x32_bf16 v[66:69], v[102:105], v[114:117], v[66:69]
	s_waitcnt lgkmcnt(0)
	v_mfma_f32_16x16x32_bf16 v[62:65], v[130:133], v[86:89], v[62:65]
	v_mfma_f32_16x16x32_bf16 v[58:61], v[130:133], v[90:93], v[58:61]
	v_mfma_f32_16x16x32_bf16 v[54:57], v[130:133], v[110:113], v[54:57]
	v_mfma_f32_16x16x32_bf16 v[50:53], v[130:133], v[114:117], v[50:53]
	ds_read_b128 v[102:105], v164 offset:40960
	ds_read_b128 v[130:133], v164 offset:43008
	s_waitcnt lgkmcnt(1)
; DI f32x4 mfma16(bf16x8 a, bf16x8 b, f32x4 c) { return __builtin_amdgcn_mfma_f32_16x16x32_bf16(a, b, c, 0, 0, 0); }
; template <int MI, int NI>
; DI void gemm_kloop(const u16* Au, int lda, const u16* Bu, int ldb, int K, f32x4 (&acc)[NI][MI], unsigned char* smem) {
;     ...
;     {
;       const unsigned char* sa = smem + (kt & 1) * 65536;
;       const unsigned char* sb = sa + 32768;
; #pragma unroll
;       for (int ks = 0; ks < 2; ++ks) {
;         const int fo = ks ? fro1 : fro0;
;         bf16x8 af[MI];
; #pragma unroll
;         for (int i = 0; i < MI; ++i) af[i] = *(const bf16x8*)(sa + (wm * 16 * MI + i * 16) * 128 + fo);
; #pragma unroll
;         for (int nh = 0; nh < NI; nh += 4) {
;           bf16x8 wf[4];
; #pragma unroll
;           for (int i = 0; i < 4; ++i) wf[i] = *(const bf16x8*)(sb + (wn * 16 * NI + (nh + i) * 16) * 128 + fo);
; #pragma unroll
;           for (int ni = 0; ni < 4; ++ni)
; #pragma unroll
;             for (int mi = 0; mi < MI; ++mi) acc[nh + ni][mi] = mfma16(wf[ni], af[mi], acc[nh + ni][mi]);
;         }
;       }
;     }
;   }
;   __syncthreads();
	v_mfma_f32_16x16x32_bf16 v[46:49], v[102:105], v[86:89], v[46:49]
	v_mfma_f32_16x16x32_bf16 v[42:45], v[102:105], v[90:93], v[42:45]
	v_mfma_f32_16x16x32_bf16 v[38:41], v[102:105], v[110:113], v[38:41]
	v_mfma_f32_16x16x32_bf16 v[34:37], v[102:105], v[114:117], v[34:37]
	s_waitcnt lgkmcnt(0)
	v_mfma_f32_16x16x32_bf16 v[26:29], v[130:133], v[86:89], v[26:29]
	v_mfma_f32_16x16x32_bf16 v[18:21], v[130:133], v[90:93], v[18:21]
	v_mfma_f32_16x16x32_bf16 v[30:33], v[130:133], v[110:113], v[30:33]
	v_mfma_f32_16x16x32_bf16 v[22:25], v[130:133], v[114:117], v[22:25]
	ds_read_b128 v[102:105], v164 offset:45056
	ds_read_b128 v[130:133], v164 offset:47104
	v_or_b32_e32 v164, 0x18000, v178
	v_add_u32_e32 v165, v164, v177
	s_waitcnt lgkmcnt(1)
	v_mfma_f32_16x16x32_bf16 v[14:17], v[102:105], v[90:93], v[14:17]
	v_add_u32_e32 v164, v164, v175
	s_waitcnt lgkmcnt(0)
	v_mfma_f32_16x16x32_bf16 v[90:93], v[130:133], v[90:93], v[154:157]
	s_nop 2
	v_add_u32_e32 v154, v178, v175
	v_mfma_f32_16x16x32_bf16 v[6:9], v[102:105], v[86:89], v[6:9]
	v_mfma_f32_16x16x32_bf16 v[10:13], v[102:105], v[110:113], v[10:13]
	v_mfma_f32_16x16x32_bf16 v[2:5], v[102:105], v[114:117], v[2:5]
	v_mfma_f32_16x16x32_bf16 v[102:105], v[130:133], v[110:113], v[150:153]
	ds_read_b128 v[110:113], v154 offset:32768
	s_nop 1
	v_add_u32_e32 v150, v176, v175
	v_mfma_f32_16x16x32_bf16 v[86:89], v[130:133], v[86:89], v[146:149]
	v_mfma_f32_16x16x32_bf16 v[114:117], v[130:133], v[114:117], v[158:161]
	ds_read_b128 v[130:133], v150
	ds_read_b128 v[138:141], v150 offset:2048
	ds_read_b128 v[142:145], v154 offset:34816
	ds_read_b128 v[146:149], v150 offset:4096
	ds_read_b128 v[150:153], v150 offset:6144
	s_waitcnt lgkmcnt(4)
	v_mfma_f32_16x16x32_bf16 v[98:101], v[110:113], v[130:133], v[98:101]
	s_waitcnt lgkmcnt(3)
	v_mfma_f32_16x16x32_bf16 v[106:109], v[110:113], v[138:141], v[106:109]
	s_waitcnt lgkmcnt(1)
	v_mfma_f32_16x16x32_bf16 v[134:137], v[110:113], v[146:149], v[134:137]
	s_waitcnt lgkmcnt(0)
	v_mfma_f32_16x16x32_bf16 v[82:85], v[110:113], v[150:153], v[82:85]
	v_mfma_f32_16x16x32_bf16 v[110:113], v[142:145], v[130:133], v[126:129]
	v_mfma_f32_16x16x32_bf16 v[122:125], v[142:145], v[138:141], v[122:125]
	v_mfma_f32_16x16x32_bf16 v[118:121], v[142:145], v[146:149], v[118:121]
	v_mfma_f32_16x16x32_bf16 v[94:97], v[142:145], v[150:153], v[94:97]
	ds_read_b128 v[126:129], v154 offset:36864
	ds_read_b128 v[142:145], v154 offset:38912
	s_waitcnt lgkmcnt(1)
	v_mfma_f32_16x16x32_bf16 v[78:81], v[126:129], v[130:133], v[78:81]
	v_mfma_f32_16x16x32_bf16 v[74:77], v[126:129], v[138:141], v[74:77]
	v_mfma_f32_16x16x32_bf16 v[70:73], v[126:129], v[146:149], v[70:73]
	v_mfma_f32_16x16x32_bf16 v[66:69], v[126:129], v[150:153], v[66:69]
	s_waitcnt lgkmcnt(0)
	v_mfma_f32_16x16x32_bf16 v[62:65], v[142:145], v[130:133], v[62:65]
	v_mfma_f32_16x16x32_bf16 v[58:61], v[142:145], v[138:141], v[58:61]
	v_mfma_f32_16x16x32_bf16 v[54:57], v[142:145], v[146:149], v[54:57]
	v_mfma_f32_16x16x32_bf16 v[50:53], v[142:145], v[150:153], v[50:53]
	ds_read_b128 v[126:129], v154 offset:40960
	ds_read_b128 v[142:145], v154 offset:43008
	s_waitcnt lgkmcnt(1)
	v_mfma_f32_16x16x32_bf16 v[46:49], v[126:129], v[130:133], v[46:49]
	v_mfma_f32_16x16x32_bf16 v[42:45], v[126:129], v[138:141], v[42:45]
	v_mfma_f32_16x16x32_bf16 v[38:41], v[126:129], v[146:149], v[38:41]
	v_mfma_f32_16x16x32_bf16 v[34:37], v[126:129], v[150:153], v[34:37]
	s_waitcnt lgkmcnt(0)
	v_mfma_f32_16x16x32_bf16 v[26:29], v[142:145], v[130:133], v[26:29]
	v_mfma_f32_16x16x32_bf16 v[18:21], v[142:145], v[138:141], v[18:21]
	v_mfma_f32_16x16x32_bf16 v[30:33], v[142:145], v[146:149], v[30:33]
	v_mfma_f32_16x16x32_bf16 v[22:25], v[142:145], v[150:153], v[22:25]
	ds_read_b128 v[126:129], v154 offset:45056
	ds_read_b128 v[142:145], v154 offset:47104
	s_waitcnt vmcnt(0) lgkmcnt(0)
	s_barrier
	v_mfma_f32_16x16x32_bf16 v[6:9], v[126:129], v[130:133], v[6:9]
	v_mfma_f32_16x16x32_bf16 v[14:17], v[126:129], v[138:141], v[14:17]
	v_mfma_f32_16x16x32_bf16 v[10:13], v[126:129], v[146:149], v[10:13]
	v_mfma_f32_16x16x32_bf16 v[2:5], v[126:129], v[150:153], v[2:5]
	ds_read_b128 v[126:129], v165
	v_mfma_f32_16x16x32_bf16 v[102:105], v[142:145], v[146:149], v[102:105]
	v_add_u32_e32 v146, v168, v177
	v_mfma_f32_16x16x32_bf16 v[86:89], v[142:145], v[130:133], v[86:89]
	ds_read_b128 v[130:133], v146
	v_mfma_f32_16x16x32_bf16 v[90:93], v[142:145], v[138:141], v[90:93]
	ds_read_b128 v[138:141], v146 offset:2048
	v_mfma_f32_16x16x32_bf16 v[114:117], v[142:145], v[150:153], v[114:117]
	ds_read_b128 v[142:145], v146 offset:4096
	ds_read_b128 v[146:149], v146 offset:6144
	s_waitcnt lgkmcnt(3)
	v_mfma_f32_16x16x32_bf16 v[98:101], v[126:129], v[130:133], v[98:101]
	s_waitcnt lgkmcnt(2)
	v_mfma_f32_16x16x32_bf16 v[106:109], v[126:129], v[138:141], v[106:109]
	s_waitcnt lgkmcnt(1)
	v_mfma_f32_16x16x32_bf16 v[134:137], v[126:129], v[142:145], v[134:137]
	s_waitcnt lgkmcnt(0)
	v_mfma_f32_16x16x32_bf16 v[82:85], v[126:129], v[146:149], v[82:85]
	ds_read_b128 v[126:129], v165 offset:2048
	s_waitcnt lgkmcnt(0)
	v_mfma_f32_16x16x32_bf16 v[150:153], v[126:129], v[142:145], v[118:121]
	s_nop 2
	ds_read_b128 v[118:121], v165 offset:4096
	v_mfma_f32_16x16x32_bf16 v[110:113], v[126:129], v[130:133], v[110:113]
	v_mfma_f32_16x16x32_bf16 v[122:125], v[126:129], v[138:141], v[122:125]
	v_mfma_f32_16x16x32_bf16 v[94:97], v[126:129], v[146:149], v[94:97]
	s_waitcnt lgkmcnt(0)
	v_mfma_f32_16x16x32_bf16 v[126:129], v[118:121], v[142:145], v[70:73]
	s_nop 2
	ds_read_b128 v[70:73], v165 offset:6144
	s_waitcnt lgkmcnt(0)
; DI void phase_g1(const Params& p, int layer, unsigned char* smem) {
;     ...
;     int mrow[4];
; #pragma unroll
;     for (int mi = 0; mi < 4; ++mi) {
;       mrow[mi] = mt * 256 + wm * 64 + mi * 16 + lm;
;       float rs = rsqrtf(rowss[mrow[mi]] * (1.f / DM) + EPS);
; #pragma unroll
;       for (int ni = 0; ni < 8; ++ni) acc[ni][mi] *= rs;
;     }
;     int kind;
;     u16* dst = nullptr; int ld = 256, col0 = 0, vrows = 256; const float* gn = nullptr;
;     if (nt == 0) { kind = 0; dst = p.qsb; }
;     else if (nt == 1) { kind = 0; dst = p.ksb; }
;     else if (nt == 2) { kind = 2; dst = p.vtsb; vrows = 256; }
;     else if (nt == 3) { kind = 1; dst = p.qsp; gn = p.qn_sp + layer * 64; }
;     else if (nt == 4) { kind = 1; dst = p.ksp; gn = p.kn_sp + layer * 64; }
;     else if (nt == 5) { kind = 2; dst = p.vtsp; vrows = 256; }
;     else if (nt < 8) { kind = 1; dst = p.qdf; ld = 512; col0 = (nt - 6) * 256; gn = p.qn_df + layer * 64; }
;     else if (nt < 10) { kind = 1; dst = p.kdf; ld = 512; col0 = (nt - 8) * 256; gn = p.kn_df + layer * 64; }
;     else if (nt < 12) { kind = 2; dst = p.vtdf; col0 = (nt - 10) * 256; vrows = 512; }
;     else { kind = 0; dst = p.qix; }
	v_mfma_f32_16x16x32_bf16 v[154:157], v[70:73], v[146:149], v[50:53]
	s_nop 2
	ds_read_b128 v[50:53], v165 offset:8192
	s_waitcnt lgkmcnt(0)
	v_mfma_f32_16x16x32_bf16 v[176:179], v[50:53], v[142:145], v[38:41]
	s_nop 2
	ds_read_b128 v[38:41], v165 offset:10240
	s_waitcnt lgkmcnt(0)
	v_mfma_f32_16x16x32_bf16 v[180:183], v[38:41], v[146:149], v[22:25]
	s_nop 2
	ds_read_b128 v[22:25], v165 offset:12288
	s_waitcnt lgkmcnt(0)
	v_mfma_f32_16x16x32_bf16 v[226:229], v[22:25], v[146:149], v[2:5]
	s_nop 2
	ds_read_b128 v[2:5], v165 offset:14336
	v_mfma_f32_16x16x32_bf16 v[184:187], v[22:25], v[130:133], v[6:9]
	s_nop 2
	ds_read_b128 v[6:9], v164
	v_mfma_f32_16x16x32_bf16 v[192:195], v[22:25], v[142:145], v[10:13]
	s_nop 2
	v_add_u32_e32 v10, v168, v175
	v_mfma_f32_16x16x32_bf16 v[78:81], v[118:121], v[130:133], v[78:81]
	ds_read_b128 v[230:233], v10 offset:2048
	ds_read_b128 v[234:237], v10 offset:4096
	ds_read_b128 v[238:241], v10 offset:6144
	v_mfma_f32_16x16x32_bf16 v[74:77], v[118:121], v[138:141], v[74:77]
	v_mfma_f32_16x16x32_bf16 v[66:69], v[118:121], v[146:149], v[66:69]
	v_mfma_f32_16x16x32_bf16 v[62:65], v[70:73], v[130:133], v[62:65]
	v_mfma_f32_16x16x32_bf16 v[58:61], v[70:73], v[138:141], v[58:61]
	v_mfma_f32_16x16x32_bf16 v[54:57], v[70:73], v[142:145], v[54:57]
	v_mfma_f32_16x16x32_bf16 v[46:49], v[50:53], v[130:133], v[46:49]
	v_mfma_f32_16x16x32_bf16 v[158:161], v[50:53], v[138:141], v[42:45]
	v_mfma_f32_16x16x32_bf16 v[34:37], v[50:53], v[146:149], v[34:37]
	v_mfma_f32_16x16x32_bf16 v[26:29], v[38:41], v[130:133], v[26:29]
	v_mfma_f32_16x16x32_bf16 v[18:21], v[38:41], v[138:141], v[18:21]
	v_mfma_f32_16x16x32_bf16 v[30:33], v[38:41], v[142:145], v[30:33]
	v_mfma_f32_16x16x32_bf16 v[188:191], v[22:25], v[138:141], v[14:17]
	s_waitcnt lgkmcnt(4)
	v_mfma_f32_16x16x32_bf16 v[86:89], v[2:5], v[130:133], v[86:89]
	v_mfma_f32_16x16x32_bf16 v[130:133], v[2:5], v[138:141], v[90:93]
	v_mfma_f32_16x16x32_bf16 v[138:141], v[2:5], v[142:145], v[102:105]
	v_mfma_f32_16x16x32_bf16 v[142:145], v[2:5], v[146:149], v[114:117]
	ds_read_b128 v[146:149], v10
	ds_read_b128 v[10:13], v164 offset:6144
	s_waitcnt lgkmcnt(1)
	v_mfma_f32_16x16x32_bf16 v[102:105], v[6:9], v[146:149], v[98:101]
	v_mfma_f32_16x16x32_bf16 v[70:73], v[6:9], v[230:233], v[106:109]
	v_mfma_f32_16x16x32_bf16 v[38:41], v[6:9], v[234:237], v[134:137]
	v_mfma_f32_16x16x32_bf16 v[2:5], v[6:9], v[238:241], v[82:85]
	ds_read_b128 v[6:9], v164 offset:2048
	s_waitcnt lgkmcnt(0)
	v_mfma_f32_16x16x32_bf16 v[118:121], v[6:9], v[146:149], v[110:113]
	v_mfma_f32_16x16x32_bf16 v[82:85], v[6:9], v[230:233], v[122:125]
	v_mfma_f32_16x16x32_bf16 v[50:53], v[6:9], v[234:237], v[150:153]
	v_mfma_f32_16x16x32_bf16 v[14:17], v[6:9], v[238:241], v[94:97]
	ds_read_b128 v[6:9], v164 offset:4096
	v_mfma_f32_16x16x32_bf16 v[122:125], v[10:13], v[146:149], v[62:65]
	v_mfma_f32_16x16x32_bf16 v[90:93], v[10:13], v[230:233], v[58:61]
	v_mfma_f32_16x16x32_bf16 v[54:57], v[10:13], v[234:237], v[54:57]
	v_mfma_f32_16x16x32_bf16 v[22:25], v[10:13], v[238:241], v[154:157]
	ds_read_b128 v[10:13], v164 offset:8192
	s_waitcnt lgkmcnt(1)
	v_mfma_f32_16x16x32_bf16 v[110:113], v[6:9], v[146:149], v[78:81]
	s_waitcnt lgkmcnt(0)
	v_mfma_f32_16x16x32_bf16 v[114:117], v[10:13], v[146:149], v[46:49]
	v_mfma_f32_16x16x32_bf16 v[78:81], v[10:13], v[230:233], v[158:161]
	v_mfma_f32_16x16x32_bf16 v[46:49], v[10:13], v[234:237], v[176:179]
	v_mfma_f32_16x16x32_bf16 v[10:13], v[10:13], v[238:241], v[34:37]
	s_nop 2
	ds_read_b128 v[34:37], v164 offset:10240
	s_waitcnt lgkmcnt(0)
	v_mfma_f32_16x16x32_bf16 v[94:97], v[34:37], v[230:233], v[18:21]
	s_nop 2
	ds_read_b128 v[18:21], v164 offset:12288
	v_mfma_f32_16x16x32_bf16 v[58:61], v[34:37], v[234:237], v[30:33]
	s_nop 2
	ds_read_b128 v[30:33], v164 offset:14336
	s_waitcnt lgkmcnt(0)
	v_mfma_f32_16x16x32_bf16 v[106:109], v[30:33], v[146:149], v[86:89]
	s_barrier
	v_mfma_f32_16x16x32_bf16 v[86:89], v[30:33], v[230:233], v[130:133]
	s_nop 2
	v_add_u32_e32 v130, s2, v173
	v_ashrrev_i32_e32 v131, 31, v130
	v_lshl_add_u64 v[136:137], v[130:131], 2, s[6:7]
	global_load_dword v133, v[136:137], off
	global_load_dword v132, v[136:137], off offset:64
	global_load_dword v135, v[136:137], off offset:128
	global_load_dword v134, v[136:137], off offset:192
	v_mfma_f32_16x16x32_bf16 v[74:77], v[6:9], v[230:233], v[74:77]
	v_mfma_f32_16x16x32_bf16 v[42:45], v[6:9], v[234:237], v[126:129]
	v_mfma_f32_16x16x32_bf16 v[6:9], v[6:9], v[238:241], v[66:69]
	v_mfma_f32_16x16x32_bf16 v[126:129], v[34:37], v[146:149], v[26:29]
	v_mfma_f32_16x16x32_bf16 v[26:29], v[34:37], v[238:241], v[180:183]
	v_mfma_f32_16x16x32_bf16 v[98:101], v[18:21], v[146:149], v[184:187]
	v_mfma_f32_16x16x32_bf16 v[66:69], v[18:21], v[230:233], v[188:191]
	v_mfma_f32_16x16x32_bf16 v[34:37], v[18:21], v[234:237], v[192:195]
	v_mfma_f32_16x16x32_bf16 v[18:21], v[18:21], v[238:241], v[226:229]
	v_mfma_f32_16x16x32_bf16 v[62:65], v[30:33], v[234:237], v[138:141]
	v_mfma_f32_16x16x32_bf16 v[30:33], v[30:33], v[238:241], v[142:145]
	s_cbranch_scc1 .LBB0_1205
	s_mov_b64 s[34:35], -1
	s_mov_b64 s[52:53], 0
	s_cmp_lt_i32 s54, 3
	s_mov_b64 s[30:31], 0
	s_cbranch_scc1 .LBB0_1206
	s_cmp_gt_i32 s54, 3
	s_cbranch_scc0 .LBB0_1221
	s_mov_b64 s[50:51], -1
	s_mov_b64 s[2:3], 0
	s_cmp_gt_i32 s54, 4
	s_mov_b64 s[28:29], -1
	s_cbranch_scc0 .LBB0_1191
	s_cmp_eq_u32 s54, 5
	s_mov_b64 s[30:31], -1
	s_cbranch_scc0 .LBB0_1190
	s_mov_b64 s[30:31], 0

; __global__ void __launch_bounds__(512) mega(Params p, int ph_lo, int ph_hi) {
;   __shared__ __attribute__((aligned(16))) unsigned char smem[SMEM_BYTES];
	.amdhsa_kernel _Z4mega6Paramsii
		.amdhsa_group_segment_fixed_size 151808
		.amdhsa_private_segment_fixed_size 0
		.amdhsa_kernarg_size 656
		.amdhsa_user_sgpr_count 2
		.amdhsa_user_sgpr_dispatch_ptr 0
		.amdhsa_user_sgpr_queue_ptr 0
		.amdhsa_user_sgpr_kernarg_segment_ptr 1
		.amdhsa_user_sgpr_dispatch_id 0
		.amdhsa_user_sgpr_kernarg_preload_length 0
		.amdhsa_user_sgpr_kernarg_preload_offset 0
		.amdhsa_user_sgpr_private_segment_size 0
		.amdhsa_uses_dynamic_stack 0
		.amdhsa_enable_private_segment 0
		.amdhsa_system_sgpr_workgroup_id_x 1
		.amdhsa_system_sgpr_workgroup_id_y 0
		.amdhsa_system_sgpr_workgroup_id_z 0
		.amdhsa_system_sgpr_workgroup_info 0
		.amdhsa_system_vgpr_workitem_id 2
		.amdhsa_next_free_vgpr 256
		.amdhsa_next_free_sgpr 100
		.amdhsa_accum_offset 256
		.amdhsa_reserve_vcc 1
		.amdhsa_float_round_mode_32 0
		.amdhsa_float_round_mode_16_64 0
		.amdhsa_float_denorm_mode_32 3
		.amdhsa_float_denorm_mode_16_64 3
		.amdhsa_dx10_clamp 1
		.amdhsa_ieee_mode 1
		.amdhsa_fp16_overflow 0
		.amdhsa_tg_split 0
		.amdhsa_exception_fp_ieee_invalid_op 0
		.amdhsa_exception_fp_denorm_src 0
		.amdhsa_exception_fp_ieee_div_zero 0
		.amdhsa_exception_fp_ieee_overflow 0
		.amdhsa_exception_fp_ieee_underflow 0
		.amdhsa_exception_fp_ieee_inexact 0
		.amdhsa_exception_int_div_zero 0
	.end_amdhsa_kernel

; __global__ void __launch_bounds__(512) mega(Params p, int ph_lo, int ph_hi) {
;   __shared__ __attribute__((aligned(16))) unsigned char smem[SMEM_BYTES];
amdhsa.kernels:
  - .agpr_count:     0
    .args:
      - .offset:         0
        .size:           392
        .value_kind:     by_value
      - .offset:         392
        .size:           4
        .value_kind:     by_value
      - .offset:         396
        .size:           4
        .value_kind:     by_value
      - .offset:         400
        .size:           4
        .value_kind:     hidden_block_count_x
      - .offset:         404
        .size:           4
        .value_kind:     hidden_block_count_y
      - .offset:         408
        .size:           4
        .value_kind:     hidden_block_count_z
      - .offset:         412
        .size:           2
        .value_kind:     hidden_group_size_x
      - .offset:         414
        .size:           2
        .value_kind:     hidden_group_size_y
      - .offset:         416
        .size:           2
        .value_kind:     hidden_group_size_z
      - .offset:         418
        .size:           2
        .value_kind:     hidden_remainder_x
      - .offset:         420
        .size:           2
        .value_kind:     hidden_remainder_y
      - .offset:         422
        .size:           2
        .value_kind:     hidden_remainder_z
      - .offset:         440
        .size:           8
        .value_kind:     hidden_global_offset_x
      - .offset:         448
        .size:           8
        .value_kind:     hidden_global_offset_y
      - .offset:         456
        .size:           8
        .value_kind:     hidden_global_offset_z
      - .offset:         464
        .size:           2
        .value_kind:     hidden_grid_dims
      - .offset:         488
        .size:           8
        .value_kind:     hidden_multigrid_sync_arg
    .group_segment_fixed_size: 151808
    .kernarg_segment_align: 8
    .kernarg_segment_size: 656
    .language:       OpenCL C
    .language_version:
      - 2
      - 0
    .max_flat_workgroup_size: 512
    .name:           _Z4mega6Paramsii
    .private_segment_fixed_size: 0
    .sgpr_count:     106
    .sgpr_spill_count: 114
    .symbol:         _Z4mega6Paramsii.kd
    .uniform_work_group_size: 1
    .uses_dynamic_stack: false
    .vgpr_count:     256
    .vgpr_spill_count: 0
    .wavefront_size: 64
